# all global stores (phase outputs consumed after a grid barrier) made sc1 write-through so the buffer_wbl2 at barrier arrival has fewer dirty lines to flush
# speedup vs baseline: 1.0083x; 1.0083x over previous
; DI void phase_prep(const Params& p, u16* sm, int wv) {
;     ...
; #pragma unroll
;     for (int j = 0; j < 2; ++j) {
;       const int c = tid + 256 * j, kc = c & 7, n = c >> 3;
;       const float* q = smf + n * 65 + kc * 8;
;       u32x4 o = {pk2(q[0], q[1]), pk2(q[2], q[3]), pk2(q[4], q[5]), pk2(q[6], q[7])};
;       *(u32x4*)(dst + (size_t)(nt * 64 + n) * 1024 + kt * 64 + kc * 8) = o;
;     }
.Lprep_store:
	s_cmp_eq_u32 s26, 0
	s_cbranch_scc1 .Lprep_write
	ds_read2_b32 v[0:1], v23 offset1:1
	ds_read2_b32 v[2:3], v23 offset0:2 offset1:3
	ds_read2_b32 v[4:5], v23 offset0:4 offset1:5
	ds_read2_b32 v[6:7], v23 offset0:6 offset1:7
	s_ashr_i32 s31, s30, 31
	s_lshl_b64 s[30:31], s[30:31], 1
	s_add_u32 s30, s24, s30
	s_addc_u32 s31, s25, s31
	s_waitcnt lgkmcnt(3)
	v_cvt_pk_bf16_f32 v0, v0, v1
	s_waitcnt lgkmcnt(2)
	v_cvt_pk_bf16_f32 v1, v2, v3
	s_waitcnt lgkmcnt(1)
	v_cvt_pk_bf16_f32 v2, v4, v5
	v_add_u32_e32 v4, s28, v20
	v_ashrrev_i32_e32 v5, 31, v4
	v_lshl_add_u64 v[12:13], s[30:31], 0, v[10:11]
	s_waitcnt lgkmcnt(0)
	v_cvt_pk_bf16_f32 v3, v6, v7
	v_lshlrev_b64 v[4:5], 11, v[4:5]
	ds_read2_b32 v[6:7], v24 offset1:1
	ds_read2_b32 v[14:15], v24 offset0:2 offset1:3
	ds_read2_b32 v[16:17], v24 offset0:4 offset1:5
	ds_read2_b32 v[26:27], v24 offset0:6 offset1:7
	v_lshl_add_u64 v[4:5], v[12:13], 0, v[4:5]
	global_store_dwordx4 v[4:5], v[0:3], off sc1
	v_add_u32_e32 v4, s28, v22
	v_ashrrev_i32_e32 v5, 31, v4
	v_lshlrev_b64 v[4:5], 11, v[4:5]
	s_waitcnt lgkmcnt(3)
	v_cvt_pk_bf16_f32 v0, v6, v7
	s_waitcnt lgkmcnt(2)
	v_cvt_pk_bf16_f32 v1, v14, v15
	s_waitcnt lgkmcnt(1)
	v_cvt_pk_bf16_f32 v2, v16, v17
	s_waitcnt lgkmcnt(0)
	v_cvt_pk_bf16_f32 v3, v26, v27
	v_lshl_add_u64 v[4:5], v[12:13], 0, v[4:5]
	s_cmpk_gt_i32 s19, 0x87f
	global_store_dwordx4 v[4:5], v[0:3], off sc1
	s_cbranch_scc1 .LBB0_33

; DI void phase_prep(const Params& p, u16* sm, int wv) {
;     ...
;     for (int row0 = (bid * 4 + (tid >> 6)) * 4; row0 < MTOK; row0 += nb * 16) {
;       f32x4 xv[4][4];
; #pragma unroll
;       for (int q = 0; q < 4; ++q)
; #pragma unroll
;         for (int j = 0; j < 4; ++j) xv[q][j] = __builtin_nontemporal_load((const f32x4*)(p.x + (size_t)(row0 + q) * DM + j * 256 + lane * 4));
; #pragma unroll
;       for (int q = 0; q < 4; ++q) {
;         float sq = 0.f;
; #pragma unroll
;         for (int j = 0; j < 4; ++j) {
;           const f32x4 v = xv[q][j];
;           sq += v[0] * v[0] + v[1] * v[1] + v[2] * v[2] + v[3] * v[3];
;           u32x2 o = {pk2(v[0], v[1]), pk2(v[2], v[3])};
;           *(u32x2*)(p.xg + (size_t)(row0 + q) * DM + j * 256 + lane * 4) = o;
;         }
;         sq = wave_sum(sq, lane);
;         if (lane == 0) p.ss[row0 + q] = sq;
;       }
;     }
.LBB0_36:
	v_add_co_u32_e32 v0, vcc, 0xffffd000, v54
	s_nop 1
	v_addc_co_u32_e32 v1, vcc, -1, v55, vcc
	global_load_dwordx4 v[66:69], v[0:1], off offset:-3072 nt
	global_load_dwordx4 v[70:73], v[0:1], off offset:-2048 nt
	global_load_dwordx4 v[74:77], v[0:1], off offset:-1024 nt
	global_load_dwordx4 v[78:81], v[0:1], off nt
	global_load_dwordx4 v[12:15], v[54:55], off offset:-3072 nt
	global_load_dwordx4 v[8:11], v[54:55], off offset:-2048 nt
	s_waitcnt lgkmcnt(0)
	global_load_dwordx4 v[4:7], v[54:55], off offset:-1024 nt
	global_load_dwordx4 v[0:3], v[54:55], off nt
	v_add_co_u32_e32 v16, vcc, 0xffffe000, v54
	s_waitcnt vmcnt(7)
	v_mul_f32_e32 v51, v67, v67
	v_addc_co_u32_e32 v17, vcc, -1, v55, vcc
	v_add_co_u32_e32 v18, vcc, 0xfffff000, v54
	global_load_dwordx4 v[44:47], v[16:17], off offset:-3072 nt
	global_load_dwordx4 v[40:43], v[16:17], off offset:-2048 nt
	global_load_dwordx4 v[36:39], v[16:17], off offset:-1024 nt
	global_load_dwordx4 v[32:35], v[16:17], off nt
	v_addc_co_u32_e32 v19, vcc, -1, v55, vcc
	global_load_dwordx4 v[28:31], v[18:19], off offset:-3072 nt
	global_load_dwordx4 v[24:27], v[18:19], off offset:-2048 nt
	global_load_dwordx4 v[20:23], v[18:19], off offset:-1024 nt
	s_nop 0
	global_load_dwordx4 v[16:19], v[54:55], off offset:-4096 nt
	s_waitcnt vmcnt(14)
	v_mul_f32_e32 v58, v71, v71
	s_waitcnt vmcnt(13)
	v_mul_f32_e32 v59, v75, v75
	v_fmac_f32_e32 v51, v66, v66
	v_fmac_f32_e32 v58, v70, v70
	s_waitcnt vmcnt(12)
	v_mul_f32_e32 v65, v79, v79
	v_fmac_f32_e32 v59, v74, v74
	v_fmac_f32_e32 v51, v68, v68
	v_fmac_f32_e32 v58, v72, v72
	v_fmac_f32_e32 v65, v78, v78
	v_fmac_f32_e32 v59, v76, v76
	v_fmac_f32_e32 v51, v69, v69
	v_fmac_f32_e32 v58, v73, v73
	v_fmac_f32_e32 v65, v80, v80
	v_fmac_f32_e32 v59, v77, v77
	v_add_f32_e32 v51, v51, v58
	v_fmac_f32_e32 v65, v81, v81
	v_add_f32_e32 v51, v51, v59
	v_add_f32_e32 v51, v51, v65
	ds_bpermute_b32 v58, v49, v51
	v_cvt_pk_bf16_f32 v66, v66, v67
	v_cvt_pk_bf16_f32 v67, v68, v69
	s_waitcnt lgkmcnt(0)
	v_add_f32_e32 v51, v51, v58
	ds_bpermute_b32 v58, v60, v51
	s_waitcnt lgkmcnt(0)
	v_add_f32_e32 v51, v51, v58
	ds_bpermute_b32 v58, v61, v51
	s_waitcnt lgkmcnt(0)
	v_add_f32_e32 v51, v51, v58
	ds_bpermute_b32 v65, v62, v51
	v_add_co_u32_e32 v58, vcc, s16, v52
	s_waitcnt lgkmcnt(0)
	v_add_f32_e32 v51, v51, v65
	ds_bpermute_b32 v65, v63, v51
	v_addc_co_u32_e32 v59, vcc, -1, v53, vcc
	global_store_dwordx2 v[58:59], v[66:67], off offset:-3584 sc1
	v_cvt_pk_bf16_f32 v66, v70, v71
	s_waitcnt lgkmcnt(0)
	v_add_f32_e32 v51, v51, v65
	ds_bpermute_b32 v65, v64, v51
	v_cvt_pk_bf16_f32 v67, v72, v73
	global_store_dwordx2 v[58:59], v[66:67], off offset:-3072 sc1
	v_cvt_pk_bf16_f32 v66, v74, v75
	v_cvt_pk_bf16_f32 v67, v76, v77
	global_store_dwordx2 v[58:59], v[66:67], off offset:-2560 sc1
	v_cvt_pk_bf16_f32 v66, v78, v79
	v_cvt_pk_bf16_f32 v67, v80, v81
	global_store_dwordx2 v[58:59], v[66:67], off offset:-2048 sc1
	s_and_saveexec_b64 s[14:15], s[0:1]
	s_cbranch_execz .LBB0_38
	s_waitcnt lgkmcnt(0)
	v_add_f32_e32 v51, v51, v65
	global_store_dword v[56:57], v51, off offset:-8 sc1
.LBB0_38:
	s_or_b64 exec, exec, s[14:15]
	s_waitcnt vmcnt(11)
	v_mul_f32_e32 v51, v45, v45
	s_waitcnt vmcnt(10) lgkmcnt(0)
	v_mul_f32_e32 v65, v41, v41
	v_fmac_f32_e32 v51, v44, v44
	v_fmac_f32_e32 v65, v40, v40
	v_fmac_f32_e32 v51, v46, v46
	v_fmac_f32_e32 v65, v42, v42
	v_fmac_f32_e32 v51, v47, v47
	v_fmac_f32_e32 v65, v43, v43
	v_add_f32_e32 v51, v51, v65
	s_waitcnt vmcnt(9)
	v_mul_f32_e32 v65, v37, v37
	v_fmac_f32_e32 v65, v36, v36
	v_fmac_f32_e32 v65, v38, v38
	v_fmac_f32_e32 v65, v39, v39
	v_add_f32_e32 v51, v51, v65
	s_waitcnt vmcnt(8)
	v_mul_f32_e32 v65, v33, v33
	v_fmac_f32_e32 v65, v32, v32
	v_fmac_f32_e32 v65, v34, v34
	v_fmac_f32_e32 v65, v35, v35
	v_add_f32_e32 v51, v51, v65
	ds_bpermute_b32 v65, v49, v51
	v_cvt_pk_bf16_f32 v44, v44, v45
	v_cvt_pk_bf16_f32 v45, v46, v47
	global_store_dwordx2 v[58:59], v[44:45], off offset:-1536 sc1
	v_cvt_pk_bf16_f32 v40, v40, v41
	s_waitcnt lgkmcnt(0)
	v_add_f32_e32 v51, v51, v65
	ds_bpermute_b32 v65, v60, v51
	v_cvt_pk_bf16_f32 v41, v42, v43
	global_store_dwordx2 v[58:59], v[40:41], off offset:-1024 sc1
	v_cvt_pk_bf16_f32 v40, v36, v37
	v_cvt_pk_bf16_f32 v41, v38, v39
	s_waitcnt lgkmcnt(0)
	v_add_f32_e32 v51, v51, v65
	ds_bpermute_b32 v65, v61, v51
	v_cvt_pk_bf16_f32 v32, v32, v33
	v_cvt_pk_bf16_f32 v33, v34, v35
	global_store_dwordx2 v[58:59], v[40:41], off offset:-512 sc1
	global_store_dwordx2 v[52:53], v[32:33], off offset:-4096 sc1
	s_waitcnt lgkmcnt(0)
	v_add_f32_e32 v51, v51, v65
	ds_bpermute_b32 v65, v62, v51
	s_waitcnt lgkmcnt(0)
	v_add_f32_e32 v44, v51, v65
	ds_bpermute_b32 v45, v63, v44
	s_waitcnt lgkmcnt(0)
	v_add_f32_e32 v36, v44, v45
	ds_bpermute_b32 v37, v64, v36
	s_and_saveexec_b64 s[14:15], s[0:1]
	s_cbranch_execz .LBB0_40
	s_waitcnt lgkmcnt(0)
	v_add_f32_e32 v32, v36, v37
	global_store_dword v[56:57], v32, off offset:-4 sc1
; DI void phase_prep(const Params& p, u16* sm, int wv) {
;     ...
;         for (int j = 0; j < 4; ++j) xv[q][j] = __builtin_nontemporal_load((const f32x4*)(p.x + (size_t)(row0 + q) * DM + j * 256 + lane * 4));
; #pragma unroll
;       for (int q = 0; q < 4; ++q) {
;         float sq = 0.f;
; #pragma unroll
;         for (int j = 0; j < 4; ++j) {
;           const f32x4 v = xv[q][j];
;           sq += v[0] * v[0] + v[1] * v[1] + v[2] * v[2] + v[3] * v[3];
;           u32x2 o = {pk2(v[0], v[1]), pk2(v[2], v[3])};
;           *(u32x2*)(p.xg + (size_t)(row0 + q) * DM + j * 256 + lane * 4) = o;
;         }
;         sq = wave_sum(sq, lane);
;         if (lane == 0) p.ss[row0 + q] = sq;
;       }
;     }
.LBB0_40:
	s_or_b64 exec, exec, s[14:15]
	s_waitcnt vmcnt(11)
	v_mul_f32_e32 v32, v29, v29
	s_waitcnt vmcnt(10)
	v_mul_f32_e32 v33, v25, v25
	v_fmac_f32_e32 v32, v28, v28
	v_fmac_f32_e32 v33, v24, v24
	v_fmac_f32_e32 v32, v30, v30
	v_fmac_f32_e32 v33, v26, v26
	v_fmac_f32_e32 v32, v31, v31
	v_fmac_f32_e32 v33, v27, v27
	v_add_f32_e32 v32, v32, v33
	s_waitcnt vmcnt(9)
	v_mul_f32_e32 v33, v21, v21
	v_fmac_f32_e32 v33, v20, v20
	v_fmac_f32_e32 v33, v22, v22
	v_fmac_f32_e32 v33, v23, v23
	v_add_f32_e32 v32, v32, v33
	s_waitcnt vmcnt(8)
	v_mul_f32_e32 v33, v17, v17
	v_fmac_f32_e32 v33, v16, v16
	v_fmac_f32_e32 v33, v18, v18
	v_fmac_f32_e32 v33, v19, v19
	v_add_f32_e32 v32, v32, v33
	ds_bpermute_b32 v33, v49, v32
	v_cvt_pk_bf16_f32 v28, v28, v29
	v_cvt_pk_bf16_f32 v29, v30, v31
	global_store_dwordx2 v[52:53], v[28:29], off offset:-3584 sc1
	v_cvt_pk_bf16_f32 v24, v24, v25
	s_waitcnt lgkmcnt(0)
	v_add_f32_e32 v32, v32, v33
	ds_bpermute_b32 v33, v60, v32
	v_cvt_pk_bf16_f32 v25, v26, v27
	global_store_dwordx2 v[52:53], v[24:25], off offset:-3072 sc1
	v_cvt_pk_bf16_f32 v24, v20, v21
	v_cvt_pk_bf16_f32 v25, v22, v23
	s_waitcnt lgkmcnt(0)
	v_add_f32_e32 v32, v32, v33
	ds_bpermute_b32 v33, v61, v32
	v_cvt_pk_bf16_f32 v16, v16, v17
	v_cvt_pk_bf16_f32 v17, v18, v19
	global_store_dwordx2 v[52:53], v[24:25], off offset:-2560 sc1
	global_store_dwordx2 v[52:53], v[16:17], off offset:-2048 sc1
	s_waitcnt lgkmcnt(0)
	v_add_f32_e32 v32, v32, v33
	ds_bpermute_b32 v33, v62, v32
	s_waitcnt lgkmcnt(0)
	v_add_f32_e32 v28, v32, v33
	ds_bpermute_b32 v29, v63, v28
	s_waitcnt lgkmcnt(0)
	v_add_f32_e32 v20, v28, v29
	ds_bpermute_b32 v21, v64, v20
	s_and_saveexec_b64 s[14:15], s[0:1]
	s_cbranch_execz .LBB0_42
	s_waitcnt lgkmcnt(0)
	v_add_f32_e32 v16, v20, v21
	global_store_dword v[56:57], v16, off sc1
.LBB0_42:
	s_or_b64 exec, exec, s[14:15]
	v_mul_f32_e32 v16, v13, v13
	v_mul_f32_e32 v17, v9, v9
	v_fmac_f32_e32 v16, v12, v12
	v_fmac_f32_e32 v17, v8, v8
	v_fmac_f32_e32 v16, v14, v14
	v_fmac_f32_e32 v17, v10, v10
	v_fmac_f32_e32 v16, v15, v15
	v_fmac_f32_e32 v17, v11, v11
	v_add_f32_e32 v16, v16, v17
	v_mul_f32_e32 v17, v5, v5
	v_fmac_f32_e32 v17, v4, v4
	v_fmac_f32_e32 v17, v6, v6
	v_fmac_f32_e32 v17, v7, v7
	v_add_f32_e32 v16, v16, v17
	v_mul_f32_e32 v17, v1, v1
	v_fmac_f32_e32 v17, v0, v0
	v_fmac_f32_e32 v17, v2, v2
	v_fmac_f32_e32 v17, v3, v3
	v_add_f32_e32 v16, v16, v17
	ds_bpermute_b32 v17, v49, v16
	v_cvt_pk_bf16_f32 v12, v12, v13
	v_cvt_pk_bf16_f32 v13, v14, v15
	global_store_dwordx2 v[52:53], v[12:13], off offset:-1536 sc1
	v_cvt_pk_bf16_f32 v8, v8, v9
	s_waitcnt lgkmcnt(0)
	v_add_f32_e32 v16, v16, v17
	ds_bpermute_b32 v17, v60, v16
	v_cvt_pk_bf16_f32 v9, v10, v11
	global_store_dwordx2 v[52:53], v[8:9], off offset:-1024 sc1
	v_cvt_pk_bf16_f32 v8, v4, v5
	v_cvt_pk_bf16_f32 v9, v6, v7
	s_waitcnt lgkmcnt(0)
	v_add_f32_e32 v16, v16, v17
	ds_bpermute_b32 v17, v61, v16
	v_cvt_pk_bf16_f32 v0, v0, v1
	v_cvt_pk_bf16_f32 v1, v2, v3
	global_store_dwordx2 v[52:53], v[8:9], off offset:-512 sc1
	global_store_dwordx2 v[52:53], v[0:1], off sc1
	s_waitcnt lgkmcnt(0)
	v_add_f32_e32 v16, v16, v17
	ds_bpermute_b32 v17, v62, v16
	s_waitcnt lgkmcnt(0)
	v_add_f32_e32 v12, v16, v17
	ds_bpermute_b32 v13, v63, v12
	s_waitcnt lgkmcnt(0)
	v_add_f32_e32 v4, v12, v13
	ds_bpermute_b32 v5, v64, v4
	s_and_saveexec_b64 s[14:15], s[0:1]
	s_cbranch_execz .LBB0_35
	s_waitcnt lgkmcnt(0)
	v_add_f32_e32 v0, v4, v5
	global_store_dword v[56:57], v0, off offset:4 sc1
	s_branch .LBB0_35

; DI void phase_prep(const Params& p, u16* sm, int wv) {
;     ...
;   for (int i = bid * 256 + tid; i < 2 * MTOK; i += nb * 256) p.ss[MTOK + i] = 0.f;
.LBB0_47:
	v_ashrrev_i32_e32 v11, 31, v2
	v_mov_b32_e32 v10, v2
	v_lshl_add_u64 v[10:11], v[10:11], 2, s[92:93]
	v_ashrrev_i32_e32 v9, 31, v3
	v_mov_b32_e32 v8, v3
	v_add_co_u32_e32 v10, vcc, 0x10000, v10
	v_add_u32_e32 v7, -2, v7
	v_lshl_add_u64 v[8:9], v[8:9], 2, s[92:93]
	v_addc_co_u32_e32 v11, vcc, 0, v11, vcc
	v_cmp_eq_u32_e64 s[0:1], 0, v7
	v_add_co_u32_e32 v8, vcc, 0x10000, v8
	v_add_u32_e32 v3, s12, v3
	v_add_u32_e32 v2, s7, v2
	s_or_b64 s[10:11], s[0:1], s[10:11]
	v_addc_co_u32_e32 v9, vcc, 0, v9, vcc
	global_store_dword v[10:11], v6, off sc1
	global_store_dword v[8:9], v6, off sc1
	s_andn2_b64 exec, exec, s[10:11]
	s_cbranch_execnz .LBB0_47
	s_or_b64 exec, exec, s[10:11]
	v_mad_u64_u32 v[0:1], s[0:1], v5, s6, v[0:1]
	v_cmp_ne_u32_e32 vcc, v4, v5
	s_orn2_b64 s[0:1], vcc, exec

; DI void phase_prep(const Params& p, u16* sm, int wv) {
;     ...
;   for (int i = bid * 256 + tid; i < 2 * MTOK; i += nb * 256) p.ss[MTOK + i] = 0.f;
;   if (bid == 0 && tid < 64) p.ctr[tid] = 0u;
.LBB0_51:
	v_add_u32_e32 v0, s6, v0
	v_cmp_lt_i32_e32 vcc, s7, v0
	global_store_dword v[2:3], v1, off sc1
	s_or_b64 s[8:9], vcc, s[8:9]
	v_lshl_add_u64 v[2:3], v[2:3], 0, s[0:1]
	s_andn2_b64 exec, exec, s[8:9]
	s_cbranch_execnz .LBB0_51
.LBB0_52:
	s_or_b64 exec, exec, s[4:5]
	s_cmp_eq_u32 s2, 0
	s_cselect_b64 s[0:1], -1, 0
	v_cmp_gt_i32_e32 vcc, 64, v48
	s_and_b64 s[4:5], s[0:1], vcc
	s_and_saveexec_b64 s[0:1], s[4:5]
	s_cbranch_execz .LBB0_54
	v_ashrrev_i32_e32 v49, 31, v48
	v_lshl_add_u64 v[0:1], v[48:49], 2, s[94:95]
	v_mov_b32_e32 v2, 0
	global_store_dword v[0:1], v2, off sc1

; template <int EPI>
; DI void gemm_tile(const Params& p, int layer, int mt, int nt, u16* sm, int wv) {
;     ...
;       const int vbase = (nt == 4) ? 0 : (nt == 5) ? 2 : (nt == 13) ? 4 : (nt == 22) ? 6 : 8;
;       const int bb = m0 / SEQ, s0 = m0 % SEQ;
;       constexpr int VSTR = 136;
; #pragma unroll
;       for (int i = 0; i < 8; ++i) {
;         float rs[4];
; #pragma unroll
;         for (int e = 0; e < 4; ++e) rs[e] = __builtin_amdgcn_rsqf(ssl[m0 + wm * 128 + 16 * i + 4 * fq + e] * (1.f / DM) + EPS);
;         const int pos = 16 * i + 8 * (fq & 1) + 4 * (fq >> 1);
; #pragma unroll
;         for (int j = 0; j < 4; ++j) {
;           u32x2 v = {pk2(acc[i][j][0] * rs[0], acc[i][j][1] * rs[1]), pk2(acc[i][j][2] * rs[2], acc[i][j][3] * rs[3])};
;           *(u32x2*)(stg + (16 * j + fr) * VSTR + pos) = v;
;         }
;       }
.LBB0_111:
	v_lshl_or_b32 v132, v134, 2, v139
	v_lshrrev_b32_e32 v133, 2, v138
	s_waitcnt vmcnt(6)
	v_and_b32_e32 v142, 8, v133
	v_ashrrev_i32_e32 v133, 31, v132
	v_lshl_add_u64 v[132:133], v[132:133], 2, s[0:1]
	global_load_dwordx4 v[138:141], v[132:133], off
	v_lshlrev_b32_e32 v0, 4, v134
	v_and_b32_e32 v0, 16, v0
	v_add_u32_e32 v0, v135, v0
	s_lshr_b32 s2, s19, 5
	s_mul_i32 s2, s2, 10
	s_add_i32 s2, s6, s2
	s_and_b32 s3, s21, 0x1f00
	s_mov_b32 s5, s25
	s_lshl_b32 s4, s3, 1
	s_waitcnt vmcnt(0)
	v_fmamk_f32 v138, v138, 0x3a800000, v188
	v_fmamk_f32 v139, v139, 0x3a800000, v188
	v_fmamk_f32 v140, v140, 0x3a800000, v188
	v_fmamk_f32 v141, v141, 0x3a800000, v188
	v_rsq_f32_e32 v138, v138
	v_rsq_f32_e32 v139, v139
	v_rsq_f32_e32 v140, v140
	v_rsq_f32_e32 v141, v141
	v_mul_f32_e32 v118, v118, v138
	v_mul_f32_e32 v119, v119, v139
	v_mul_f32_e32 v114, v114, v138
	v_mul_f32_e32 v115, v115, v139
	v_mul_f32_e32 v120, v120, v140
	v_mul_f32_e32 v121, v121, v141
	v_cvt_pk_bf16_f32 v118, v118, v119
	v_cvt_pk_bf16_f32 v119, v120, v121
	v_cvt_pk_bf16_f32 v120, v114, v115
	v_mul_f32_e32 v114, v116, v140
	v_mul_f32_e32 v115, v117, v141
	v_mul_f32_e32 v126, v126, v138
	v_mul_f32_e32 v127, v127, v139
	v_cvt_pk_bf16_f32 v121, v114, v115
	global_load_dwordx4 v[114:117], v[132:133], off offset:64
	v_mul_f32_e32 v128, v128, v140
	v_mul_f32_e32 v129, v129, v141
	v_cvt_pk_bf16_f32 v126, v126, v127
	v_cvt_pk_bf16_f32 v127, v128, v129
	v_mul_u32_u24_e32 v128, 0x110, v137
	v_add3_u32 v0, v0, v142, v128
	v_mul_f32_e32 v122, v122, v138
	v_mul_f32_e32 v123, v123, v139
	v_mul_f32_e32 v124, v124, v140
	v_mul_f32_e32 v125, v125, v141
	v_cvt_pk_bf16_f32 v122, v122, v123
	v_cvt_pk_bf16_f32 v123, v124, v125
	s_waitcnt vmcnt(0)
	v_fmamk_f32 v114, v114, 0x3a800000, v188
	v_fmamk_f32 v115, v115, 0x3a800000, v188
	v_fmamk_f32 v116, v116, 0x3a800000, v188
	v_fmamk_f32 v117, v117, 0x3a800000, v188
	v_rsq_f32_e32 v114, v114
	v_rsq_f32_e32 v115, v115
	v_rsq_f32_e32 v116, v116
	v_rsq_f32_e32 v117, v117
	v_mul_f32_e32 v110, v110, v114
	v_mul_f32_e32 v111, v111, v115
	s_nop 0
	v_cvt_pk_bf16_f32 v110, v110, v111
	v_mul_f32_e32 v112, v112, v116
	v_mul_f32_e32 v113, v113, v117
	v_mul_f32_e32 v106, v106, v114
	v_mul_f32_e32 v107, v107, v115
	v_cvt_pk_bf16_f32 v111, v112, v113
	v_mul_f32_e32 v102, v102, v114
	v_mul_f32_e32 v103, v103, v115
	ds_write2_b64 v0, v[126:127], v[110:111] offset1:4
	v_cvt_pk_bf16_f32 v110, v106, v107
	v_mul_f32_e32 v106, v108, v116
	v_mul_f32_e32 v107, v109, v117
	v_cvt_pk_bf16_f32 v108, v102, v103
	v_mul_f32_e32 v102, v104, v116
	v_mul_f32_e32 v103, v105, v117
	v_cvt_pk_bf16_f32 v111, v106, v107
	v_add_u32_e32 v106, 0x1000, v0
	v_cvt_pk_bf16_f32 v109, v102, v103
	v_add_u32_e32 v102, 0x2000, v0
	ds_write2_b64 v106, v[122:123], v[110:111] offset0:32 offset1:36
	ds_write2_b64 v102, v[118:119], v[108:109] offset0:64 offset1:68
	global_load_dwordx4 v[108:111], v[132:133], off offset:128
	v_mul_f32_e32 v98, v98, v114
	v_mul_f32_e32 v99, v99, v115
	s_nop 0
	v_cvt_pk_bf16_f32 v104, v98, v99
	v_mul_f32_e32 v98, v100, v116
	v_mul_f32_e32 v99, v101, v117
	s_nop 0
	v_cvt_pk_bf16_f32 v105, v98, v99
	v_add_u32_e32 v98, 0x3000, v0
	ds_write2_b64 v98, v[120:121], v[104:105] offset0:96 offset1:100
	s_waitcnt vmcnt(0)
	v_fmamk_f32 v99, v108, 0x3a800000, v188
	v_rsq_f32_e32 v100, v99
	v_fmamk_f32 v99, v109, 0x3a800000, v188
	v_rsq_f32_e32 v101, v99
	v_fmamk_f32 v99, v110, 0x3a800000, v188
	v_rsq_f32_e32 v104, v99
	v_fmamk_f32 v99, v111, 0x3a800000, v188
	v_rsq_f32_e32 v105, v99
	v_mul_f32_e32 v86, v86, v100
	v_mul_f32_e32 v87, v87, v101
	v_mul_f32_e32 v82, v82, v100
	v_mul_f32_e32 v83, v83, v101
	v_cvt_pk_bf16_f32 v86, v86, v87
	v_mul_f32_e32 v88, v88, v104
	v_mul_f32_e32 v89, v89, v105
	v_mul_f32_e32 v94, v94, v100
	v_mul_f32_e32 v95, v95, v101
	v_cvt_pk_bf16_f32 v87, v88, v89
	v_cvt_pk_bf16_f32 v88, v82, v83
	v_mul_f32_e32 v82, v84, v104
	v_mul_f32_e32 v83, v85, v105
	v_mul_f32_e32 v96, v96, v104
	v_mul_f32_e32 v97, v97, v105
	v_cvt_pk_bf16_f32 v89, v82, v83
	global_load_dwordx4 v[82:85], v[132:133], off offset:192
	v_cvt_pk_bf16_f32 v94, v94, v95
	v_cvt_pk_bf16_f32 v95, v96, v97
	v_mul_f32_e32 v90, v90, v100
	v_mul_f32_e32 v91, v91, v101
	v_mul_f32_e32 v92, v92, v104
	v_mul_f32_e32 v93, v93, v105
	v_cvt_pk_bf16_f32 v90, v90, v91
	v_cvt_pk_bf16_f32 v91, v92, v93
	s_waitcnt vmcnt(0)
	v_fmamk_f32 v82, v82, 0x3a800000, v188
	v_fmamk_f32 v83, v83, 0x3a800000, v188
	v_fmamk_f32 v84, v84, 0x3a800000, v188
	v_fmamk_f32 v85, v85, 0x3a800000, v188
	v_rsq_f32_e32 v82, v82
	v_rsq_f32_e32 v83, v83
	v_rsq_f32_e32 v84, v84
	v_rsq_f32_e32 v85, v85
	v_mul_f32_e32 v66, v66, v82
	v_mul_f32_e32 v67, v67, v83
	s_nop 0
	v_cvt_pk_bf16_f32 v66, v66, v67
	v_mul_f32_e32 v68, v68, v84
	v_mul_f32_e32 v69, v69, v85
	v_mul_f32_e32 v78, v78, v82
	v_mul_f32_e32 v79, v79, v83
	v_cvt_pk_bf16_f32 v67, v68, v69
	ds_write2_b64 v98, v[88:89], v[66:67] offset0:104 offset1:108
	global_load_dwordx4 v[66:69], v[132:133], off offset:256
	v_mul_f32_e32 v80, v80, v84
	v_mul_f32_e32 v81, v81, v85
	v_cvt_pk_bf16_f32 v78, v78, v79
	v_cvt_pk_bf16_f32 v79, v80, v81
	ds_write2_b64 v0, v[94:95], v[78:79] offset0:8 offset1:12
	v_mul_f32_e32 v74, v74, v82
	v_mul_f32_e32 v75, v75, v83
	v_mul_f32_e32 v76, v76, v84
	v_mul_f32_e32 v77, v77, v85
	v_mul_f32_e32 v70, v70, v82
	v_mul_f32_e32 v71, v71, v83
	v_mul_f32_e32 v72, v72, v84
	v_mul_f32_e32 v73, v73, v85
	v_cvt_pk_bf16_f32 v74, v74, v75
	v_cvt_pk_bf16_f32 v75, v76, v77
	v_cvt_pk_bf16_f32 v70, v70, v71
	v_cvt_pk_bf16_f32 v71, v72, v73
	ds_write2_b64 v106, v[90:91], v[74:75] offset0:40 offset1:44
	ds_write2_b64 v102, v[86:87], v[70:71] offset0:72 offset1:76
	s_waitcnt vmcnt(0)
; template <int EPI>
; DI void gemm_tile(const Params& p, int layer, int mt, int nt, u16* sm, int wv) {
;     ...
;       for (int i = 0; i < 8; ++i) {
;         float rs[4];
; #pragma unroll
;         for (int e = 0; e < 4; ++e) rs[e] = __builtin_amdgcn_rsqf(ssl[m0 + wm * 128 + 16 * i + 4 * fq + e] * (1.f / DM) + EPS);
;         const int pos = 16 * i + 8 * (fq & 1) + 4 * (fq >> 1);
; #pragma unroll
;         for (int j = 0; j < 4; ++j) {
;           u32x2 v = {pk2(acc[i][j][0] * rs[0], acc[i][j][1] * rs[1]), pk2(acc[i][j][2] * rs[2], acc[i][j][3] * rs[3])};
;           *(u32x2*)(stg + (16 * j + fr) * VSTR + pos) = v;
;         }
;       }
	v_fmamk_f32 v66, v66, 0x3a800000, v188
	v_fmamk_f32 v67, v67, 0x3a800000, v188
	v_fmamk_f32 v68, v68, 0x3a800000, v188
	v_fmamk_f32 v69, v69, 0x3a800000, v188
	v_rsq_f32_e32 v66, v66
	v_rsq_f32_e32 v67, v67
	v_rsq_f32_e32 v68, v68
	v_rsq_f32_e32 v69, v69
	v_mul_f32_e32 v54, v54, v66
	v_mul_f32_e32 v55, v55, v67
	v_mul_f32_e32 v50, v50, v66
	v_mul_f32_e32 v51, v51, v67
	v_mul_f32_e32 v56, v56, v68
	v_mul_f32_e32 v57, v57, v69
	v_cvt_pk_bf16_f32 v54, v54, v55
	v_cvt_pk_bf16_f32 v55, v56, v57
	v_cvt_pk_bf16_f32 v56, v50, v51
	v_mul_f32_e32 v50, v52, v68
	v_mul_f32_e32 v51, v53, v69
	v_mul_f32_e32 v62, v62, v66
	v_mul_f32_e32 v63, v63, v67
	v_cvt_pk_bf16_f32 v57, v50, v51
	global_load_dwordx4 v[50:53], v[132:133], off offset:320
	v_mul_f32_e32 v64, v64, v68
	v_mul_f32_e32 v65, v65, v69
	v_cvt_pk_bf16_f32 v62, v62, v63
	v_cvt_pk_bf16_f32 v63, v64, v65
	v_mul_f32_e32 v58, v58, v66
	v_mul_f32_e32 v59, v59, v67
	v_mul_f32_e32 v60, v60, v68
	v_mul_f32_e32 v61, v61, v69
	v_cvt_pk_bf16_f32 v58, v58, v59
	v_cvt_pk_bf16_f32 v59, v60, v61
	s_waitcnt vmcnt(0)
	v_fmamk_f32 v50, v50, 0x3a800000, v188
	v_fmamk_f32 v51, v51, 0x3a800000, v188
	v_fmamk_f32 v52, v52, 0x3a800000, v188
	v_fmamk_f32 v53, v53, 0x3a800000, v188
	v_rsq_f32_e32 v50, v50
	v_rsq_f32_e32 v51, v51
	v_rsq_f32_e32 v52, v52
	v_rsq_f32_e32 v53, v53
	v_mul_f32_e32 v34, v34, v50
	v_mul_f32_e32 v35, v35, v51
	s_nop 0
	v_cvt_pk_bf16_f32 v34, v34, v35
	v_mul_f32_e32 v36, v36, v52
	v_mul_f32_e32 v37, v37, v53
	v_mul_f32_e32 v46, v46, v50
	v_mul_f32_e32 v47, v47, v51
	v_cvt_pk_bf16_f32 v35, v36, v37
	ds_write2_b64 v98, v[56:57], v[34:35] offset0:112 offset1:116
	global_load_dwordx4 v[34:37], v[132:133], off offset:384
	v_mul_f32_e32 v48, v48, v52
	v_mul_f32_e32 v49, v49, v53
	v_cvt_pk_bf16_f32 v46, v46, v47
	v_cvt_pk_bf16_f32 v47, v48, v49
	ds_write2_b64 v0, v[62:63], v[46:47] offset0:16 offset1:20
	v_mul_f32_e32 v42, v42, v50
	v_mul_f32_e32 v43, v43, v51
	v_mul_f32_e32 v44, v44, v52
	v_mul_f32_e32 v45, v45, v53
	v_mul_f32_e32 v38, v38, v50
	v_mul_f32_e32 v39, v39, v51
	v_mul_f32_e32 v40, v40, v52
	v_mul_f32_e32 v41, v41, v53
	v_cvt_pk_bf16_f32 v42, v42, v43
	v_cvt_pk_bf16_f32 v43, v44, v45
	v_cvt_pk_bf16_f32 v38, v38, v39
	v_cvt_pk_bf16_f32 v39, v40, v41
	ds_write2_b64 v106, v[58:59], v[42:43] offset0:48 offset1:52
	ds_write2_b64 v102, v[54:55], v[38:39] offset0:80 offset1:84
	s_waitcnt vmcnt(0)
	v_fmamk_f32 v34, v34, 0x3a800000, v188
	v_fmamk_f32 v35, v35, 0x3a800000, v188
	v_fmamk_f32 v36, v36, 0x3a800000, v188
	v_fmamk_f32 v37, v37, 0x3a800000, v188
	v_rsq_f32_e32 v34, v34
	v_rsq_f32_e32 v35, v35
	v_rsq_f32_e32 v36, v36
	v_rsq_f32_e32 v37, v37
	v_mul_f32_e32 v30, v30, v34
	v_mul_f32_e32 v31, v31, v35
	s_nop 0
	v_cvt_pk_bf16_f32 v30, v30, v31
	v_mul_f32_e32 v32, v32, v36
	v_mul_f32_e32 v33, v33, v37
	v_mul_f32_e32 v26, v26, v34
	v_mul_f32_e32 v27, v27, v35
	v_cvt_pk_bf16_f32 v31, v32, v33
	v_mul_f32_e32 v22, v22, v34
	v_mul_f32_e32 v23, v23, v35
	v_mul_f32_e32 v18, v18, v34
	v_mul_f32_e32 v19, v19, v35
	global_load_dwordx4 v[32:35], v[132:133], off offset:448
	v_mul_f32_e32 v24, v24, v36
	v_mul_f32_e32 v25, v25, v37
	v_mul_f32_e32 v20, v20, v36
	v_mul_f32_e32 v21, v21, v37
	v_cvt_pk_bf16_f32 v22, v22, v23
	v_cvt_pk_bf16_f32 v23, v24, v25
	v_cvt_pk_bf16_f32 v18, v18, v19
	v_cvt_pk_bf16_f32 v19, v20, v21
	v_mul_f32_e32 v28, v28, v36
	v_mul_f32_e32 v29, v29, v37
	v_cvt_pk_bf16_f32 v26, v26, v27
	v_cvt_pk_bf16_f32 v27, v28, v29
	s_waitcnt vmcnt(0)
; template <int EPI>
; DI void gemm_tile(const Params& p, int layer, int mt, int nt, u16* sm, int wv) {
;     ...
;       for (int i = 0; i < 8; ++i) {
;         float rs[4];
; #pragma unroll
;         for (int e = 0; e < 4; ++e) rs[e] = __builtin_amdgcn_rsqf(ssl[m0 + wm * 128 + 16 * i + 4 * fq + e] * (1.f / DM) + EPS);
;         const int pos = 16 * i + 8 * (fq & 1) + 4 * (fq >> 1);
; #pragma unroll
;         for (int j = 0; j < 4; ++j) {
;           u32x2 v = {pk2(acc[i][j][0] * rs[0], acc[i][j][1] * rs[1]), pk2(acc[i][j][2] * rs[2], acc[i][j][3] * rs[3])};
;           *(u32x2*)(stg + (16 * j + fr) * VSTR + pos) = v;
;         }
;       }
;       u16* gdst = p.vt + ((size_t)(bb * NVH + vbase + wn) * 64) * SEQ + s0 + wm * 128;
; #pragma unroll
;       for (int t = 0; t < 16; ++t) {
;         const int c = lane + 64 * t, row = c >> 4, kc = c & 15;
;         const u32x4 v = *(const u32x4*)(stg + row * VSTR + kc * 8);
;         *(u32x4*)(gdst + (size_t)row * SEQ + kc * 8) = v;
;       }
	v_fmamk_f32 v20, v32, 0x3a800000, v188
	v_fmamk_f32 v21, v33, 0x3a800000, v188
	v_fmamk_f32 v24, v34, 0x3a800000, v188
	v_fmamk_f32 v25, v35, 0x3a800000, v188
	v_rsq_f32_e32 v20, v20
	v_rsq_f32_e32 v21, v21
	v_rsq_f32_e32 v24, v24
	v_rsq_f32_e32 v25, v25
	v_mul_f32_e32 v14, v14, v20
	v_mul_f32_e32 v15, v15, v21
	v_mul_f32_e32 v2, v2, v20
	v_mul_f32_e32 v3, v3, v21
	v_mul_f32_e32 v16, v16, v24
	v_mul_f32_e32 v17, v17, v25
	v_mul_f32_e32 v4, v4, v24
	v_mul_f32_e32 v5, v5, v25
	v_cvt_pk_bf16_f32 v14, v14, v15
	v_cvt_pk_bf16_f32 v15, v16, v17
	v_cvt_pk_bf16_f32 v2, v2, v3
	v_cvt_pk_bf16_f32 v3, v4, v5
	ds_write2_b64 v0, v[30:31], v[14:15] offset0:24 offset1:28
	ds_write2_b64 v102, v[22:23], v[2:3] offset0:88 offset1:92
	v_mul_f32_e32 v2, v10, v20
	v_mul_f32_e32 v3, v11, v21
	v_mul_f32_e32 v4, v12, v24
	v_mul_f32_e32 v5, v13, v25
	v_or_b32_e32 v0, s2, v131
	v_cvt_pk_bf16_f32 v2, v2, v3
	v_cvt_pk_bf16_f32 v3, v4, v5
	v_lshlrev_b32_e32 v0, 20, v0
	ds_write2_b64 v98, v[18:19], v[2:3] offset0:120 offset1:124
	v_lshl_add_u64 v[2:3], s[88:89], 0, v[0:1]
	v_lshl_add_u64 v[2:3], v[2:3], 0, s[4:5]
	v_ashrrev_i32_e32 v131, 31, v130
	v_mul_f32_e32 v6, v6, v20
	v_mul_f32_e32 v7, v7, v21
	v_mul_f32_e32 v8, v8, v24
	v_mul_f32_e32 v9, v9, v25
	v_lshl_add_u64 v[2:3], v[130:131], 1, v[2:3]
	v_and_b32_e32 v0, 0xf0, v136
	v_cvt_pk_bf16_f32 v6, v6, v7
	v_cvt_pk_bf16_f32 v7, v8, v9
	v_lshl_add_u64 v[132:133], v[2:3], 0, v[0:1]
	v_mul_u32_u24_e32 v2, 0x110, v134
	ds_write2_b64 v106, v[26:27], v[6:7] offset0:56 offset1:60
	v_add3_u32 v8, v135, v0, v2
	ds_read_b128 v[2:5], v8
	v_lshlrev_b32_e32 v0, 14, v134
	v_lshl_add_u64 v[6:7], v[132:133], 0, v[0:1]
	v_add_u32_e32 v140, 0x3fc0, v8
	s_waitcnt lgkmcnt(0)
	global_store_dwordx4 v[6:7], v[2:5], off sc1
	ds_read_b128 v[2:5], v8 offset:1088
	v_or_b32_e32 v6, 0x10000, v0
	v_mov_b32_e32 v7, v1
	v_lshl_add_u64 v[6:7], v[132:133], 0, v[6:7]
	s_waitcnt lgkmcnt(0)
	global_store_dwordx4 v[6:7], v[2:5], off sc1
	ds_read_b128 v[2:5], v8 offset:2176
	v_or_b32_e32 v6, 0x20000, v0
	v_mov_b32_e32 v7, v1
	v_lshl_add_u64 v[6:7], v[132:133], 0, v[6:7]
	s_waitcnt lgkmcnt(0)
	global_store_dwordx4 v[6:7], v[2:5], off sc1
	ds_read_b128 v[2:5], v8 offset:3264
	v_or_b32_e32 v6, 0x30000, v0
	v_mov_b32_e32 v7, v1
	v_lshl_add_u64 v[6:7], v[132:133], 0, v[6:7]
	s_waitcnt lgkmcnt(0)
	global_store_dwordx4 v[6:7], v[2:5], off sc1
	ds_read_b128 v[2:5], v8 offset:4352
	v_or_b32_e32 v6, 0x40000, v0
	v_mov_b32_e32 v7, v1
	v_lshl_add_u64 v[6:7], v[132:133], 0, v[6:7]
	s_waitcnt lgkmcnt(0)
	global_store_dwordx4 v[6:7], v[2:5], off sc1
	ds_read_b128 v[2:5], v8 offset:5440
	v_or_b32_e32 v6, 0x50000, v0
	v_mov_b32_e32 v7, v1
	v_lshl_add_u64 v[6:7], v[132:133], 0, v[6:7]
	s_waitcnt lgkmcnt(0)
	global_store_dwordx4 v[6:7], v[2:5], off sc1
	ds_read_b128 v[2:5], v8 offset:6528
	v_or_b32_e32 v6, 0x60000, v0
	v_mov_b32_e32 v7, v1
	v_lshl_add_u64 v[6:7], v[132:133], 0, v[6:7]
	s_waitcnt lgkmcnt(0)
	global_store_dwordx4 v[6:7], v[2:5], off sc1
	ds_read_b128 v[2:5], v8 offset:7616
	v_or_b32_e32 v6, 0x70000, v0
	v_mov_b32_e32 v7, v1
	v_lshl_add_u64 v[6:7], v[132:133], 0, v[6:7]
	s_waitcnt lgkmcnt(0)
	global_store_dwordx4 v[6:7], v[2:5], off sc1
	ds_read_b128 v[2:5], v8 offset:8704
	v_or_b32_e32 v6, 0x80000, v0
	v_mov_b32_e32 v7, v1
	v_lshl_add_u64 v[6:7], v[132:133], 0, v[6:7]
	s_waitcnt lgkmcnt(0)
	global_store_dwordx4 v[6:7], v[2:5], off sc1
	ds_read_b128 v[2:5], v8 offset:9792
	v_or_b32_e32 v6, 0x90000, v0
	v_mov_b32_e32 v7, v1
	v_lshl_add_u64 v[6:7], v[132:133], 0, v[6:7]
	s_waitcnt lgkmcnt(0)
	global_store_dwordx4 v[6:7], v[2:5], off sc1
	ds_read_b128 v[2:5], v8 offset:10880
	v_or_b32_e32 v6, 0xa0000, v0
	v_mov_b32_e32 v7, v1
	v_lshl_add_u64 v[6:7], v[132:133], 0, v[6:7]
	s_waitcnt lgkmcnt(0)
	global_store_dwordx4 v[6:7], v[2:5], off sc1
	ds_read_b128 v[2:5], v8 offset:11968
	v_or_b32_e32 v6, 0xb0000, v0
	v_mov_b32_e32 v7, v1
	v_lshl_add_u64 v[6:7], v[132:133], 0, v[6:7]
	s_waitcnt lgkmcnt(0)
	global_store_dwordx4 v[6:7], v[2:5], off sc1
	ds_read_b128 v[2:5], v8 offset:13056
	v_or_b32_e32 v6, 0xc0000, v0
	v_mov_b32_e32 v7, v1
	v_lshl_add_u64 v[6:7], v[132:133], 0, v[6:7]
	s_waitcnt lgkmcnt(0)
	global_store_dwordx4 v[6:7], v[2:5], off sc1
	ds_read_b128 v[2:5], v8 offset:14144
	v_or_b32_e32 v6, 0xd0000, v0
	v_mov_b32_e32 v7, v1
	v_lshl_add_u64 v[6:7], v[132:133], 0, v[6:7]
	v_or_b32_e32 v0, 0xe0000, v0
	s_waitcnt lgkmcnt(0)
	global_store_dwordx4 v[6:7], v[2:5], off sc1
	ds_read_b128 v[2:5], v8 offset:15232
	v_lshl_add_u64 v[6:7], v[132:133], 0, v[0:1]
	v_lshl_or_b32 v0, v134, 13, v194
	s_waitcnt lgkmcnt(0)
	global_store_dwordx4 v[6:7], v[2:5], off sc1
.LBB0_112:
	ds_read_b128 v[2:5], v140
	s_add_i32 s18, s18, s97
	v_lshl_add_u64 v[6:7], v[0:1], 1, v[132:133]
	s_cmpk_gt_i32 s18, 0xbf
	s_waitcnt lgkmcnt(0)
	global_store_dwordx4 v[6:7], v[2:5], off sc1
	s_cbranch_scc1 .Lgx_exit

; template <int EPI>
; DI void gemm_tile(const Params& p, int layer, int mt, int nt, u16* sm, int wv) {
;     ...
;     if (!vtile) {
;       const float qsc = (nt < 2) ? 0.17677669529663687f * LOG2E
;                         : ((nt >= 8 && nt < 12) || nt == 18 || nt == 19) ? 0.125f * LOG2E : 1.f;
; #pragma unroll
;       for (int i = 0; i < 8; ++i) {
;         const int m = m0 + wm * 128 + 16 * i + fr;
;         const float rs = __builtin_amdgcn_rsqf(ssl[m] * (1.f / DM) + EPS) * qsc;
;         u16* d = stg + (16 * i + fr) * LSTR + 4 * fq;
; #pragma unroll
;         for (int j = 0; j < 4; ++j) {
;           u32x2 v = {pk2(acc[i][j][0] * rs, acc[i][j][1] * rs), pk2(acc[i][j][2] * rs, acc[i][j][3] * rs)};
;           *(u32x2*)(d + 16 * j) = v;
;         }
;       }
.LBB0_124:
	s_waitcnt vmcnt(8)
	v_mbcnt_lo_u32_b32 v138, -1, 0
	v_mbcnt_hi_u32_b32 v138, -1, v138
	s_lshl_b32 s21, s21, 8
	v_add_u32_e32 v0, s33, v138
	v_bfe_u32 v130, v0, 6, 21
	s_waitcnt vmcnt(7)
	v_mul_u32_u24_e32 v135, 0x4800, v130
	v_and_b32_e32 v130, 0xffffff80, v0
	v_and_b32_e32 v137, 15, v138
	v_bfe_u32 v134, v138, 4, 2
	v_bfe_u32 v131, v0, 6, 1
	s_mov_b64 s[6:7], -1
	s_andn2_b64 vcc, exec, s[4:5]
	v_add_u32_e32 v139, s21, v130
	v_lshlrev_b32_e32 v136, 4, v138
	s_barrier
	s_cbranch_vccnz .LBB0_126
	v_or_b32_e32 v132, v139, v137
	v_ashrrev_i32_e32 v133, 31, v132
	v_lshl_add_u64 v[132:133], v[132:133], 2, s[0:1]
	global_load_dword v142, v[132:133], off
	global_load_dword v150, v[132:133], off offset:64
	global_load_dword v151, v[132:133], off offset:128
	global_load_dword v152, v[132:133], off offset:192
	global_load_dword v153, v[132:133], off offset:256
	global_load_dword v154, v[132:133], off offset:320
	global_load_dword v155, v[132:133], off offset:384
	global_load_dword v156, v[132:133], off offset:448
	s_and_b32 s4, s20, 0x7ffffffc
	s_cmp_eq_u32 s4, 8
	s_cselect_b64 s[4:5], -1, 0
	s_and_b32 s6, s18, -16
	s_cmpk_eq_i32 s6, 0x90
	s_cselect_b64 s[6:7], -1, 0
	s_or_b64 vcc, s[6:7], s[4:5]
	s_cmp_gt_i32 s20, 1
	v_cndmask_b32_e32 v0, 1.0, v191, vcc
	s_cselect_b64 vcc, -1, 0
	v_cndmask_b32_e32 v0, v192, v0, vcc
	s_waitcnt vmcnt(7)
	v_mul_u32_u24_e32 v143, 0x90, v137
	v_lshlrev_b32_e32 v141, 3, v134
	v_add3_u32 v141, v135, v141, v143
	v_and_b32_e32 v140, 63, v138
	s_mov_b64 s[6:7], 0
	s_waitcnt vmcnt(0)
	v_fmamk_f32 v142, v142, 0x3a800000, v188
	v_rsq_f32_e32 v142, v142
	s_nop 0
	v_mul_f32_e32 v142, v0, v142
	v_mul_f32_e32 v144, v126, v142
	v_mul_f32_e32 v145, v127, v142
	v_mul_f32_e32 v146, v128, v142
	v_mul_f32_e32 v147, v129, v142
	v_cvt_pk_bf16_f32 v144, v144, v145
	v_cvt_pk_bf16_f32 v145, v146, v147
	v_mul_f32_e32 v146, v122, v142
	v_mul_f32_e32 v147, v123, v142
	v_mul_f32_e32 v148, v124, v142
	v_mul_f32_e32 v149, v125, v142
	v_cvt_pk_bf16_f32 v146, v146, v147
	v_cvt_pk_bf16_f32 v147, v148, v149
	ds_write2_b64 v141, v[144:145], v[146:147] offset1:4
	v_mul_f32_e32 v144, v118, v142
	v_mul_f32_e32 v145, v119, v142
	v_mul_f32_e32 v146, v120, v142
	v_mul_f32_e32 v147, v121, v142
	v_cvt_pk_bf16_f32 v144, v144, v145
	v_cvt_pk_bf16_f32 v145, v146, v147
	v_mul_f32_e32 v146, v114, v142
	v_mul_f32_e32 v147, v115, v142
	v_mul_f32_e32 v143, v117, v142
	v_mul_f32_e32 v142, v116, v142
	v_cvt_pk_bf16_f32 v146, v146, v147
	v_cvt_pk_bf16_f32 v147, v142, v143
	v_mov_b32_e32 v142, v150
	ds_write2_b64 v141, v[144:145], v[146:147] offset0:8 offset1:12
	s_waitcnt vmcnt(0)
	v_fmamk_f32 v142, v142, 0x3a800000, v188
	v_rsq_f32_e32 v142, v142
	s_nop 0
	v_mul_f32_e32 v142, v0, v142
	v_mul_f32_e32 v144, v110, v142
	v_mul_f32_e32 v145, v111, v142
	v_mul_f32_e32 v146, v112, v142
	v_mul_f32_e32 v147, v113, v142
	v_cvt_pk_bf16_f32 v144, v144, v145
	v_cvt_pk_bf16_f32 v145, v146, v147
	v_mul_f32_e32 v146, v106, v142
	v_mul_f32_e32 v147, v107, v142
	v_mul_f32_e32 v148, v108, v142
	v_mul_f32_e32 v149, v109, v142
	v_cvt_pk_bf16_f32 v146, v146, v147
	v_cvt_pk_bf16_f32 v147, v148, v149
	v_add_u32_e32 v148, 0x800, v141
	ds_write2_b64 v148, v[144:145], v[146:147] offset0:32 offset1:36
	v_mul_f32_e32 v144, v102, v142
	v_mul_f32_e32 v145, v103, v142
	v_mul_f32_e32 v146, v104, v142
	v_mul_f32_e32 v147, v105, v142
	v_cvt_pk_bf16_f32 v144, v144, v145
	v_cvt_pk_bf16_f32 v145, v146, v147
	v_mul_f32_e32 v146, v98, v142
	v_mul_f32_e32 v147, v99, v142
	v_mul_f32_e32 v143, v101, v142
	v_mul_f32_e32 v142, v100, v142
	v_cvt_pk_bf16_f32 v146, v146, v147
	v_cvt_pk_bf16_f32 v147, v142, v143
	v_mov_b32_e32 v142, v151
	ds_write2_b64 v148, v[144:145], v[146:147] offset0:40 offset1:44
	s_waitcnt vmcnt(0)
	v_fmamk_f32 v142, v142, 0x3a800000, v188
	v_rsq_f32_e32 v142, v142
	s_nop 0
	v_mul_f32_e32 v142, v0, v142
	v_mul_f32_e32 v144, v94, v142
	v_mul_f32_e32 v145, v95, v142
	v_mul_f32_e32 v146, v96, v142
	v_mul_f32_e32 v147, v97, v142
	v_cvt_pk_bf16_f32 v144, v144, v145
	v_cvt_pk_bf16_f32 v145, v146, v147
	v_mul_f32_e32 v146, v90, v142
	v_mul_f32_e32 v147, v91, v142
	v_mul_f32_e32 v148, v92, v142
	v_mul_f32_e32 v149, v93, v142
	v_cvt_pk_bf16_f32 v146, v146, v147
	v_cvt_pk_bf16_f32 v147, v148, v149
	v_add_u32_e32 v148, 0x1000, v141
	ds_write2_b64 v148, v[144:145], v[146:147] offset0:64 offset1:68
	v_mul_f32_e32 v144, v86, v142
	v_mul_f32_e32 v145, v87, v142
	v_mul_f32_e32 v146, v88, v142
	v_mul_f32_e32 v147, v89, v142
	v_cvt_pk_bf16_f32 v144, v144, v145
	v_cvt_pk_bf16_f32 v145, v146, v147
	v_mul_f32_e32 v146, v82, v142
	v_mul_f32_e32 v147, v83, v142
	v_mul_f32_e32 v143, v85, v142
	v_mul_f32_e32 v142, v84, v142
	v_cvt_pk_bf16_f32 v146, v146, v147
	v_cvt_pk_bf16_f32 v147, v142, v143
	v_mov_b32_e32 v142, v152
	ds_write2_b64 v148, v[144:145], v[146:147] offset0:72 offset1:76
	s_waitcnt vmcnt(0)
	v_fmamk_f32 v142, v142, 0x3a800000, v188
	v_rsq_f32_e32 v142, v142
	s_nop 0
	v_mul_f32_e32 v142, v0, v142
	v_mul_f32_e32 v144, v78, v142
	v_mul_f32_e32 v145, v79, v142
	v_mul_f32_e32 v146, v80, v142
	v_mul_f32_e32 v147, v81, v142
	v_cvt_pk_bf16_f32 v144, v144, v145
	v_cvt_pk_bf16_f32 v145, v146, v147
	v_mul_f32_e32 v146, v74, v142
	v_mul_f32_e32 v147, v75, v142
	v_mul_f32_e32 v148, v76, v142
	v_mul_f32_e32 v149, v77, v142
	v_cvt_pk_bf16_f32 v146, v146, v147
	v_cvt_pk_bf16_f32 v147, v148, v149
	v_add_u32_e32 v148, 0x1800, v141
	ds_write2_b64 v148, v[144:145], v[146:147] offset0:96 offset1:100
	v_mul_f32_e32 v144, v70, v142
	v_mul_f32_e32 v145, v71, v142
	v_mul_f32_e32 v146, v72, v142
	v_mul_f32_e32 v147, v73, v142
	v_cvt_pk_bf16_f32 v144, v144, v145
	v_cvt_pk_bf16_f32 v145, v146, v147
	v_mul_f32_e32 v146, v66, v142
	v_mul_f32_e32 v147, v67, v142
	v_mul_f32_e32 v143, v69, v142
	v_mul_f32_e32 v142, v68, v142
	v_cvt_pk_bf16_f32 v146, v146, v147
	v_cvt_pk_bf16_f32 v147, v142, v143
	v_mov_b32_e32 v142, v153
	ds_write2_b64 v148, v[144:145], v[146:147] offset0:104 offset1:108
	s_waitcnt vmcnt(0)
; template <int EPI>
; DI void gemm_tile(const Params& p, int layer, int mt, int nt, u16* sm, int wv) {
;     ...
;       for (int i = 0; i < 8; ++i) {
;         const int m = m0 + wm * 128 + 16 * i + fr;
;         const float rs = __builtin_amdgcn_rsqf(ssl[m] * (1.f / DM) + EPS) * qsc;
;         u16* d = stg + (16 * i + fr) * LSTR + 4 * fq;
; #pragma unroll
;         for (int j = 0; j < 4; ++j) {
;           u32x2 v = {pk2(acc[i][j][0] * rs, acc[i][j][1] * rs), pk2(acc[i][j][2] * rs, acc[i][j][3] * rs)};
;           *(u32x2*)(d + 16 * j) = v;
;         }
;       }
;       u16* gdst = p.proj + (size_t)(m0 + wm * 128) * DIN + n0 + wn * 64;
; #pragma unroll
;       for (int t = 0; t < 16; ++t) {
;         const int c = lane + 64 * t, row = c >> 3, kc = c & 7;
;         const u32x4 v = *(const u32x4*)(stg + row * LSTR + kc * 8);
;         *(u32x4*)(gdst + (size_t)row * DIN + kc * 8) = v;
;       }
	v_fmamk_f32 v142, v142, 0x3a800000, v188
	v_rsq_f32_e32 v142, v142
	s_nop 0
	v_mul_f32_e32 v142, v0, v142
	v_mul_f32_e32 v144, v62, v142
	v_mul_f32_e32 v145, v63, v142
	v_mul_f32_e32 v146, v64, v142
	v_mul_f32_e32 v147, v65, v142
	v_cvt_pk_bf16_f32 v144, v144, v145
	v_cvt_pk_bf16_f32 v145, v146, v147
	v_mul_f32_e32 v146, v58, v142
	v_mul_f32_e32 v147, v59, v142
	v_mul_f32_e32 v148, v60, v142
	v_mul_f32_e32 v149, v61, v142
	v_cvt_pk_bf16_f32 v146, v146, v147
	v_cvt_pk_bf16_f32 v147, v148, v149
	v_add_u32_e32 v148, 0x2000, v141
	ds_write2_b64 v148, v[144:145], v[146:147] offset0:128 offset1:132
	v_mul_f32_e32 v144, v54, v142
	v_mul_f32_e32 v145, v55, v142
	v_mul_f32_e32 v146, v56, v142
	v_mul_f32_e32 v147, v57, v142
	v_cvt_pk_bf16_f32 v144, v144, v145
	v_cvt_pk_bf16_f32 v145, v146, v147
	v_mul_f32_e32 v146, v50, v142
	v_mul_f32_e32 v147, v51, v142
	v_mul_f32_e32 v143, v53, v142
	v_mul_f32_e32 v142, v52, v142
	v_cvt_pk_bf16_f32 v146, v146, v147
	v_cvt_pk_bf16_f32 v147, v142, v143
	v_mov_b32_e32 v142, v154
	ds_write2_b64 v148, v[144:145], v[146:147] offset0:136 offset1:140
	s_waitcnt vmcnt(0)
	v_fmamk_f32 v142, v142, 0x3a800000, v188
	v_rsq_f32_e32 v142, v142
	s_nop 0
	v_mul_f32_e32 v142, v0, v142
	v_mul_f32_e32 v144, v46, v142
	v_mul_f32_e32 v145, v47, v142
	v_mul_f32_e32 v146, v48, v142
	v_mul_f32_e32 v147, v49, v142
	v_cvt_pk_bf16_f32 v144, v144, v145
	v_cvt_pk_bf16_f32 v145, v146, v147
	v_mul_f32_e32 v146, v42, v142
	v_mul_f32_e32 v147, v43, v142
	v_mul_f32_e32 v148, v44, v142
	v_mul_f32_e32 v149, v45, v142
	v_cvt_pk_bf16_f32 v146, v146, v147
	v_cvt_pk_bf16_f32 v147, v148, v149
	v_add_u32_e32 v148, 0x2800, v141
	ds_write2_b64 v148, v[144:145], v[146:147] offset0:160 offset1:164
	v_mul_f32_e32 v144, v38, v142
	v_mul_f32_e32 v145, v39, v142
	v_mul_f32_e32 v146, v40, v142
	v_mul_f32_e32 v147, v41, v142
	v_cvt_pk_bf16_f32 v144, v144, v145
	v_cvt_pk_bf16_f32 v145, v146, v147
	v_mul_f32_e32 v146, v34, v142
	v_mul_f32_e32 v147, v35, v142
	v_mul_f32_e32 v143, v37, v142
	v_mul_f32_e32 v142, v36, v142
	v_cvt_pk_bf16_f32 v146, v146, v147
	v_cvt_pk_bf16_f32 v147, v142, v143
	v_mov_b32_e32 v142, v155
	ds_write2_b64 v148, v[144:145], v[146:147] offset0:168 offset1:172
	v_mov_b32_e32 v132, v156
	s_waitcnt vmcnt(1)
	v_fmamk_f32 v142, v142, 0x3a800000, v188
	v_rsq_f32_e32 v142, v142
	s_waitcnt vmcnt(0)
	v_fmamk_f32 v132, v132, 0x3a800000, v188
	v_rsq_f32_e32 v132, v132
	v_mul_f32_e32 v142, v0, v142
	v_mul_f32_e32 v144, v30, v142
	v_mul_f32_e32 v145, v31, v142
	v_mul_f32_e32 v146, v32, v142
	v_mul_f32_e32 v147, v33, v142
	v_cvt_pk_bf16_f32 v144, v144, v145
	v_cvt_pk_bf16_f32 v145, v146, v147
	v_mul_f32_e32 v146, v26, v142
	v_mul_f32_e32 v147, v27, v142
	v_mul_f32_e32 v148, v28, v142
	v_mul_f32_e32 v149, v29, v142
	v_cvt_pk_bf16_f32 v146, v146, v147
	v_cvt_pk_bf16_f32 v147, v148, v149
	v_add_u32_e32 v148, 0x3000, v141
	ds_write2_b64 v148, v[144:145], v[146:147] offset0:192 offset1:196
	v_mul_f32_e32 v144, v22, v142
	v_mul_f32_e32 v145, v23, v142
	v_mul_f32_e32 v146, v24, v142
	v_mul_f32_e32 v147, v25, v142
	v_cvt_pk_bf16_f32 v144, v144, v145
	v_cvt_pk_bf16_f32 v145, v146, v147
	v_mul_f32_e32 v146, v18, v142
	v_mul_f32_e32 v147, v19, v142
	v_mul_f32_e32 v143, v21, v142
	v_mul_f32_e32 v142, v20, v142
	v_mul_f32_e32 v0, v0, v132
	v_cvt_pk_bf16_f32 v146, v146, v147
	v_cvt_pk_bf16_f32 v147, v142, v143
	v_mul_f32_e32 v132, v14, v0
	v_mul_f32_e32 v133, v15, v0
	v_mul_f32_e32 v142, v16, v0
	v_mul_f32_e32 v143, v17, v0
	ds_write2_b64 v148, v[144:145], v[146:147] offset0:200 offset1:204
	v_cvt_pk_bf16_f32 v132, v132, v133
	v_cvt_pk_bf16_f32 v133, v142, v143
	v_mul_f32_e32 v142, v6, v0
	v_mul_f32_e32 v143, v7, v0
	v_mul_f32_e32 v144, v8, v0
	v_mul_f32_e32 v145, v9, v0
	v_cvt_pk_bf16_f32 v142, v142, v143
	v_cvt_pk_bf16_f32 v143, v144, v145
	v_add_u32_e32 v141, 0x3800, v141
	ds_write2_b64 v141, v[132:133], v[142:143] offset0:224 offset1:228
	v_mul_f32_e32 v132, v2, v0
	v_mul_f32_e32 v133, v3, v0
	v_mul_f32_e32 v142, v4, v0
	v_mul_f32_e32 v143, v5, v0
	v_cvt_pk_bf16_f32 v132, v132, v133
	v_cvt_pk_bf16_f32 v133, v142, v143
	v_mul_f32_e32 v142, v10, v0
	v_mul_f32_e32 v143, v11, v0
	v_mul_f32_e32 v144, v12, v0
	v_mul_f32_e32 v145, v13, v0
	v_cvt_pk_bf16_f32 v142, v142, v143
	v_cvt_pk_bf16_f32 v143, v144, v145
	ds_write2_b64 v141, v[132:133], v[142:143] offset0:232 offset1:236
	v_mov_b64_e32 v[132:133], s[62:63]
	v_mad_i64_i32 v[132:133], s[4:5], v139, s8, v[132:133]
	v_lshl_add_u64 v[132:133], s[2:3], 1, v[132:133]
	v_lshlrev_b32_e32 v0, 7, v131
	v_lshrrev_b32_e32 v148, 3, v140
	v_lshl_add_u64 v[132:133], v[132:133], 0, v[0:1]
	v_and_b32_e32 v0, 0x70, v136
	v_mul_u32_u24_e32 v140, 0x90, v148
	v_add3_u32 v149, v135, v0, v140
	ds_read_b128 v[140:143], v149
	v_lshl_add_u64 v[132:133], v[132:133], 0, v[0:1]
	v_mul_u32_u24_e32 v0, 0xd00, v148
	v_lshlrev_b32_e32 v0, 1, v0
	v_lshl_add_u64 v[144:145], v[132:133], 0, v[0:1]
	s_cmp_eq_u32 s40, 2
	s_cbranch_scc1 .Lepi_hi_skip
	s_waitcnt lgkmcnt(0)
	global_store_dwordx4 v[144:145], v[140:143], off sc1
	ds_read_b128 v[140:143], v149 offset:1152
	s_mov_b32 s2, 0xd000
	v_add_co_u32_e32 v146, vcc, s2, v144
	s_mov_b32 s2, 0x1a000
	s_nop 0
	v_addc_co_u32_e32 v147, vcc, 0, v145, vcc
	s_waitcnt lgkmcnt(0)
	global_store_dwordx4 v[146:147], v[140:143], off sc1
	ds_read_b128 v[140:143], v149 offset:2304
	v_add_co_u32_e32 v146, vcc, s2, v144
	s_mov_b32 s2, 0x27000
	s_nop 0
	v_addc_co_u32_e32 v147, vcc, 0, v145, vcc
	s_waitcnt lgkmcnt(0)
	global_store_dwordx4 v[146:147], v[140:143], off sc1
	ds_read_b128 v[140:143], v149 offset:3456
	v_add_co_u32_e32 v144, vcc, s2, v144
	s_movk_i32 s2, 0xd00
	s_nop 0
	v_addc_co_u32_e32 v145, vcc, 0, v145, vcc
	s_waitcnt lgkmcnt(0)
	global_store_dwordx4 v[144:145], v[140:143], off sc1
	ds_read_b128 v[140:143], v149 offset:4608
	v_add_u32_e32 v144, 0x34000, v0
	v_mov_b32_e32 v145, v1
	v_lshl_add_u64 v[144:145], v[132:133], 0, v[144:145]
	s_waitcnt lgkmcnt(0)
	global_store_dwordx4 v[144:145], v[140:143], off sc1
	ds_read_b128 v[140:143], v149 offset:5760
	v_add_u32_e32 v144, 0x41000, v0
	v_mov_b32_e32 v145, v1
	v_lshl_add_u64 v[144:145], v[132:133], 0, v[144:145]
	s_waitcnt lgkmcnt(0)
	global_store_dwordx4 v[144:145], v[140:143], off sc1
	ds_read_b128 v[140:143], v149 offset:6912
	v_add_u32_e32 v144, 0x4e000, v0
	v_mov_b32_e32 v145, v1
	v_lshl_add_u64 v[144:145], v[132:133], 0, v[144:145]
	s_waitcnt lgkmcnt(0)
	global_store_dwordx4 v[144:145], v[140:143], off sc1
	ds_read_b128 v[140:143], v149 offset:8064
	v_add_u32_e32 v144, 0x5b000, v0
	v_mov_b32_e32 v145, v1
	v_lshl_add_u64 v[144:145], v[132:133], 0, v[144:145]
	s_waitcnt lgkmcnt(0)
	global_store_dwordx4 v[144:145], v[140:143], off sc1
	s_cmp_eq_u32 s40, 1
	s_cbranch_scc1 .Lgx_halfdone
	s_branch .Lepi_t8

; template <int EPI>
; DI void gemm_tile(const Params& p, int layer, int mt, int nt, u16* sm, int wv) {
;     ...
; #pragma unroll
;       for (int t = 0; t < 16; ++t) {
;         const int c = lane + 64 * t, row = c >> 3, kc = c & 7;
;         const u32x4 v = *(const u32x4*)(stg + row * LSTR + kc * 8);
;         *(u32x4*)(gdst + (size_t)row * DIN + kc * 8) = v;
;       }
.Lepi_t8:
	ds_read_b128 v[140:143], v149 offset:9216
	v_add_u32_e32 v144, 0x68000, v0
	v_mov_b32_e32 v145, v1
	v_lshl_add_u64 v[144:145], v[132:133], 0, v[144:145]
	s_waitcnt lgkmcnt(0)
	global_store_dwordx4 v[144:145], v[140:143], off sc1
	ds_read_b128 v[140:143], v149 offset:10368
	v_add_u32_e32 v144, 0x75000, v0
	v_mov_b32_e32 v145, v1
	v_lshl_add_u64 v[144:145], v[132:133], 0, v[144:145]
	s_waitcnt lgkmcnt(0)
	global_store_dwordx4 v[144:145], v[140:143], off sc1
	ds_read_b128 v[140:143], v149 offset:11520
	v_add_u32_e32 v144, 0x82000, v0
	v_mov_b32_e32 v145, v1
	v_lshl_add_u64 v[144:145], v[132:133], 0, v[144:145]
	s_waitcnt lgkmcnt(0)
	global_store_dwordx4 v[144:145], v[140:143], off sc1
	ds_read_b128 v[140:143], v149 offset:12672
	v_add_u32_e32 v144, 0x8f000, v0
	v_mov_b32_e32 v145, v1
	v_lshl_add_u64 v[144:145], v[132:133], 0, v[144:145]
	s_waitcnt lgkmcnt(0)
	global_store_dwordx4 v[144:145], v[140:143], off sc1
	ds_read_b128 v[140:143], v149 offset:13824
	v_add_u32_e32 v144, 0x9c000, v0
	v_mov_b32_e32 v145, v1
	v_lshl_add_u64 v[144:145], v[132:133], 0, v[144:145]
	s_waitcnt lgkmcnt(0)
	global_store_dwordx4 v[144:145], v[140:143], off sc1
	ds_read_b128 v[140:143], v149 offset:14976
	v_add_u32_e32 v144, 0xa9000, v0
	v_mov_b32_e32 v145, v1
	v_lshl_add_u64 v[144:145], v[132:133], 0, v[144:145]
	v_add_u32_e32 v0, 0xb6000, v0
	s_waitcnt lgkmcnt(0)
	global_store_dwordx4 v[144:145], v[140:143], off sc1
	ds_read_b128 v[140:143], v149 offset:16128
	v_lshl_add_u64 v[144:145], v[132:133], 0, v[0:1]
	v_mad_u32_u24 v0, v148, s2, v193
	s_waitcnt lgkmcnt(0)
	global_store_dwordx4 v[144:145], v[140:143], off sc1
	s_nop 1
	v_add_u32_e32 v140, 0x4380, v149

; DI float bflo(unsigned v) { return __uint_as_float(v << 16); }
; DI float bfhi(unsigned v) { return __uint_as_float(v & 0xffff0000u); }
; DI float silu(float g) { return g * __builtin_amdgcn_rcpf(1.f + ex2(-g * LOG2E)); }
; DI void store_y(const f32x16& oa, const f32x16& ob, float mult, const float* sg, const u32x2 (&gv)[8], u16* yrow0, float* stg,
;                 int lane, int r, int h) {
;     ...
;   const int kc = lane & 15;
;   f32x4 sv = {1.f, 1.f, 1.f, 1.f};
;   if (sg) sv = *(const f32x4*)(sg + kc * 4);
; #pragma unroll
;   for (int t = 0; t < 8; ++t) {
;     const int row = (lane >> 4) + 4 * t;
;     const f32x4 v = *(const f32x4*)(stg + row * 68 + kc * 4);
;     float y0 = v[0] * sv[0] * silu(bflo(gv[t][0]));
;     float y1 = v[1] * sv[1] * silu(bfhi(gv[t][0]));
;     float y2 = v[2] * sv[2] * silu(bflo(gv[t][1]));
;     float y3 = v[3] * sv[3] * silu(bfhi(gv[t][1]));
;     u32x2 yo = {pk2(y0, y1), pk2(y2, y3)};
;     *(u32x2*)(yrow0 + (size_t)row * DM + kc * 4) = yo;
;   }
.LBB0_194:
	v_readlane_b32 s4, v250, 9
	v_ashrrev_i32_e32 v159, 31, v158
	v_readlane_b32 s5, v250, 10
	v_lshlrev_b32_e32 v0, 1, v0
	s_waitcnt vmcnt(7)
	v_lshlrev_b32_e32 v10, 16, v84
	v_lshl_add_u64 v[2:3], v[158:159], 0, s[4:5]
	v_readlane_b32 s4, v250, 13
	v_lshlrev_b64 v[2:3], 11, v[2:3]
	v_readlane_b32 s5, v250, 14
	v_and_b32_e32 v11, 0xffff0000, v84
	s_nop 0
	v_lshl_add_u64 v[2:3], s[4:5], 0, v[2:3]
	v_lshl_add_u64 v[2:3], v[2:3], 0, v[0:1]
	v_mul_u32_u24_e32 v0, 0x110, v170
	v_add3_u32 v4, v46, v4, v0
	v_mul_f32_e32 v0, 0xbfb8aa3b, v10
	v_exp_f32_e32 v0, v0
	ds_read_b128 v[6:9], v4 offset:36864
	v_add_f32_e32 v0, 1.0, v0
	v_rcp_f32_e32 v12, v0
	v_mul_f32_e32 v0, 0xbfb8aa3b, v11
	v_exp_f32_e32 v0, v0
	s_waitcnt vmcnt(0) lgkmcnt(0)
	v_pk_mul_f32 v[6:7], v[66:67], v[6:7]
	v_pk_mul_f32 v[8:9], v[68:69], v[8:9]
	v_add_f32_e32 v0, 1.0, v0
	v_rcp_f32_e32 v13, v0
	s_nop 0
	v_pk_mul_f32 v[10:11], v[12:13], v[10:11]
	s_nop 0
	v_pk_mul_f32 v[6:7], v[10:11], v[6:7]
	v_lshlrev_b32_e32 v10, 16, v85
	v_mul_f32_e32 v0, 0xbfb8aa3b, v10
	v_exp_f32_e32 v0, v0
	v_and_b32_e32 v11, 0xffff0000, v85
	v_cvt_pk_bf16_f32 v6, v6, v7
	v_add_f32_e32 v0, 1.0, v0
	v_rcp_f32_e32 v12, v0
	v_mul_f32_e32 v0, 0xbfb8aa3b, v11
	v_exp_f32_e32 v0, v0
	s_nop 0
	v_add_f32_e32 v0, 1.0, v0
	v_rcp_f32_e32 v13, v0
	v_lshlrev_b32_e32 v0, 11, v170
	v_pk_mul_f32 v[10:11], v[12:13], v[10:11]
	s_nop 0
	v_pk_mul_f32 v[8:9], v[10:11], v[8:9]
	v_lshlrev_b32_e32 v10, 16, v82
	v_mul_f32_e32 v5, 0xbfb8aa3b, v10
	v_exp_f32_e32 v5, v5
	v_and_b32_e32 v11, 0xffff0000, v82
	v_cvt_pk_bf16_f32 v7, v8, v9
	v_lshl_add_u64 v[8:9], v[2:3], 0, v[0:1]
	v_add_f32_e32 v5, 1.0, v5
	v_rcp_f32_e32 v12, v5
	v_mul_f32_e32 v5, 0xbfb8aa3b, v11
	v_exp_f32_e32 v5, v5
	global_store_dwordx2 v[8:9], v[6:7], off sc1
	ds_read_b128 v[6:9], v4 offset:37952
	v_add_f32_e32 v5, 1.0, v5
	v_rcp_f32_e32 v13, v5
	s_waitcnt lgkmcnt(0)
	v_pk_mul_f32 v[6:7], v[66:67], v[6:7]
	v_pk_mul_f32 v[8:9], v[68:69], v[8:9]
	v_pk_mul_f32 v[10:11], v[12:13], v[10:11]
	s_nop 0
	v_pk_mul_f32 v[6:7], v[10:11], v[6:7]
	v_lshlrev_b32_e32 v10, 16, v83
	v_mul_f32_e32 v5, 0xbfb8aa3b, v10
	v_exp_f32_e32 v5, v5
	v_and_b32_e32 v11, 0xffff0000, v83
	v_cvt_pk_bf16_f32 v6, v6, v7
	v_add_f32_e32 v5, 1.0, v5
	v_rcp_f32_e32 v12, v5
	v_mul_f32_e32 v5, 0xbfb8aa3b, v11
	v_exp_f32_e32 v5, v5
	s_nop 0
	v_add_f32_e32 v5, 1.0, v5
	v_rcp_f32_e32 v13, v5
	s_nop 0
	v_pk_mul_f32 v[10:11], v[12:13], v[10:11]
	s_nop 0
	v_pk_mul_f32 v[8:9], v[10:11], v[8:9]
	v_lshlrev_b32_e32 v10, 16, v80
	v_mul_f32_e32 v5, 0xbfb8aa3b, v10
	v_exp_f32_e32 v5, v5
	v_and_b32_e32 v11, 0xffff0000, v80
	v_cvt_pk_bf16_f32 v7, v8, v9
	v_or_b32_e32 v8, 0x2000, v0
	v_add_f32_e32 v5, 1.0, v5
	v_rcp_f32_e32 v12, v5
	v_mul_f32_e32 v5, 0xbfb8aa3b, v11
	v_exp_f32_e32 v5, v5
	v_mov_b32_e32 v9, v1
	v_lshl_add_u64 v[8:9], v[2:3], 0, v[8:9]
	global_store_dwordx2 v[8:9], v[6:7], off sc1
	ds_read_b128 v[6:9], v4 offset:39040
	v_add_f32_e32 v5, 1.0, v5
	v_rcp_f32_e32 v13, v5
	s_waitcnt lgkmcnt(0)
	v_pk_mul_f32 v[6:7], v[66:67], v[6:7]
	v_pk_mul_f32 v[10:11], v[12:13], v[10:11]
	v_pk_mul_f32 v[8:9], v[68:69], v[8:9]
	v_pk_mul_f32 v[6:7], v[10:11], v[6:7]
	v_lshlrev_b32_e32 v10, 16, v81
	v_mul_f32_e32 v5, 0xbfb8aa3b, v10
	v_exp_f32_e32 v5, v5
	v_and_b32_e32 v11, 0xffff0000, v81
	v_cvt_pk_bf16_f32 v6, v6, v7
	v_add_f32_e32 v5, 1.0, v5
	v_rcp_f32_e32 v12, v5
	v_mul_f32_e32 v5, 0xbfb8aa3b, v11
	v_exp_f32_e32 v5, v5
	s_nop 0
	v_add_f32_e32 v5, 1.0, v5
	v_rcp_f32_e32 v13, v5
	s_nop 0
	v_pk_mul_f32 v[10:11], v[12:13], v[10:11]
	s_nop 0
	v_pk_mul_f32 v[8:9], v[10:11], v[8:9]
	v_lshlrev_b32_e32 v10, 16, v78
	v_mul_f32_e32 v5, 0xbfb8aa3b, v10
	v_exp_f32_e32 v5, v5
	v_and_b32_e32 v11, 0xffff0000, v78
	v_cvt_pk_bf16_f32 v7, v8, v9
	v_or_b32_e32 v8, 0x4000, v0
	v_add_f32_e32 v5, 1.0, v5
	v_rcp_f32_e32 v12, v5
	v_mul_f32_e32 v5, 0xbfb8aa3b, v11
	v_exp_f32_e32 v5, v5
	v_mov_b32_e32 v9, v1
	v_lshl_add_u64 v[8:9], v[2:3], 0, v[8:9]
	global_store_dwordx2 v[8:9], v[6:7], off sc1
	ds_read_b128 v[6:9], v4 offset:40128
	v_add_f32_e32 v5, 1.0, v5
	v_rcp_f32_e32 v13, v5
	s_waitcnt lgkmcnt(0)
; DI float bflo(unsigned v) { return __uint_as_float(v << 16); }
; DI float bfhi(unsigned v) { return __uint_as_float(v & 0xffff0000u); }
; DI float silu(float g) { return g * __builtin_amdgcn_rcpf(1.f + ex2(-g * LOG2E)); }
; DI void store_y(const f32x16& oa, const f32x16& ob, float mult, const float* sg, const u32x2 (&gv)[8], u16* yrow0, float* stg,
;                 int lane, int r, int h) {
;     ...
;   for (int t = 0; t < 8; ++t) {
;     const int row = (lane >> 4) + 4 * t;
;     const f32x4 v = *(const f32x4*)(stg + row * 68 + kc * 4);
;     float y0 = v[0] * sv[0] * silu(bflo(gv[t][0]));
;     float y1 = v[1] * sv[1] * silu(bfhi(gv[t][0]));
;     float y2 = v[2] * sv[2] * silu(bflo(gv[t][1]));
;     float y3 = v[3] * sv[3] * silu(bfhi(gv[t][1]));
;     u32x2 yo = {pk2(y0, y1), pk2(y2, y3)};
;     *(u32x2*)(yrow0 + (size_t)row * DM + kc * 4) = yo;
;   }
	v_pk_mul_f32 v[6:7], v[66:67], v[6:7]
	v_pk_mul_f32 v[10:11], v[12:13], v[10:11]
	v_pk_mul_f32 v[8:9], v[68:69], v[8:9]
	v_pk_mul_f32 v[6:7], v[10:11], v[6:7]
	v_lshlrev_b32_e32 v10, 16, v79
	v_mul_f32_e32 v5, 0xbfb8aa3b, v10
	v_exp_f32_e32 v5, v5
	v_and_b32_e32 v11, 0xffff0000, v79
	v_cvt_pk_bf16_f32 v6, v6, v7
	v_add_f32_e32 v5, 1.0, v5
	v_rcp_f32_e32 v12, v5
	v_mul_f32_e32 v5, 0xbfb8aa3b, v11
	v_exp_f32_e32 v5, v5
	s_nop 0
	v_add_f32_e32 v5, 1.0, v5
	v_rcp_f32_e32 v13, v5
	s_nop 0
	v_pk_mul_f32 v[10:11], v[12:13], v[10:11]
	s_nop 0
	v_pk_mul_f32 v[8:9], v[10:11], v[8:9]
	v_lshlrev_b32_e32 v10, 16, v76
	v_mul_f32_e32 v5, 0xbfb8aa3b, v10
	v_exp_f32_e32 v5, v5
	v_and_b32_e32 v11, 0xffff0000, v76
	v_cvt_pk_bf16_f32 v7, v8, v9
	v_or_b32_e32 v8, 0x6000, v0
	v_add_f32_e32 v5, 1.0, v5
	v_rcp_f32_e32 v12, v5
	v_mul_f32_e32 v5, 0xbfb8aa3b, v11
	v_exp_f32_e32 v5, v5
	v_mov_b32_e32 v9, v1
	v_lshl_add_u64 v[8:9], v[2:3], 0, v[8:9]
	global_store_dwordx2 v[8:9], v[6:7], off sc1
	ds_read_b128 v[6:9], v4 offset:41216
	v_add_f32_e32 v5, 1.0, v5
	v_rcp_f32_e32 v13, v5
	s_waitcnt lgkmcnt(0)
	v_pk_mul_f32 v[6:7], v[66:67], v[6:7]
	v_pk_mul_f32 v[10:11], v[12:13], v[10:11]
	v_pk_mul_f32 v[8:9], v[68:69], v[8:9]
	v_pk_mul_f32 v[6:7], v[10:11], v[6:7]
	v_lshlrev_b32_e32 v10, 16, v77
	v_mul_f32_e32 v5, 0xbfb8aa3b, v10
	v_exp_f32_e32 v5, v5
	v_and_b32_e32 v11, 0xffff0000, v77
	v_cvt_pk_bf16_f32 v6, v6, v7
	v_add_f32_e32 v5, 1.0, v5
	v_rcp_f32_e32 v12, v5
	v_mul_f32_e32 v5, 0xbfb8aa3b, v11
	v_exp_f32_e32 v5, v5
	s_nop 0
	v_add_f32_e32 v5, 1.0, v5
	v_rcp_f32_e32 v13, v5
	s_nop 0
	v_pk_mul_f32 v[10:11], v[12:13], v[10:11]
	s_nop 0
	v_pk_mul_f32 v[8:9], v[10:11], v[8:9]
	v_lshlrev_b32_e32 v10, 16, v74
	v_mul_f32_e32 v5, 0xbfb8aa3b, v10
	v_exp_f32_e32 v5, v5
	v_and_b32_e32 v11, 0xffff0000, v74
	v_cvt_pk_bf16_f32 v7, v8, v9
	v_or_b32_e32 v8, 0x8000, v0
	v_add_f32_e32 v5, 1.0, v5
	v_rcp_f32_e32 v12, v5
	v_mul_f32_e32 v5, 0xbfb8aa3b, v11
	v_exp_f32_e32 v5, v5
	v_mov_b32_e32 v9, v1
	v_lshl_add_u64 v[8:9], v[2:3], 0, v[8:9]
	global_store_dwordx2 v[8:9], v[6:7], off sc1
	ds_read_b128 v[6:9], v4 offset:42304
	v_add_f32_e32 v5, 1.0, v5
	v_rcp_f32_e32 v13, v5
	s_waitcnt lgkmcnt(0)
	v_pk_mul_f32 v[6:7], v[66:67], v[6:7]
	v_pk_mul_f32 v[10:11], v[12:13], v[10:11]
	v_pk_mul_f32 v[8:9], v[68:69], v[8:9]
	v_pk_mul_f32 v[6:7], v[10:11], v[6:7]
	v_lshlrev_b32_e32 v10, 16, v75
	v_mul_f32_e32 v5, 0xbfb8aa3b, v10
	v_exp_f32_e32 v5, v5
	v_and_b32_e32 v11, 0xffff0000, v75
	v_cvt_pk_bf16_f32 v6, v6, v7
	v_add_f32_e32 v5, 1.0, v5
	v_rcp_f32_e32 v12, v5
	v_mul_f32_e32 v5, 0xbfb8aa3b, v11
	v_exp_f32_e32 v5, v5
	s_nop 0
	v_add_f32_e32 v5, 1.0, v5
	v_rcp_f32_e32 v13, v5
	s_nop 0
	v_pk_mul_f32 v[10:11], v[12:13], v[10:11]
	s_nop 0
	v_pk_mul_f32 v[8:9], v[10:11], v[8:9]
	v_lshlrev_b32_e32 v10, 16, v72
	v_mul_f32_e32 v5, 0xbfb8aa3b, v10
	v_exp_f32_e32 v5, v5
	v_and_b32_e32 v11, 0xffff0000, v72
	v_cvt_pk_bf16_f32 v7, v8, v9
	v_or_b32_e32 v8, 0xa000, v0
	v_add_f32_e32 v5, 1.0, v5
	v_rcp_f32_e32 v12, v5
	v_mul_f32_e32 v5, 0xbfb8aa3b, v11
	v_exp_f32_e32 v5, v5
	v_mov_b32_e32 v9, v1
	v_lshl_add_u64 v[8:9], v[2:3], 0, v[8:9]
	global_store_dwordx2 v[8:9], v[6:7], off sc1
	ds_read_b128 v[6:9], v4 offset:43392
	v_add_f32_e32 v5, 1.0, v5
	v_rcp_f32_e32 v13, v5
	s_waitcnt lgkmcnt(0)
	v_pk_mul_f32 v[6:7], v[66:67], v[6:7]
	v_pk_mul_f32 v[10:11], v[12:13], v[10:11]
	v_pk_mul_f32 v[8:9], v[68:69], v[8:9]
	v_pk_mul_f32 v[6:7], v[10:11], v[6:7]
	v_lshlrev_b32_e32 v10, 16, v73
	v_mul_f32_e32 v5, 0xbfb8aa3b, v10
	v_exp_f32_e32 v5, v5
	v_and_b32_e32 v11, 0xffff0000, v73
	v_cvt_pk_bf16_f32 v6, v6, v7
	v_add_f32_e32 v5, 1.0, v5
	v_rcp_f32_e32 v12, v5
	v_mul_f32_e32 v5, 0xbfb8aa3b, v11
	v_exp_f32_e32 v5, v5
	s_nop 0
	v_add_f32_e32 v5, 1.0, v5
	v_rcp_f32_e32 v13, v5
	s_nop 0
	v_pk_mul_f32 v[10:11], v[12:13], v[10:11]
	s_nop 0
	v_pk_mul_f32 v[8:9], v[10:11], v[8:9]
	s_nop 0
	v_cvt_pk_bf16_f32 v7, v8, v9
	v_or_b32_e32 v8, 0xc000, v0
	v_mov_b32_e32 v9, v1
	v_lshl_add_u64 v[8:9], v[2:3], 0, v[8:9]
	global_store_dwordx2 v[8:9], v[6:7], off sc1
	v_lshlrev_b32_e32 v8, 16, v70
	v_and_b32_e32 v9, 0xffff0000, v70
	v_mul_f32_e32 v10, 0xbfb8aa3b, v8
	v_mul_f32_e32 v11, 0xbfb8aa3b, v9
	v_exp_f32_e32 v10, v10
	v_exp_f32_e32 v11, v11
	ds_read_b128 v[4:7], v4 offset:44480
	v_or_b32_e32 v0, 0xe000, v0
	v_add_f32_e32 v10, 1.0, v10
	v_add_f32_e32 v11, 1.0, v11
	v_rcp_f32_e32 v10, v10
	v_rcp_f32_e32 v11, v11
	s_waitcnt lgkmcnt(0)
	v_pk_mul_f32 v[4:5], v[66:67], v[4:5]
	v_pk_mul_f32 v[6:7], v[68:69], v[6:7]
	v_lshl_add_u64 v[2:3], v[2:3], 0, v[0:1]
	v_pk_mul_f32 v[8:9], v[10:11], v[8:9]
	s_nop 0
	v_pk_mul_f32 v[4:5], v[8:9], v[4:5]
	v_lshlrev_b32_e32 v8, 16, v71
	v_and_b32_e32 v9, 0xffff0000, v71
	v_mul_f32_e32 v10, 0xbfb8aa3b, v8
	v_mul_f32_e32 v11, 0xbfb8aa3b, v9
	v_exp_f32_e32 v10, v10
	v_exp_f32_e32 v11, v11
	v_cvt_pk_bf16_f32 v4, v4, v5
	v_add_f32_e32 v10, 1.0, v10
	v_add_f32_e32 v11, 1.0, v11
	v_rcp_f32_e32 v10, v10
	v_rcp_f32_e32 v11, v11
	s_nop 0
	v_pk_mul_f32 v[8:9], v[10:11], v[8:9]
	s_nop 0
	v_pk_mul_f32 v[6:7], v[8:9], v[6:7]
	s_nop 0
	v_cvt_pk_bf16_f32 v5, v6, v7
	global_store_dwordx2 v[2:3], v[4:5], off sc1

; DI float bflo(unsigned v) { return __uint_as_float(v << 16); }
; DI float bfhi(unsigned v) { return __uint_as_float(v & 0xffff0000u); }
; DI float silu(float g) { return g * __builtin_amdgcn_rcpf(1.f + ex2(-g * LOG2E)); }
; DI void store_y(const f32x16& oa, const f32x16& ob, float mult, const float* sg, const u32x2 (&gv)[8], u16* yrow0, float* stg,
;                 int lane, int r, int h) {
; #pragma unroll
;   for (int dt = 0; dt < 2; ++dt)
; #pragma unroll
;     for (int g = 0; g < 4; ++g) {
;       f32x4 v;
;       v[0] = (dt ? ob[4 * g] : oa[4 * g]) * mult; v[1] = (dt ? ob[4 * g + 1] : oa[4 * g + 1]) * mult;
;       v[2] = (dt ? ob[4 * g + 2] : oa[4 * g + 2]) * mult; v[3] = (dt ? ob[4 * g + 3] : oa[4 * g + 3]) * mult;
;       *(f32x4*)(stg + r * 68 + 32 * dt + 8 * g + 4 * h) = v;
;     }
;   const int kc = lane & 15;
;   f32x4 sv = {1.f, 1.f, 1.f, 1.f};
;   if (sg) sv = *(const f32x4*)(sg + kc * 4);
; #pragma unroll
;   for (int t = 0; t < 8; ++t) {
;     const int row = (lane >> 4) + 4 * t;
;     const f32x4 v = *(const f32x4*)(stg + row * 68 + kc * 4);
;     float y0 = v[0] * sv[0] * silu(bflo(gv[t][0]));
;     float y1 = v[1] * sv[1] * silu(bfhi(gv[t][0]));
;     float y2 = v[2] * sv[2] * silu(bflo(gv[t][1]));
;     float y3 = v[3] * sv[3] * silu(bfhi(gv[t][1]));
;     u32x2 yo = {pk2(y0, y1), pk2(y2, y3)};
;     *(u32x2*)(yrow0 + (size_t)row * DM + kc * 4) = yo;
;   }
.LBB0_246:
	s_or_b64 exec, exec, s[0:1]
	v_readlane_b32 s0, v250, 9
	v_ashrrev_i32_e32 v149, 31, v148
	v_readlane_b32 s1, v250, 10
	s_waitcnt vmcnt(2)
	v_mul_u32_u24_e32 v4, 0x110, v169
	v_lshlrev_b32_e32 v8, 16, v150
	v_lshl_add_u64 v[2:3], v[148:149], 0, s[0:1]
	v_readlane_b32 s0, v250, 13
	v_lshlrev_b64 v[2:3], 11, v[2:3]
	v_readlane_b32 s1, v250, 14
	s_waitcnt lgkmcnt(0)
	s_barrier
	v_lshl_add_u64 v[2:3], s[0:1], 0, v[2:3]
	s_movk_i32 s0, 0x2200
	v_mul_lo_u32 v0, v168, s0
	v_add3_u32 v4, v0, v4, v152
	v_lshl_or_b32 v0, v170, 2, v0
	s_movk_i32 s0, 0x110
	ds_write_b128 v4, v[32:35] offset:36864
	ds_write_b128 v4, v[36:39] offset:36896
	ds_write_b128 v4, v[40:43] offset:36928
	ds_write_b128 v4, v[44:47] offset:36960
	ds_write_b128 v4, v[16:19] offset:36992
	ds_write_b128 v4, v[20:23] offset:37024
	ds_write_b128 v4, v[24:27] offset:37056
	ds_write_b128 v4, v[28:31] offset:37088
	v_mad_u32_u24 v20, v153, s0, v0
	v_and_b32_e32 v9, 0xffff0000, v150
	v_mul_f32_e32 v0, 0xbfb8aa3b, v8
	v_exp_f32_e32 v0, v0
	v_mul_f32_e32 v4, 0xbfb8aa3b, v9
	v_exp_f32_e32 v11, v4
	v_lshlrev_b32_e32 v12, 16, v151
	v_add_f32_e32 v0, 1.0, v0
	v_rcp_f32_e32 v10, v0
	v_add_f32_e32 v0, 1.0, v11
	v_and_b32_e32 v13, 0xffff0000, v151
	v_mul_f32_e32 v11, 0xbfb8aa3b, v12
	v_exp_f32_e32 v14, v11
	v_mul_f32_e32 v11, 0xbfb8aa3b, v13
	v_exp_f32_e32 v15, v11
	v_rcp_f32_e32 v11, v0
	v_add_f32_e32 v0, 1.0, v14
	v_rcp_f32_e32 v14, v0
	v_add_f32_e32 v0, 1.0, v15
	ds_read_b128 v[4:7], v20 offset:36864
	v_rcp_f32_e32 v15, v0
	v_mul_f32_e32 v16, v10, v8
	v_mul_f32_e32 v17, v11, v9
	ds_read_b128 v[8:11], v20 offset:37952
	v_mov_b32_e32 v147, v1
	v_mul_f32_e32 v12, v14, v12
	v_mul_f32_e32 v13, v15, v13
	s_waitcnt lgkmcnt(1)
	v_mul_f32_e32 v4, v16, v4
	v_mul_f32_e32 v5, v17, v5
	v_mul_f32_e32 v6, v12, v6
	v_mul_f32_e32 v7, v13, v7
	v_cvt_pk_bf16_f32 v4, v4, v5
	v_cvt_pk_bf16_f32 v5, v6, v7
	v_lshlrev_b32_e32 v6, 16, v144
	v_and_b32_e32 v7, 0xffff0000, v144
	v_mul_f32_e32 v12, 0xbfb8aa3b, v6
	v_lshlrev_b32_e32 v16, 16, v145
	v_and_b32_e32 v17, 0xffff0000, v145
	v_exp_f32_e32 v14, v12
	v_mul_f32_e32 v12, 0xbfb8aa3b, v7
	v_mul_f32_e32 v18, 0xbfb8aa3b, v16
	v_mul_f32_e32 v19, 0xbfb8aa3b, v17
	v_exp_f32_e32 v15, v12
	v_exp_f32_e32 v18, v18
	v_exp_f32_e32 v19, v19
	v_add_f32_e32 v14, 1.0, v14
	v_add_f32_e32 v15, 1.0, v15
	v_add_f32_e32 v18, 1.0, v18
	v_add_f32_e32 v19, 1.0, v19
	v_rcp_f32_e32 v14, v14
	v_rcp_f32_e32 v15, v15
	v_rcp_f32_e32 v18, v18
	v_rcp_f32_e32 v19, v19
	v_lshl_add_u64 v[2:3], v[2:3], 0, v[146:147]
	v_lshlrev_b32_e32 v0, 11, v153
	v_lshl_add_u64 v[12:13], v[2:3], 0, v[0:1]
	global_store_dwordx2 v[12:13], v[4:5], off offset:1536 sc1
	v_mul_f32_e32 v4, v14, v6
	v_mul_f32_e32 v5, v15, v7
	v_mul_f32_e32 v6, v18, v16
	v_mul_f32_e32 v7, v19, v17
	s_waitcnt lgkmcnt(0)
	v_mul_f32_e32 v4, v4, v8
	v_mul_f32_e32 v5, v5, v9
	v_mul_f32_e32 v6, v6, v10
	v_mul_f32_e32 v7, v7, v11
	v_cvt_pk_bf16_f32 v4, v4, v5
	v_cvt_pk_bf16_f32 v5, v6, v7
	v_or_b32_e32 v6, 0x2000, v0
	v_mov_b32_e32 v7, v1
	v_lshl_add_u64 v[6:7], v[2:3], 0, v[6:7]
	v_lshlrev_b32_e32 v8, 16, v142
	global_store_dwordx2 v[6:7], v[4:5], off offset:1536 sc1
	v_and_b32_e32 v9, 0xffff0000, v142
	v_mul_f32_e32 v4, 0xbfb8aa3b, v8
	v_lshlrev_b32_e32 v12, 16, v143
	v_and_b32_e32 v13, 0xffff0000, v143
	v_exp_f32_e32 v10, v4
	v_mul_f32_e32 v4, 0xbfb8aa3b, v9
	v_mul_f32_e32 v14, 0xbfb8aa3b, v12
	v_mul_f32_e32 v15, 0xbfb8aa3b, v13
	v_exp_f32_e32 v11, v4
	v_exp_f32_e32 v14, v14
	v_exp_f32_e32 v15, v15
	v_add_f32_e32 v10, 1.0, v10
	v_add_f32_e32 v11, 1.0, v11
	v_add_f32_e32 v14, 1.0, v14
	v_add_f32_e32 v15, 1.0, v15
	ds_read_b128 v[4:7], v20 offset:39040
	v_rcp_f32_e32 v10, v10
	v_rcp_f32_e32 v11, v11
	v_rcp_f32_e32 v14, v14
	v_rcp_f32_e32 v15, v15
	v_mul_f32_e32 v16, v10, v8
	v_mul_f32_e32 v17, v11, v9
	s_waitcnt lgkmcnt(0)
	v_mul_f32_e32 v4, v16, v4
	v_mul_f32_e32 v5, v17, v5
	v_mul_f32_e32 v12, v14, v12
	v_mul_f32_e32 v13, v15, v13
	v_lshlrev_b32_e32 v16, 16, v141
	v_mul_f32_e32 v6, v12, v6
	v_mul_f32_e32 v7, v13, v7
	v_lshlrev_b32_e32 v12, 16, v140
	v_and_b32_e32 v13, 0xffff0000, v140
	v_and_b32_e32 v17, 0xffff0000, v141
	v_mul_f32_e32 v14, 0xbfb8aa3b, v12
	v_mul_f32_e32 v15, 0xbfb8aa3b, v13
	v_mul_f32_e32 v18, 0xbfb8aa3b, v16
	v_mul_f32_e32 v19, 0xbfb8aa3b, v17
	v_exp_f32_e32 v14, v14
	v_exp_f32_e32 v15, v15
	v_exp_f32_e32 v18, v18
	v_exp_f32_e32 v19, v19
	v_add_f32_e32 v14, 1.0, v14
	v_add_f32_e32 v15, 1.0, v15
	v_add_f32_e32 v18, 1.0, v18
	v_add_f32_e32 v19, 1.0, v19
	ds_read_b128 v[8:11], v20 offset:40128
	v_rcp_f32_e32 v14, v14
	v_rcp_f32_e32 v15, v15
	v_rcp_f32_e32 v18, v18
	v_rcp_f32_e32 v19, v19
	v_cvt_pk_bf16_f32 v4, v4, v5
	v_cvt_pk_bf16_f32 v5, v6, v7
	v_or_b32_e32 v6, 0x4000, v0
	v_mov_b32_e32 v7, v1
	v_lshl_add_u64 v[6:7], v[2:3], 0, v[6:7]
	global_store_dwordx2 v[6:7], v[4:5], off offset:1536 sc1
	v_mul_f32_e32 v4, v14, v12
	v_mul_f32_e32 v5, v15, v13
	v_mul_f32_e32 v6, v18, v16
	v_mul_f32_e32 v7, v19, v17
	s_waitcnt lgkmcnt(0)
; DI float bflo(unsigned v) { return __uint_as_float(v << 16); }
; DI float bfhi(unsigned v) { return __uint_as_float(v & 0xffff0000u); }
; DI float silu(float g) { return g * __builtin_amdgcn_rcpf(1.f + ex2(-g * LOG2E)); }
; DI void store_y(const f32x16& oa, const f32x16& ob, float mult, const float* sg, const u32x2 (&gv)[8], u16* yrow0, float* stg,
;                 int lane, int r, int h) {
;     ...
;   for (int t = 0; t < 8; ++t) {
;     const int row = (lane >> 4) + 4 * t;
;     const f32x4 v = *(const f32x4*)(stg + row * 68 + kc * 4);
;     float y0 = v[0] * sv[0] * silu(bflo(gv[t][0]));
;     float y1 = v[1] * sv[1] * silu(bfhi(gv[t][0]));
;     float y2 = v[2] * sv[2] * silu(bflo(gv[t][1]));
;     float y3 = v[3] * sv[3] * silu(bfhi(gv[t][1]));
;     u32x2 yo = {pk2(y0, y1), pk2(y2, y3)};
;     *(u32x2*)(yrow0 + (size_t)row * DM + kc * 4) = yo;
;   }
	v_mul_f32_e32 v4, v4, v8
	v_mul_f32_e32 v5, v5, v9
	v_mul_f32_e32 v6, v6, v10
	v_mul_f32_e32 v7, v7, v11
	v_cvt_pk_bf16_f32 v4, v4, v5
	v_cvt_pk_bf16_f32 v5, v6, v7
	v_or_b32_e32 v6, 0x6000, v0
	v_mov_b32_e32 v7, v1
	v_lshl_add_u64 v[6:7], v[2:3], 0, v[6:7]
	v_lshlrev_b32_e32 v8, 16, v138
	global_store_dwordx2 v[6:7], v[4:5], off offset:1536 sc1
	v_and_b32_e32 v9, 0xffff0000, v138
	v_mul_f32_e32 v4, 0xbfb8aa3b, v8
	v_lshlrev_b32_e32 v12, 16, v139
	v_and_b32_e32 v13, 0xffff0000, v139
	v_exp_f32_e32 v10, v4
	v_mul_f32_e32 v4, 0xbfb8aa3b, v9
	v_mul_f32_e32 v14, 0xbfb8aa3b, v12
	v_mul_f32_e32 v15, 0xbfb8aa3b, v13
	v_exp_f32_e32 v11, v4
	v_exp_f32_e32 v14, v14
	v_exp_f32_e32 v15, v15
	v_add_f32_e32 v10, 1.0, v10
	v_add_f32_e32 v11, 1.0, v11
	v_add_f32_e32 v14, 1.0, v14
	v_add_f32_e32 v15, 1.0, v15
	ds_read_b128 v[4:7], v20 offset:41216
	v_rcp_f32_e32 v10, v10
	v_rcp_f32_e32 v11, v11
	v_rcp_f32_e32 v14, v14
	v_rcp_f32_e32 v15, v15
	v_mul_f32_e32 v16, v10, v8
	v_mul_f32_e32 v17, v11, v9
	s_waitcnt lgkmcnt(0)
	v_mul_f32_e32 v4, v16, v4
	v_mul_f32_e32 v5, v17, v5
	v_mul_f32_e32 v12, v14, v12
	v_mul_f32_e32 v13, v15, v13
	v_lshlrev_b32_e32 v16, 16, v137
	v_mul_f32_e32 v6, v12, v6
	v_mul_f32_e32 v7, v13, v7
	v_lshlrev_b32_e32 v12, 16, v136
	v_and_b32_e32 v13, 0xffff0000, v136
	v_and_b32_e32 v17, 0xffff0000, v137
	v_mul_f32_e32 v14, 0xbfb8aa3b, v12
	v_mul_f32_e32 v15, 0xbfb8aa3b, v13
	v_mul_f32_e32 v18, 0xbfb8aa3b, v16
	v_mul_f32_e32 v19, 0xbfb8aa3b, v17
	v_exp_f32_e32 v14, v14
	v_exp_f32_e32 v15, v15
	v_exp_f32_e32 v18, v18
	v_exp_f32_e32 v19, v19
	v_add_f32_e32 v14, 1.0, v14
	v_add_f32_e32 v15, 1.0, v15
	v_add_f32_e32 v18, 1.0, v18
	v_add_f32_e32 v19, 1.0, v19
	ds_read_b128 v[8:11], v20 offset:42304
	v_rcp_f32_e32 v14, v14
	v_rcp_f32_e32 v15, v15
	v_rcp_f32_e32 v18, v18
	v_rcp_f32_e32 v19, v19
	v_cvt_pk_bf16_f32 v4, v4, v5
	v_cvt_pk_bf16_f32 v5, v6, v7
	v_or_b32_e32 v6, 0x8000, v0
	v_mov_b32_e32 v7, v1
	v_lshl_add_u64 v[6:7], v[2:3], 0, v[6:7]
	global_store_dwordx2 v[6:7], v[4:5], off offset:1536 sc1
	v_mul_f32_e32 v4, v14, v12
	v_mul_f32_e32 v5, v15, v13
	v_mul_f32_e32 v6, v18, v16
	v_mul_f32_e32 v7, v19, v17
	s_waitcnt lgkmcnt(0)
	v_mul_f32_e32 v4, v4, v8
	v_mul_f32_e32 v5, v5, v9
	v_mul_f32_e32 v6, v6, v10
	v_mul_f32_e32 v7, v7, v11
	v_cvt_pk_bf16_f32 v4, v4, v5
	v_cvt_pk_bf16_f32 v5, v6, v7
	v_or_b32_e32 v6, 0xa000, v0
	v_mov_b32_e32 v7, v1
	v_lshl_add_u64 v[6:7], v[2:3], 0, v[6:7]
	s_waitcnt vmcnt(6)
	v_lshlrev_b32_e32 v8, 16, v134
	global_store_dwordx2 v[6:7], v[4:5], off offset:1536 sc1
	v_and_b32_e32 v9, 0xffff0000, v134
	v_mul_f32_e32 v4, 0xbfb8aa3b, v8
	v_lshlrev_b32_e32 v12, 16, v135
	v_and_b32_e32 v13, 0xffff0000, v135
	v_exp_f32_e32 v10, v4
	v_mul_f32_e32 v4, 0xbfb8aa3b, v9
	v_mul_f32_e32 v14, 0xbfb8aa3b, v12
	v_mul_f32_e32 v15, 0xbfb8aa3b, v13
	v_exp_f32_e32 v11, v4
	v_exp_f32_e32 v14, v14
	v_exp_f32_e32 v15, v15
	v_add_f32_e32 v10, 1.0, v10
	v_add_f32_e32 v11, 1.0, v11
	v_add_f32_e32 v14, 1.0, v14
	v_add_f32_e32 v15, 1.0, v15
	ds_read_b128 v[4:7], v20 offset:43392
	v_rcp_f32_e32 v10, v10
	v_rcp_f32_e32 v11, v11
	v_rcp_f32_e32 v14, v14
	v_rcp_f32_e32 v15, v15
	v_mul_f32_e32 v16, v10, v8
	v_mul_f32_e32 v17, v11, v9
	s_waitcnt lgkmcnt(0)
	v_mul_f32_e32 v4, v16, v4
	v_mul_f32_e32 v5, v17, v5
	v_mul_f32_e32 v12, v14, v12
	v_mul_f32_e32 v13, v15, v13
	s_waitcnt vmcnt(6)
	v_lshlrev_b32_e32 v16, 16, v133
	v_mul_f32_e32 v6, v12, v6
	v_mul_f32_e32 v7, v13, v7
	v_lshlrev_b32_e32 v12, 16, v132
	v_and_b32_e32 v13, 0xffff0000, v132
	v_and_b32_e32 v17, 0xffff0000, v133
	v_mul_f32_e32 v14, 0xbfb8aa3b, v12
	v_mul_f32_e32 v15, 0xbfb8aa3b, v13
	v_mul_f32_e32 v18, 0xbfb8aa3b, v16
	v_mul_f32_e32 v19, 0xbfb8aa3b, v17
	v_exp_f32_e32 v14, v14
	v_exp_f32_e32 v15, v15
	v_exp_f32_e32 v18, v18
	v_exp_f32_e32 v19, v19
	v_add_f32_e32 v14, 1.0, v14
	v_add_f32_e32 v15, 1.0, v15
	v_add_f32_e32 v18, 1.0, v18
	v_add_f32_e32 v19, 1.0, v19
	ds_read_b128 v[8:11], v20 offset:44480
	v_rcp_f32_e32 v14, v14
	v_rcp_f32_e32 v15, v15
	v_rcp_f32_e32 v18, v18
	v_rcp_f32_e32 v19, v19
	v_cvt_pk_bf16_f32 v4, v4, v5
	v_cvt_pk_bf16_f32 v5, v6, v7
	v_or_b32_e32 v6, 0xc000, v0
	v_mov_b32_e32 v7, v1
	v_lshl_add_u64 v[6:7], v[2:3], 0, v[6:7]
	global_store_dwordx2 v[6:7], v[4:5], off offset:1536 sc1
	v_mul_f32_e32 v4, v14, v12
	v_mul_f32_e32 v5, v15, v13
	v_mul_f32_e32 v6, v18, v16
	v_mul_f32_e32 v7, v19, v17
	s_waitcnt lgkmcnt(0)
	v_mul_f32_e32 v4, v4, v8
	v_mul_f32_e32 v5, v5, v9
	v_mul_f32_e32 v6, v6, v10
	v_mul_f32_e32 v7, v7, v11
	v_or_b32_e32 v0, 0xe000, v0
	v_cvt_pk_bf16_f32 v4, v4, v5
	v_cvt_pk_bf16_f32 v5, v6, v7
	v_lshl_add_u64 v[2:3], v[2:3], 0, v[0:1]
	global_store_dwordx2 v[2:3], v[4:5], off offset:1536 sc1

; DI float bflo(unsigned v) { return __uint_as_float(v << 16); }
; DI float bfhi(unsigned v) { return __uint_as_float(v & 0xffff0000u); }
; DI float silu(float g) { return g * __builtin_amdgcn_rcpf(1.f + ex2(-g * LOG2E)); }
; DI void store_y(const f32x16& oa, const f32x16& ob, float mult, const float* sg, const u32x2 (&gv)[8], u16* yrow0, float* stg,
;                 int lane, int r, int h) {
; #pragma unroll
;   for (int dt = 0; dt < 2; ++dt)
; #pragma unroll
;     for (int g = 0; g < 4; ++g) {
;       f32x4 v;
;       v[0] = (dt ? ob[4 * g] : oa[4 * g]) * mult; v[1] = (dt ? ob[4 * g + 1] : oa[4 * g + 1]) * mult;
;       v[2] = (dt ? ob[4 * g + 2] : oa[4 * g + 2]) * mult; v[3] = (dt ? ob[4 * g + 3] : oa[4 * g + 3]) * mult;
;       *(f32x4*)(stg + r * 68 + 32 * dt + 8 * g + 4 * h) = v;
;     }
;   const int kc = lane & 15;
;   f32x4 sv = {1.f, 1.f, 1.f, 1.f};
;   if (sg) sv = *(const f32x4*)(sg + kc * 4);
; #pragma unroll
;   for (int t = 0; t < 8; ++t) {
;     const int row = (lane >> 4) + 4 * t;
;     const f32x4 v = *(const f32x4*)(stg + row * 68 + kc * 4);
;     float y0 = v[0] * sv[0] * silu(bflo(gv[t][0]));
;     float y1 = v[1] * sv[1] * silu(bfhi(gv[t][0]));
;     float y2 = v[2] * sv[2] * silu(bflo(gv[t][1]));
;     float y3 = v[3] * sv[3] * silu(bfhi(gv[t][1]));
;     u32x2 yo = {pk2(y0, y1), pk2(y2, y3)};
;     *(u32x2*)(yrow0 + (size_t)row * DM + kc * 4) = yo;
;   }
; DI void attn_item_B2(const Params& p, int layer, int b, int head0, int qblk, u16* sm, int wv) {
;     ...
; #pragma unroll
;   for (int hh = 0; hh < 2; ++hh)
;     store_y(o[hh][0], o[hh][1], 1.f / ls[hh][0], nullptr, gate[hh], p.y + ((size_t)b * SEQ + q0w) * DM + 256 + (head0 + hh) * 64,
;             (float*)sm + 9216 + w * 2176, lane, r, h);
.LBB0_339:
	s_or_b64 exec, exec, s[0:1]
	v_readlane_b32 s0, v250, 9
	v_readlane_b32 s1, v250, 10
	s_nop 8
	v_mul_u32_u24_e32 v22, 0x110, v205
	v_lshl_add_u64 v[20:21], v[182:183], 0, s[0:1]
	s_movk_i32 s0, 0x2200
	v_mul_lo_u32 v19, v204, s0
	v_add3_u32 v51, v19, v22, v0
	v_div_scale_f32 v22, s[0:1], v50, v50, 1.0
	v_rcp_f32_e32 v23, v22
	s_barrier
	v_lshlrev_b64 v[20:21], 11, v[20:21]
	v_fma_f32 v24, -v22, v23, 1.0
	v_fmac_f32_e32 v23, v24, v23
	v_div_scale_f32 v24, vcc, 1.0, v50, 1.0
	v_mul_f32_e32 v25, v24, v23
	v_fma_f32 v26, -v22, v25, v24
	v_fmac_f32_e32 v25, v26, v23
	v_fma_f32 v22, -v22, v25, v24
	v_div_fmas_f32 v22, v22, v23, v25
	v_div_fixup_f32 v26, v22, v50, 1.0
	v_mul_f32_e32 v22, v66, v26
	v_mul_f32_e32 v23, v67, v26
	v_mul_f32_e32 v24, v68, v26
	v_mul_f32_e32 v25, v69, v26
	ds_write_b128 v51, v[22:25] offset:36864
	v_mul_f32_e32 v22, v70, v26
	v_mul_f32_e32 v23, v71, v26
	v_mul_f32_e32 v24, v72, v26
	v_mul_f32_e32 v25, v73, v26
	ds_write_b128 v51, v[22:25] offset:36896
	v_mul_f32_e32 v22, v74, v26
	v_mul_f32_e32 v23, v75, v26
	v_mul_f32_e32 v24, v76, v26
	v_mul_f32_e32 v25, v77, v26
	ds_write_b128 v51, v[22:25] offset:36928
	v_mul_f32_e32 v22, v78, v26
	v_mul_f32_e32 v23, v79, v26
	v_mul_f32_e32 v24, v80, v26
	v_mul_f32_e32 v25, v81, v26
	ds_write_b128 v51, v[22:25] offset:36960
	v_mul_f32_e32 v22, v34, v26
	v_mul_f32_e32 v23, v35, v26
	v_mul_f32_e32 v24, v36, v26
	v_mul_f32_e32 v25, v37, v26
	ds_write_b128 v51, v[22:25] offset:36992
	v_mul_f32_e32 v22, v38, v26
	v_mul_f32_e32 v23, v39, v26
	v_mul_f32_e32 v24, v40, v26
	v_mul_f32_e32 v25, v41, v26
	ds_write_b128 v51, v[22:25] offset:37024
	v_mul_f32_e32 v22, v42, v26
	v_mul_f32_e32 v23, v43, v26
	v_mul_f32_e32 v24, v44, v26
	v_mul_f32_e32 v25, v45, v26
	v_lshl_add_u64 v[20:21], s[90:91], 0, v[20:21]
	ds_write_b128 v51, v[22:25] offset:37056
	v_mul_f32_e32 v22, v46, v26
	v_mul_f32_e32 v23, v47, v26
	v_mul_f32_e32 v24, v48, v26
	v_mul_f32_e32 v25, v49, v26
	v_lshlrev_b32_e32 v26, 16, v180
	v_lshl_add_u64 v[28:29], s[42:43], 1, v[20:21]
	ds_write_b128 v51, v[22:25] offset:37088
	v_mov_b32_e32 v159, v1
	v_and_b32_e32 v27, 0xffff0000, v180
	v_mul_f32_e32 v22, 0xbfb8aa3b, v26
	v_lshlrev_b32_e32 v30, 16, v181
	v_and_b32_e32 v31, 0xffff0000, v181
	v_lshl_add_u64 v[36:37], v[28:29], 0, v[158:159]
	v_exp_f32_e32 v28, v22
	v_mul_f32_e32 v22, 0xbfb8aa3b, v27
	v_mul_f32_e32 v32, 0xbfb8aa3b, v30
	v_mul_f32_e32 v33, 0xbfb8aa3b, v31
	v_exp_f32_e32 v29, v22
	v_exp_f32_e32 v32, v32
	v_exp_f32_e32 v33, v33
	v_lshl_or_b32 v0, v207, 2, v19
	s_movk_i32 s0, 0x110
	v_mad_u32_u24 v19, v206, s0, v0
	v_add_f32_e32 v28, 1.0, v28
	v_add_f32_e32 v29, 1.0, v29
	v_add_f32_e32 v32, 1.0, v32
	v_add_f32_e32 v33, 1.0, v33
	ds_read_b128 v[22:25], v19 offset:36864
	v_rcp_f32_e32 v28, v28
	v_rcp_f32_e32 v29, v29
	v_rcp_f32_e32 v32, v32
	v_rcp_f32_e32 v33, v33
	v_lshlrev_b32_e32 v0, 11, v206
	v_mul_f32_e32 v34, v28, v26
	v_mul_f32_e32 v35, v29, v27
	ds_read_b128 v[26:29], v19 offset:37952
	v_mul_f32_e32 v30, v32, v30
	v_mul_f32_e32 v31, v33, v31
	s_waitcnt lgkmcnt(1)
	v_mul_f32_e32 v22, v34, v22
	v_mul_f32_e32 v23, v35, v23
	v_mul_f32_e32 v24, v30, v24
	v_mul_f32_e32 v25, v31, v25
	v_cvt_pk_bf16_f32 v22, v22, v23
	v_cvt_pk_bf16_f32 v23, v24, v25
	v_lshlrev_b32_e32 v24, 16, v176
	v_and_b32_e32 v25, 0xffff0000, v176
	v_mul_f32_e32 v30, 0xbfb8aa3b, v24
	v_lshlrev_b32_e32 v34, 16, v177
	v_and_b32_e32 v35, 0xffff0000, v177
	v_exp_f32_e32 v32, v30
	v_mul_f32_e32 v30, 0xbfb8aa3b, v25
	v_mul_f32_e32 v38, 0xbfb8aa3b, v34
	v_mul_f32_e32 v39, 0xbfb8aa3b, v35
	v_exp_f32_e32 v33, v30
	v_exp_f32_e32 v38, v38
	v_exp_f32_e32 v39, v39
	v_add_f32_e32 v32, 1.0, v32
	v_add_f32_e32 v33, 1.0, v33
	v_add_f32_e32 v38, 1.0, v38
	v_add_f32_e32 v39, 1.0, v39
	v_rcp_f32_e32 v32, v32
	v_rcp_f32_e32 v33, v33
	v_rcp_f32_e32 v38, v38
	v_rcp_f32_e32 v39, v39
	v_lshl_add_u64 v[30:31], v[36:37], 0, v[0:1]
	global_store_dwordx2 v[30:31], v[22:23], off offset:512 sc1
	v_mul_f32_e32 v22, v32, v24
	v_mul_f32_e32 v23, v33, v25
	v_mul_f32_e32 v24, v38, v34
	v_mul_f32_e32 v25, v39, v35
	s_waitcnt lgkmcnt(0)
	v_mul_f32_e32 v22, v22, v26
	v_mul_f32_e32 v23, v23, v27
	v_mul_f32_e32 v24, v24, v28
	v_mul_f32_e32 v25, v25, v29
	v_cvt_pk_bf16_f32 v22, v22, v23
	v_cvt_pk_bf16_f32 v23, v24, v25
	v_or_b32_e32 v24, 0x2000, v0
	v_mov_b32_e32 v25, v1
	v_lshl_add_u64 v[26:27], v[36:37], 0, v[24:25]
	global_store_dwordx2 v[26:27], v[22:23], off offset:512 sc1
	v_lshlrev_b32_e32 v22, 16, v174
	v_and_b32_e32 v23, 0xffff0000, v174
	v_mul_f32_e32 v26, 0xbfb8aa3b, v22
	v_lshlrev_b32_e32 v34, 16, v175
	v_exp_f32_e32 v30, v26
	v_mul_f32_e32 v26, 0xbfb8aa3b, v23
	v_and_b32_e32 v35, 0xffff0000, v175
	v_mul_f32_e32 v32, 0xbfb8aa3b, v34
	v_exp_f32_e32 v31, v26
	v_exp_f32_e32 v32, v32
	v_mul_f32_e32 v33, 0xbfb8aa3b, v35
	v_exp_f32_e32 v33, v33
	v_add_f32_e32 v30, 1.0, v30
	v_add_f32_e32 v31, 1.0, v31
	v_add_f32_e32 v32, 1.0, v32
	ds_read_b128 v[26:29], v19 offset:39040
	v_rcp_f32_e32 v30, v30
	v_rcp_f32_e32 v31, v31
	v_rcp_f32_e32 v38, v32
	v_add_f32_e32 v32, 1.0, v33
	v_rcp_f32_e32 v39, v32
	v_mul_f32_e32 v22, v30, v22
	v_mul_f32_e32 v23, v31, v23
	v_lshlrev_b32_e32 v40, 16, v173
	s_waitcnt lgkmcnt(0)
; DI float bflo(unsigned v) { return __uint_as_float(v << 16); }
; DI float bfhi(unsigned v) { return __uint_as_float(v & 0xffff0000u); }
; DI float silu(float g) { return g * __builtin_amdgcn_rcpf(1.f + ex2(-g * LOG2E)); }
; DI void store_y(const f32x16& oa, const f32x16& ob, float mult, const float* sg, const u32x2 (&gv)[8], u16* yrow0, float* stg,
;                 int lane, int r, int h) {
;     ...
; #pragma unroll
;   for (int t = 0; t < 8; ++t) {
;     const int row = (lane >> 4) + 4 * t;
;     const f32x4 v = *(const f32x4*)(stg + row * 68 + kc * 4);
;     float y0 = v[0] * sv[0] * silu(bflo(gv[t][0]));
;     float y1 = v[1] * sv[1] * silu(bfhi(gv[t][0]));
;     float y2 = v[2] * sv[2] * silu(bflo(gv[t][1]));
;     float y3 = v[3] * sv[3] * silu(bfhi(gv[t][1]));
;     u32x2 yo = {pk2(y0, y1), pk2(y2, y3)};
;     *(u32x2*)(yrow0 + (size_t)row * DM + kc * 4) = yo;
;   }
	v_mul_f32_e32 v22, v22, v26
	v_mul_f32_e32 v23, v23, v27
	v_mul_f32_e32 v26, v38, v34
	v_mul_f32_e32 v27, v39, v35
	v_and_b32_e32 v41, 0xffff0000, v173
	v_mul_f32_e32 v26, v26, v28
	v_mul_f32_e32 v27, v27, v29
	v_mul_f32_e32 v42, 0xbfb8aa3b, v40
	v_cvt_pk_bf16_f32 v29, v26, v27
	v_lshlrev_b32_e32 v26, 16, v172
	v_and_b32_e32 v27, 0xffff0000, v172
	v_mul_f32_e32 v34, 0xbfb8aa3b, v26
	v_exp_f32_e32 v38, v34
	v_mul_f32_e32 v34, 0xbfb8aa3b, v27
	v_mul_f32_e32 v43, 0xbfb8aa3b, v41
	v_exp_f32_e32 v39, v34
	v_exp_f32_e32 v42, v42
	v_exp_f32_e32 v43, v43
	v_add_f32_e32 v38, 1.0, v38
	v_add_f32_e32 v39, 1.0, v39
	v_add_f32_e32 v42, 1.0, v42
	v_add_f32_e32 v43, 1.0, v43
	ds_read_b128 v[30:33], v19 offset:40128
	v_rcp_f32_e32 v38, v38
	v_rcp_f32_e32 v39, v39
	v_rcp_f32_e32 v42, v42
	v_rcp_f32_e32 v43, v43
	v_cvt_pk_bf16_f32 v28, v22, v23
	v_or_b32_e32 v22, 0x4000, v0
	v_mov_b32_e32 v23, v1
	v_lshl_add_u64 v[34:35], v[36:37], 0, v[22:23]
	global_store_dwordx2 v[34:35], v[28:29], off offset:512 sc1
	v_mul_f32_e32 v26, v38, v26
	v_mul_f32_e32 v27, v39, v27
	v_mul_f32_e32 v28, v42, v40
	v_mul_f32_e32 v29, v43, v41
	s_waitcnt lgkmcnt(0)
	v_mul_f32_e32 v26, v26, v30
	v_mul_f32_e32 v27, v27, v31
	v_mul_f32_e32 v28, v28, v32
	v_mul_f32_e32 v29, v29, v33
	v_cvt_pk_bf16_f32 v26, v26, v27
	v_cvt_pk_bf16_f32 v27, v28, v29
	v_or_b32_e32 v28, 0x6000, v0
	v_mov_b32_e32 v29, v1
	v_lshl_add_u64 v[30:31], v[36:37], 0, v[28:29]
	global_store_dwordx2 v[30:31], v[26:27], off offset:512 sc1
	v_lshlrev_b32_e32 v26, 16, v170
	v_and_b32_e32 v27, 0xffff0000, v170
	v_mul_f32_e32 v30, 0xbfb8aa3b, v26
	v_lshlrev_b32_e32 v42, 16, v171
	v_exp_f32_e32 v34, v30
	v_mul_f32_e32 v30, 0xbfb8aa3b, v27
	v_and_b32_e32 v43, 0xffff0000, v171
	v_mul_f32_e32 v38, 0xbfb8aa3b, v42
	v_exp_f32_e32 v35, v30
	v_exp_f32_e32 v38, v38
	v_mul_f32_e32 v39, 0xbfb8aa3b, v43
	v_exp_f32_e32 v39, v39
	v_add_f32_e32 v34, 1.0, v34
	v_add_f32_e32 v35, 1.0, v35
	v_add_f32_e32 v38, 1.0, v38
	ds_read_b128 v[30:33], v19 offset:41216
	v_rcp_f32_e32 v34, v34
	v_rcp_f32_e32 v35, v35
	v_rcp_f32_e32 v44, v38
	v_add_f32_e32 v38, 1.0, v39
	v_rcp_f32_e32 v45, v38
	v_mul_f32_e32 v26, v34, v26
	v_mul_f32_e32 v27, v35, v27
	ds_read_b128 v[38:41], v19 offset:42304
	s_waitcnt lgkmcnt(1)
	v_mul_f32_e32 v26, v26, v30
	v_mul_f32_e32 v27, v27, v31
	v_mul_f32_e32 v30, v44, v42
	v_mul_f32_e32 v31, v45, v43
	v_lshlrev_b32_e32 v44, 16, v169
	v_mul_f32_e32 v30, v30, v32
	v_mul_f32_e32 v31, v31, v33
	v_and_b32_e32 v45, 0xffff0000, v169
	v_cvt_pk_bf16_f32 v33, v30, v31
	v_lshlrev_b32_e32 v30, 16, v168
	v_and_b32_e32 v31, 0xffff0000, v168
	v_mul_f32_e32 v34, 0xbfb8aa3b, v30
	v_exp_f32_e32 v42, v34
	v_mul_f32_e32 v34, 0xbfb8aa3b, v31
	v_mul_f32_e32 v46, 0xbfb8aa3b, v44
	v_mul_f32_e32 v47, 0xbfb8aa3b, v45
	v_exp_f32_e32 v43, v34
	v_exp_f32_e32 v46, v46
	v_exp_f32_e32 v47, v47
	v_add_f32_e32 v42, 1.0, v42
	v_add_f32_e32 v43, 1.0, v43
	v_add_f32_e32 v46, 1.0, v46
	v_add_f32_e32 v47, 1.0, v47
	v_rcp_f32_e32 v42, v42
	v_rcp_f32_e32 v43, v43
	v_rcp_f32_e32 v46, v46
	v_rcp_f32_e32 v47, v47
	v_cvt_pk_bf16_f32 v32, v26, v27
	v_or_b32_e32 v26, 0x8000, v0
	v_mov_b32_e32 v27, v1
	v_lshl_add_u64 v[34:35], v[36:37], 0, v[26:27]
	global_store_dwordx2 v[34:35], v[32:33], off offset:512 sc1
	v_mul_f32_e32 v30, v42, v30
	v_mul_f32_e32 v31, v43, v31
	v_mul_f32_e32 v32, v46, v44
	v_mul_f32_e32 v33, v47, v45
	s_waitcnt lgkmcnt(0)
	v_mul_f32_e32 v30, v30, v38
	v_mul_f32_e32 v31, v31, v39
	v_mul_f32_e32 v32, v32, v40
	v_mul_f32_e32 v33, v33, v41
	v_cvt_pk_bf16_f32 v30, v30, v31
	v_cvt_pk_bf16_f32 v31, v32, v33
	v_or_b32_e32 v32, 0xa000, v0
	v_mov_b32_e32 v33, v1
	v_lshl_add_u64 v[34:35], v[36:37], 0, v[32:33]
	v_lshlrev_b32_e32 v46, 16, v167
	global_store_dwordx2 v[34:35], v[30:31], off offset:512 sc1
	v_lshlrev_b32_e32 v30, 16, v166
	v_and_b32_e32 v31, 0xffff0000, v166
	v_and_b32_e32 v47, 0xffff0000, v167
	v_mul_f32_e32 v42, 0xbfb8aa3b, v46
	v_mul_f32_e32 v34, 0xbfb8aa3b, v30
	v_mul_f32_e32 v35, 0xbfb8aa3b, v31
	v_exp_f32_e32 v42, v42
	v_mul_f32_e32 v43, 0xbfb8aa3b, v47
	v_exp_f32_e32 v34, v34
	v_exp_f32_e32 v35, v35
	v_exp_f32_e32 v43, v43
	v_add_f32_e32 v42, 1.0, v42
	v_add_f32_e32 v34, 1.0, v34
	v_add_f32_e32 v35, 1.0, v35
	v_rcp_f32_e32 v48, v42
	v_add_f32_e32 v42, 1.0, v43
	v_rcp_f32_e32 v34, v34
	v_rcp_f32_e32 v35, v35
	v_rcp_f32_e32 v49, v42
	ds_read_b128 v[38:41], v19 offset:43392
	ds_read_b128 v[42:45], v19 offset:44480
	v_mul_f32_e32 v30, v34, v30
	v_mul_f32_e32 v31, v35, v31
	v_mul_f32_e32 v34, v48, v46
	v_mul_f32_e32 v35, v49, v47
	v_lshlrev_b32_e32 v48, 16, v165
	v_and_b32_e32 v49, 0xffff0000, v165
	v_mul_f32_e32 v50, 0xbfb8aa3b, v48
	s_waitcnt lgkmcnt(1)
	v_mul_f32_e32 v34, v34, v40
	v_mul_f32_e32 v35, v35, v41
	v_exp_f32_e32 v50, v50
	v_mul_f32_e32 v52, 0xbfb8aa3b, v49
	v_mul_f32_e32 v30, v30, v38
	v_mul_f32_e32 v31, v31, v39
	v_cvt_pk_bf16_f32 v39, v34, v35
	v_lshlrev_b32_e32 v34, 16, v164
	v_exp_f32_e32 v53, v52
	v_and_b32_e32 v35, 0xffff0000, v164
	v_mul_f32_e32 v40, 0xbfb8aa3b, v34
	v_exp_f32_e32 v46, v40
	v_mul_f32_e32 v40, 0xbfb8aa3b, v35
	v_exp_f32_e32 v47, v40
	v_add_f32_e32 v50, 1.0, v50
	v_rcp_f32_e32 v52, v50
	v_add_f32_e32 v50, 1.0, v53
	v_rcp_f32_e32 v53, v50
	v_cvt_pk_bf16_f32 v38, v30, v31
	v_or_b32_e32 v30, 0xc000, v0
	v_mov_b32_e32 v31, v1
	v_add_f32_e32 v46, 1.0, v46
	v_add_f32_e32 v47, 1.0, v47
	v_lshl_add_u64 v[40:41], v[36:37], 0, v[30:31]
	v_rcp_f32_e32 v46, v46
	v_rcp_f32_e32 v47, v47
	global_store_dwordx2 v[40:41], v[38:39], off offset:512 sc1
	v_mul_f32_e32 v38, v52, v48
	v_mul_f32_e32 v39, v53, v49
	v_lshl_add_u64 v[20:21], s[40:41], 1, v[20:21]
	s_waitcnt lgkmcnt(0)
; DI float bflo(unsigned v) { return __uint_as_float(v << 16); }
; DI float bfhi(unsigned v) { return __uint_as_float(v & 0xffff0000u); }
; DI float silu(float g) { return g * __builtin_amdgcn_rcpf(1.f + ex2(-g * LOG2E)); }
; DI void store_y(const f32x16& oa, const f32x16& ob, float mult, const float* sg, const u32x2 (&gv)[8], u16* yrow0, float* stg,
;                 int lane, int r, int h) {
; #pragma unroll
;   for (int dt = 0; dt < 2; ++dt)
; #pragma unroll
;     for (int g = 0; g < 4; ++g) {
;       f32x4 v;
;       v[0] = (dt ? ob[4 * g] : oa[4 * g]) * mult; v[1] = (dt ? ob[4 * g + 1] : oa[4 * g + 1]) * mult;
;       v[2] = (dt ? ob[4 * g + 2] : oa[4 * g + 2]) * mult; v[3] = (dt ? ob[4 * g + 3] : oa[4 * g + 3]) * mult;
;       *(f32x4*)(stg + r * 68 + 32 * dt + 8 * g + 4 * h) = v;
;     }
;   const int kc = lane & 15;
;   f32x4 sv = {1.f, 1.f, 1.f, 1.f};
;   if (sg) sv = *(const f32x4*)(sg + kc * 4);
; #pragma unroll
;   for (int t = 0; t < 8; ++t) {
;     const int row = (lane >> 4) + 4 * t;
;     const f32x4 v = *(const f32x4*)(stg + row * 68 + kc * 4);
;     float y0 = v[0] * sv[0] * silu(bflo(gv[t][0]));
;     float y1 = v[1] * sv[1] * silu(bfhi(gv[t][0]));
;     float y2 = v[2] * sv[2] * silu(bflo(gv[t][1]));
;     float y3 = v[3] * sv[3] * silu(bfhi(gv[t][1]));
;     u32x2 yo = {pk2(y0, y1), pk2(y2, y3)};
;     *(u32x2*)(yrow0 + (size_t)row * DM + kc * 4) = yo;
;   }
; DI void attn_item_B2(const Params& p, int layer, int b, int head0, int qblk, u16* sm, int wv) {
;     ...
; #pragma unroll
;   for (int hh = 0; hh < 2; ++hh)
;     store_y(o[hh][0], o[hh][1], 1.f / ls[hh][0], nullptr, gate[hh], p.y + ((size_t)b * SEQ + q0w) * DM + 256 + (head0 + hh) * 64,
;             (float*)sm + 9216 + w * 2176, lane, r, h);
	v_mul_f32_e32 v38, v38, v44
	v_mul_f32_e32 v39, v39, v45
	v_mul_f32_e32 v34, v46, v34
	v_mul_f32_e32 v35, v47, v35
	v_cvt_pk_bf16_f32 v41, v38, v39
	v_div_scale_f32 v38, s[0:1], v18, v18, 1.0
	v_rcp_f32_e32 v39, v38
	v_mul_f32_e32 v34, v34, v42
	v_mul_f32_e32 v35, v35, v43
	v_readlane_b32 s41, v250, 28
	v_cvt_pk_bf16_f32 v40, v34, v35
	v_or_b32_e32 v34, 0xe000, v0
	v_mov_b32_e32 v35, v1
	v_lshl_add_u64 v[36:37], v[36:37], 0, v[34:35]
	global_store_dwordx2 v[36:37], v[40:41], off offset:512 sc1
	v_fma_f32 v36, -v38, v39, 1.0
	v_fmac_f32_e32 v39, v36, v39
	v_div_scale_f32 v36, vcc, 1.0, v18, 1.0
	v_mul_f32_e32 v37, v36, v39
	v_fma_f32 v40, -v38, v37, v36
	v_fmac_f32_e32 v37, v40, v39
	v_fma_f32 v36, -v38, v37, v36
	v_div_fmas_f32 v36, v36, v39, v37
	v_div_fixup_f32 v18, v36, v18, 1.0
	v_mul_f32_e32 v2, v2, v18
	v_mul_f32_e32 v3, v3, v18
	v_mul_f32_e32 v4, v4, v18
	v_mul_f32_e32 v5, v5, v18
	ds_write_b128 v51, v[2:5] offset:36992
	v_mul_f32_e32 v2, v6, v18
	v_mul_f32_e32 v3, v7, v18
	v_mul_f32_e32 v4, v8, v18
	v_mul_f32_e32 v5, v9, v18
	ds_write_b128 v51, v[2:5] offset:37024
	v_mul_f32_e32 v2, v10, v18
	v_mul_f32_e32 v3, v11, v18
	v_mul_f32_e32 v4, v12, v18
	v_mul_f32_e32 v5, v13, v18
	ds_write_b128 v51, v[2:5] offset:37056
	v_mul_f32_e32 v2, v14, v18
	v_mul_f32_e32 v3, v15, v18
	v_mul_f32_e32 v4, v16, v18
	v_mul_f32_e32 v5, v17, v18
	v_lshlrev_b32_e32 v8, 16, v162
	ds_write_b128 v51, v[2:5] offset:37088
	v_and_b32_e32 v9, 0xffff0000, v162
	v_mul_f32_e32 v4, 0xbfb8aa3b, v8
	v_lshlrev_b32_e32 v12, 16, v163
	v_and_b32_e32 v13, 0xffff0000, v163
	v_exp_f32_e32 v10, v4
	v_mul_f32_e32 v4, 0xbfb8aa3b, v9
	v_mul_f32_e32 v14, 0xbfb8aa3b, v12
	v_mul_f32_e32 v15, 0xbfb8aa3b, v13
	v_mul_f32_e32 v36, v82, v18
	v_mul_f32_e32 v37, v83, v18
	v_mul_f32_e32 v38, v84, v18
	v_mul_f32_e32 v39, v85, v18
	v_exp_f32_e32 v11, v4
	v_exp_f32_e32 v14, v14
	v_exp_f32_e32 v15, v15
	ds_write_b128 v51, v[36:39] offset:36864
	v_mul_f32_e32 v36, v86, v18
	v_mul_f32_e32 v37, v87, v18
	v_mul_f32_e32 v38, v88, v18
	v_mul_f32_e32 v39, v89, v18
	ds_write_b128 v51, v[36:39] offset:36896
	v_mul_f32_e32 v36, v90, v18
	v_mul_f32_e32 v37, v91, v18
	v_mul_f32_e32 v38, v92, v18
	v_mul_f32_e32 v39, v93, v18
	ds_write_b128 v51, v[36:39] offset:36928
	v_mul_f32_e32 v36, v94, v18
	v_mul_f32_e32 v37, v95, v18
	v_mul_f32_e32 v38, v96, v18
	v_mul_f32_e32 v39, v97, v18
	ds_write_b128 v51, v[36:39] offset:36960
	v_add_f32_e32 v10, 1.0, v10
	v_add_f32_e32 v11, 1.0, v11
	v_add_f32_e32 v14, 1.0, v14
	v_add_f32_e32 v15, 1.0, v15
	ds_read_b128 v[4:7], v19 offset:36864
	v_rcp_f32_e32 v10, v10
	v_rcp_f32_e32 v11, v11
	v_rcp_f32_e32 v14, v14
	v_rcp_f32_e32 v15, v15
	v_lshl_add_u64 v[2:3], v[20:21], 0, v[158:159]
	v_mul_f32_e32 v16, v10, v8
	v_mul_f32_e32 v17, v11, v9
	ds_read_b128 v[8:11], v19 offset:37952
	v_mul_f32_e32 v12, v14, v12
	v_mul_f32_e32 v13, v15, v13
	s_waitcnt lgkmcnt(1)
	v_mul_f32_e32 v4, v16, v4
	v_mul_f32_e32 v5, v17, v5
	v_mul_f32_e32 v6, v12, v6
	v_mul_f32_e32 v7, v13, v7
	v_cvt_pk_bf16_f32 v4, v4, v5
	v_cvt_pk_bf16_f32 v5, v6, v7
	v_lshlrev_b32_e32 v6, 16, v160
	v_and_b32_e32 v7, 0xffff0000, v160
	v_mul_f32_e32 v12, 0xbfb8aa3b, v6
	v_exp_f32_e32 v14, v12
	v_mul_f32_e32 v12, 0xbfb8aa3b, v7
	v_exp_f32_e32 v15, v12
	v_lshl_add_u64 v[12:13], v[2:3], 0, v[0:1]
	v_add_f32_e32 v0, 1.0, v14
	v_lshlrev_b32_e32 v16, 16, v161
	v_rcp_f32_e32 v14, v0
	v_add_f32_e32 v0, 1.0, v15
	v_and_b32_e32 v17, 0xffff0000, v161
	v_mul_f32_e32 v15, 0xbfb8aa3b, v16
	v_exp_f32_e32 v18, v15
	v_mul_f32_e32 v15, 0xbfb8aa3b, v17
	v_exp_f32_e32 v21, v15
	v_rcp_f32_e32 v15, v0
	v_add_f32_e32 v0, 1.0, v18
	v_rcp_f32_e32 v20, v0
	v_add_f32_e32 v0, 1.0, v21
	v_rcp_f32_e32 v21, v0
	global_store_dwordx2 v[12:13], v[4:5], off offset:512 sc1
	v_mul_f32_e32 v4, v14, v6
	v_mul_f32_e32 v5, v15, v7
	v_lshlrev_b32_e32 v12, 16, v157
	v_mul_f32_e32 v6, v20, v16
	v_mul_f32_e32 v7, v21, v17
	s_waitcnt lgkmcnt(0)
	v_mul_f32_e32 v4, v4, v8
	v_mul_f32_e32 v5, v5, v9
	v_mul_f32_e32 v6, v6, v10
	v_mul_f32_e32 v7, v7, v11
	v_lshlrev_b32_e32 v8, 16, v156
	v_cvt_pk_bf16_f32 v4, v4, v5
	v_cvt_pk_bf16_f32 v5, v6, v7
	v_lshl_add_u64 v[6:7], v[2:3], 0, v[24:25]
	v_and_b32_e32 v9, 0xffff0000, v156
	v_mul_f32_e32 v0, 0xbfb8aa3b, v8
	global_store_dwordx2 v[6:7], v[4:5], off offset:512 sc1
	v_exp_f32_e32 v0, v0
	v_mul_f32_e32 v4, 0xbfb8aa3b, v9
	v_exp_f32_e32 v11, v4
	v_and_b32_e32 v13, 0xffff0000, v157
	v_add_f32_e32 v0, 1.0, v0
	v_rcp_f32_e32 v10, v0
	v_add_f32_e32 v0, 1.0, v11
	v_mul_f32_e32 v11, 0xbfb8aa3b, v12
	v_exp_f32_e32 v14, v11
	v_mul_f32_e32 v11, 0xbfb8aa3b, v13
	v_exp_f32_e32 v15, v11
	v_rcp_f32_e32 v11, v0
	v_add_f32_e32 v0, 1.0, v14
	v_rcp_f32_e32 v14, v0
	v_add_f32_e32 v0, 1.0, v15
	ds_read_b128 v[4:7], v19 offset:39040
	v_rcp_f32_e32 v15, v0
	v_mul_f32_e32 v16, v10, v8
	v_mul_f32_e32 v17, v11, v9
	ds_read_b128 v[8:11], v19 offset:40128
	v_mul_f32_e32 v12, v14, v12
	v_mul_f32_e32 v13, v15, v13
	s_waitcnt lgkmcnt(1)
; DI float bflo(unsigned v) { return __uint_as_float(v << 16); }
; DI float bfhi(unsigned v) { return __uint_as_float(v & 0xffff0000u); }
; DI float silu(float g) { return g * __builtin_amdgcn_rcpf(1.f + ex2(-g * LOG2E)); }
; DI void store_y(const f32x16& oa, const f32x16& ob, float mult, const float* sg, const u32x2 (&gv)[8], u16* yrow0, float* stg,
;                 int lane, int r, int h) {
;     ...
; #pragma unroll
;   for (int t = 0; t < 8; ++t) {
;     const int row = (lane >> 4) + 4 * t;
;     const f32x4 v = *(const f32x4*)(stg + row * 68 + kc * 4);
;     float y0 = v[0] * sv[0] * silu(bflo(gv[t][0]));
;     float y1 = v[1] * sv[1] * silu(bfhi(gv[t][0]));
;     float y2 = v[2] * sv[2] * silu(bflo(gv[t][1]));
;     float y3 = v[3] * sv[3] * silu(bfhi(gv[t][1]));
;     u32x2 yo = {pk2(y0, y1), pk2(y2, y3)};
;     *(u32x2*)(yrow0 + (size_t)row * DM + kc * 4) = yo;
;   }
	v_mul_f32_e32 v4, v16, v4
	v_mul_f32_e32 v5, v17, v5
	v_mul_f32_e32 v6, v12, v6
	v_mul_f32_e32 v7, v13, v7
	v_cvt_pk_bf16_f32 v4, v4, v5
	v_cvt_pk_bf16_f32 v5, v6, v7
	v_lshlrev_b32_e32 v6, 16, v154
	v_and_b32_e32 v7, 0xffff0000, v154
	v_mul_f32_e32 v0, 0xbfb8aa3b, v6
	v_exp_f32_e32 v0, v0
	v_mul_f32_e32 v12, 0xbfb8aa3b, v7
	v_exp_f32_e32 v15, v12
	v_lshlrev_b32_e32 v16, 16, v155
	v_add_f32_e32 v0, 1.0, v0
	v_rcp_f32_e32 v14, v0
	v_add_f32_e32 v0, 1.0, v15
	v_and_b32_e32 v17, 0xffff0000, v155
	v_mul_f32_e32 v15, 0xbfb8aa3b, v16
	v_exp_f32_e32 v18, v15
	v_mul_f32_e32 v15, 0xbfb8aa3b, v17
	v_exp_f32_e32 v21, v15
	v_rcp_f32_e32 v15, v0
	v_add_f32_e32 v0, 1.0, v18
	v_rcp_f32_e32 v20, v0
	v_add_f32_e32 v0, 1.0, v21
	v_rcp_f32_e32 v21, v0
	v_lshl_add_u64 v[12:13], v[2:3], 0, v[22:23]
	global_store_dwordx2 v[12:13], v[4:5], off offset:512 sc1
	v_mul_f32_e32 v4, v14, v6
	v_mul_f32_e32 v5, v15, v7
	v_mul_f32_e32 v6, v20, v16
	v_mul_f32_e32 v7, v21, v17
	s_waitcnt lgkmcnt(0)
	v_mul_f32_e32 v4, v4, v8
	v_mul_f32_e32 v5, v5, v9
	v_mul_f32_e32 v6, v6, v10
	v_mul_f32_e32 v7, v7, v11
	v_lshlrev_b32_e32 v8, 16, v152
	v_cvt_pk_bf16_f32 v4, v4, v5
	v_cvt_pk_bf16_f32 v5, v6, v7
	v_lshl_add_u64 v[6:7], v[2:3], 0, v[28:29]
	v_and_b32_e32 v9, 0xffff0000, v152
	v_mul_f32_e32 v0, 0xbfb8aa3b, v8
	global_store_dwordx2 v[6:7], v[4:5], off offset:512 sc1
	v_exp_f32_e32 v0, v0
	v_mul_f32_e32 v4, 0xbfb8aa3b, v9
	v_exp_f32_e32 v11, v4
	v_lshlrev_b32_e32 v12, 16, v153
	v_add_f32_e32 v0, 1.0, v0
	v_rcp_f32_e32 v10, v0
	v_add_f32_e32 v0, 1.0, v11
	v_and_b32_e32 v13, 0xffff0000, v153
	v_mul_f32_e32 v11, 0xbfb8aa3b, v12
	v_exp_f32_e32 v14, v11
	v_mul_f32_e32 v11, 0xbfb8aa3b, v13
	v_exp_f32_e32 v15, v11
	v_rcp_f32_e32 v11, v0
	v_add_f32_e32 v0, 1.0, v14
	v_rcp_f32_e32 v14, v0
	v_add_f32_e32 v0, 1.0, v15
	ds_read_b128 v[4:7], v19 offset:41216
	v_rcp_f32_e32 v15, v0
	v_mul_f32_e32 v16, v10, v8
	v_mul_f32_e32 v17, v11, v9
	ds_read_b128 v[8:11], v19 offset:42304
	v_mul_f32_e32 v12, v14, v12
	v_mul_f32_e32 v13, v15, v13
	s_waitcnt lgkmcnt(1)
	v_mul_f32_e32 v4, v16, v4
	v_mul_f32_e32 v5, v17, v5
	v_mul_f32_e32 v6, v12, v6
	v_mul_f32_e32 v7, v13, v7
	v_cvt_pk_bf16_f32 v4, v4, v5
	v_cvt_pk_bf16_f32 v5, v6, v7
	v_lshlrev_b32_e32 v6, 16, v150
	v_and_b32_e32 v7, 0xffff0000, v150
	v_mul_f32_e32 v0, 0xbfb8aa3b, v6
	v_exp_f32_e32 v0, v0
	v_mul_f32_e32 v12, 0xbfb8aa3b, v7
	v_exp_f32_e32 v15, v12
	v_lshlrev_b32_e32 v16, 16, v151
	v_add_f32_e32 v0, 1.0, v0
	v_rcp_f32_e32 v14, v0
	v_add_f32_e32 v0, 1.0, v15
	v_and_b32_e32 v17, 0xffff0000, v151
	v_mul_f32_e32 v15, 0xbfb8aa3b, v16
	v_exp_f32_e32 v18, v15
	v_mul_f32_e32 v15, 0xbfb8aa3b, v17
	v_exp_f32_e32 v21, v15
	v_rcp_f32_e32 v15, v0
	v_add_f32_e32 v0, 1.0, v18
	v_rcp_f32_e32 v20, v0
	v_add_f32_e32 v0, 1.0, v21
	v_rcp_f32_e32 v21, v0
	v_lshl_add_u64 v[12:13], v[2:3], 0, v[26:27]
	global_store_dwordx2 v[12:13], v[4:5], off offset:512 sc1
	v_mul_f32_e32 v4, v14, v6
	v_mul_f32_e32 v5, v15, v7
	v_mul_f32_e32 v6, v20, v16
	v_mul_f32_e32 v7, v21, v17
	s_waitcnt lgkmcnt(0)
	v_mul_f32_e32 v4, v4, v8
	v_mul_f32_e32 v5, v5, v9
	v_mul_f32_e32 v6, v6, v10
	v_mul_f32_e32 v7, v7, v11
	v_lshlrev_b32_e32 v8, 16, v148
	v_cvt_pk_bf16_f32 v4, v4, v5
	v_cvt_pk_bf16_f32 v5, v6, v7
	v_lshl_add_u64 v[6:7], v[2:3], 0, v[32:33]
	v_and_b32_e32 v9, 0xffff0000, v148
	v_mul_f32_e32 v0, 0xbfb8aa3b, v8
	global_store_dwordx2 v[6:7], v[4:5], off offset:512 sc1
	v_exp_f32_e32 v0, v0
	v_mul_f32_e32 v4, 0xbfb8aa3b, v9
	v_exp_f32_e32 v11, v4
	v_lshlrev_b32_e32 v12, 16, v149
	v_add_f32_e32 v0, 1.0, v0
	v_rcp_f32_e32 v10, v0
	v_add_f32_e32 v0, 1.0, v11
	v_and_b32_e32 v13, 0xffff0000, v149
	v_mul_f32_e32 v11, 0xbfb8aa3b, v12
	v_exp_f32_e32 v14, v11
	v_mul_f32_e32 v11, 0xbfb8aa3b, v13
	v_exp_f32_e32 v15, v11
	v_rcp_f32_e32 v11, v0
	v_add_f32_e32 v0, 1.0, v14
	v_rcp_f32_e32 v14, v0
	v_add_f32_e32 v0, 1.0, v15
	ds_read_b128 v[4:7], v19 offset:43392
	v_rcp_f32_e32 v15, v0
	v_mul_f32_e32 v16, v10, v8
	v_mul_f32_e32 v17, v11, v9
	ds_read_b128 v[8:11], v19 offset:44480
	v_mul_f32_e32 v12, v14, v12
	v_mul_f32_e32 v13, v15, v13
	s_waitcnt lgkmcnt(1)
	v_mul_f32_e32 v4, v16, v4
	v_mul_f32_e32 v5, v17, v5
	v_mul_f32_e32 v6, v12, v6
	v_mul_f32_e32 v7, v13, v7
	v_cvt_pk_bf16_f32 v4, v4, v5
	v_cvt_pk_bf16_f32 v5, v6, v7
	v_lshlrev_b32_e32 v6, 16, v146
	v_and_b32_e32 v7, 0xffff0000, v146
	v_mul_f32_e32 v0, 0xbfb8aa3b, v6
	v_exp_f32_e32 v0, v0
	v_mul_f32_e32 v12, 0xbfb8aa3b, v7
	v_exp_f32_e32 v15, v12
	v_lshlrev_b32_e32 v16, 16, v147
	v_add_f32_e32 v0, 1.0, v0
	v_rcp_f32_e32 v14, v0
	v_add_f32_e32 v0, 1.0, v15
	v_and_b32_e32 v17, 0xffff0000, v147
	v_mul_f32_e32 v15, 0xbfb8aa3b, v16
	v_exp_f32_e32 v18, v15
	v_mul_f32_e32 v15, 0xbfb8aa3b, v17
	v_exp_f32_e32 v19, v15
	v_rcp_f32_e32 v15, v0
	v_add_f32_e32 v0, 1.0, v18
	v_rcp_f32_e32 v18, v0
	v_add_f32_e32 v0, 1.0, v19
	v_rcp_f32_e32 v19, v0
	v_lshl_add_u64 v[12:13], v[2:3], 0, v[30:31]
	global_store_dwordx2 v[12:13], v[4:5], off offset:512 sc1
	v_mul_f32_e32 v4, v14, v6
	v_mul_f32_e32 v5, v15, v7
	v_mul_f32_e32 v6, v18, v16
	v_mul_f32_e32 v7, v19, v17
	s_waitcnt lgkmcnt(0)
	v_mul_f32_e32 v4, v4, v8
	v_mul_f32_e32 v5, v5, v9
	v_mul_f32_e32 v6, v6, v10
	v_mul_f32_e32 v7, v7, v11
	v_cvt_pk_bf16_f32 v4, v4, v5
	v_cvt_pk_bf16_f32 v5, v6, v7
	v_lshl_add_u64 v[2:3], v[2:3], 0, v[34:35]
	global_store_dwordx2 v[2:3], v[4:5], off offset:512 sc1
	s_or_b64 exec, exec, s[38:39]
	s_andn2_saveexec_b64 s[0:1], s[64:65]
	s_cbranch_execz .LBB0_196
	s_branch .LBB0_254

; DI float bflo(unsigned v) { return __uint_as_float(v << 16); }
; DI float bfhi(unsigned v) { return __uint_as_float(v & 0xffff0000u); }
; template <int EPI>
; DI void gemm_tile(const Params& p, int layer, int mt, int nt, u16* sm, int wv) {
;     ...
;     const bool has_next = (layer + 1 < DEPTH);
;     float* ssn = p.ss + (size_t)(layer + 1) * MTOK;
;     __syncthreads();
;     float* stg = (float*)(sm + (wm * 2 + wn) * (128 * LSTR));
;     const int kc = lane & 15;
; #pragma unroll
;     for (int hh = 0; hh < 2; ++hh) {
; #pragma unroll
;       for (int i2 = 0; i2 < 4; ++i2)
; #pragma unroll
;         for (int j = 0; j < 4; ++j)
;           *(f32x4*)(stg + (16 * i2 + fr) * 68 + 16 * j + 4 * fq) = acc[4 * hh + i2][j];
;       const size_t mrow0 = (size_t)(m0 + wm * 128 + 64 * hh);
;       u16* xrow = p.xg + mrow0 * DM + n0 + wn * 64 + kc * 4;
;       u16* x2row = (u16*)p.x2 + mrow0 * DM + n0 + wn * 64 + kc * 4;
;       u32x2 xb[16];
; #pragma unroll
;       for (int t = 0; t < 16; ++t) xb[t] = __builtin_nontemporal_load((const u32x2*)(xrow + (size_t)((lane >> 4) + 4 * t) * DM));
; #pragma unroll
;       for (int t = 0; t < 16; ++t) {
;         const int row = (lane >> 4) + 4 * t;
;         const f32x4 a4 = *(const f32x4*)(stg + row * 68 + kc * 4);
;         const float v0 = bflo(xb[t][0]) + a4[0], v1 = bfhi(xb[t][0]) + a4[1], v2 = bflo(xb[t][1]) + a4[2], v3 = bfhi(xb[t][1]) + a4[3];
;         float sq = v0 * v0 + v1 * v1 + v2 * v2 + v3 * v3;
;         u32x2 pv = {pk2(v0, v1), pk2(v2, v3)};
;         if (has_next) *(u32x2*)(xrow + (size_t)row * DM) = pv;
.LBB0_399:
	v_mbcnt_lo_u32_b32 v185, -1, 0
	v_mbcnt_hi_u32_b32 v185, -1, v185
	s_lshl_b64 s[2:3], s[2:3], 1
	v_add_u32_e32 v0, s33, v185
	v_bfe_u32 v181, v0, 6, 1
	s_waitcnt vmcnt(9)
	v_bfe_u32 v66, v0, 6, 21
	v_and_b32_e32 v0, 0xffffff80, v0
	v_lshl_add_u32 v68, s4, 8, v0
	v_and_b32_e32 v180, 15, v185
	v_mul_u32_u24_e32 v66, 0x4800, v66
	v_ashrrev_i32_e32 v69, 31, v68
	v_and_or_b32 v182, v185, 48, v66
	v_lshl_or_b32 v184, v180, 4, v66
	s_movk_i32 s4, 0x110
	v_lshlrev_b64 v[66:67], 11, v[68:69]
	v_mad_u32_u24 v0, v180, s4, v182
	s_waitcnt vmcnt(7)
	v_lshl_add_u64 v[70:71], s[60:61], 0, v[66:67]
	s_barrier
	ds_write_b128 v0, v[174:177]
	ds_write_b128 v0, v[170:173] offset:64
	ds_write_b128 v0, v[166:169] offset:128
	ds_write_b128 v0, v[162:165] offset:192
	ds_write_b128 v0, v[158:161] offset:4352
	ds_write_b128 v0, v[154:157] offset:4416
	ds_write_b128 v0, v[150:153] offset:4480
	ds_write_b128 v0, v[146:149] offset:4544
	ds_write_b128 v0, v[142:145] offset:8704
	ds_write_b128 v0, v[138:141] offset:8768
	ds_write_b128 v0, v[134:137] offset:8832
	ds_write_b128 v0, v[130:133] offset:8896
	ds_write_b128 v0, v[126:129] offset:13056
	ds_write_b128 v0, v[122:125] offset:13120
	ds_write_b128 v0, v[118:121] offset:13184
	ds_write_b128 v0, v[114:117] offset:13248
	v_lshl_add_u64 v[70:71], v[70:71], 0, s[2:3]
	v_lshlrev_b32_e32 v0, 7, v181
	v_lshl_add_u64 v[66:67], s[82:83], 0, v[66:67]
	v_bfe_u32 v183, v185, 4, 2
	v_lshl_add_u64 v[70:71], v[70:71], 0, v[0:1]
	s_waitcnt vmcnt(1)
	v_lshlrev_b32_e32 v104, 3, v180
	v_mov_b32_e32 v105, v1
	v_lshl_add_u64 v[66:67], v[66:67], 0, s[2:3]
	v_lshlrev_b32_e32 v186, 10, v183
	s_waitcnt vmcnt(0)
	v_lshl_add_u64 v[110:111], v[70:71], 0, v[104:105]
	v_lshl_add_u64 v[134:135], v[66:67], 0, v[0:1]
	v_lshlrev_b32_e32 v0, 11, v183
	v_lshl_add_u64 v[66:67], v[110:111], 0, v[0:1]
	v_or_b32_e32 v0, 0x1000, v186
	v_lshlrev_b32_e32 v70, 1, v0
	v_mov_b32_e32 v71, v1
	v_lshl_add_u64 v[72:73], v[110:111], 0, v[70:71]
	v_or_b32_e32 v0, 0x2000, v186
	global_load_dwordx2 v[132:133], v[72:73], off nt
	v_lshlrev_b32_e32 v72, 1, v0
	v_mov_b32_e32 v73, v1
	v_lshl_add_u64 v[74:75], v[110:111], 0, v[72:73]
	v_or_b32_e32 v0, 0x3000, v186
	global_load_dwordx2 v[130:131], v[74:75], off nt
	v_lshlrev_b32_e32 v74, 1, v0
	v_mov_b32_e32 v75, v1
	v_or_b32_e32 v0, 0x4000, v186
	v_lshl_add_u64 v[76:77], v[110:111], 0, v[74:75]
	v_lshlrev_b32_e32 v80, 1, v0
	v_mov_b32_e32 v81, v1
	global_load_dwordx2 v[128:129], v[76:77], off nt
	v_lshl_add_u64 v[76:77], v[110:111], 0, v[80:81]
	v_or_b32_e32 v0, 0x5000, v186
	global_load_dwordx2 v[126:127], v[76:77], off nt
	v_lshlrev_b32_e32 v76, 1, v0
	v_mov_b32_e32 v77, v1
	v_lshl_add_u64 v[78:79], v[110:111], 0, v[76:77]
	v_or_b32_e32 v0, 0x6000, v186
	global_load_dwordx2 v[124:125], v[78:79], off nt
	v_lshlrev_b32_e32 v78, 1, v0
	v_mov_b32_e32 v79, v1
	v_lshl_add_u64 v[82:83], v[110:111], 0, v[78:79]
	v_or_b32_e32 v0, 0x7000, v186
	global_load_dwordx2 v[122:123], v[82:83], off nt
	v_lshlrev_b32_e32 v82, 1, v0
	v_mov_b32_e32 v83, v1
	v_or_b32_e32 v0, 0x8000, v186
	v_lshl_add_u64 v[84:85], v[110:111], 0, v[82:83]
	v_lshlrev_b32_e32 v88, 1, v0
	v_mov_b32_e32 v89, v1
	global_load_dwordx2 v[120:121], v[84:85], off nt
	v_lshl_add_u64 v[84:85], v[110:111], 0, v[88:89]
	v_or_b32_e32 v0, 0x9000, v186
	global_load_dwordx2 v[118:119], v[84:85], off nt
	v_lshlrev_b32_e32 v84, 1, v0
	v_mov_b32_e32 v85, v1
	v_lshl_add_u64 v[86:87], v[110:111], 0, v[84:85]
	v_or_b32_e32 v0, 0xa000, v186
	global_load_dwordx2 v[116:117], v[86:87], off nt
	v_lshlrev_b32_e32 v86, 1, v0
	v_mov_b32_e32 v87, v1
	v_lshl_add_u64 v[90:91], v[110:111], 0, v[86:87]
	v_or_b32_e32 v0, 0xb000, v186
	global_load_dwordx2 v[114:115], v[90:91], off nt
	v_lshlrev_b32_e32 v90, 1, v0
	v_mov_b32_e32 v91, v1
	v_or_b32_e32 v0, 0xc000, v186
	v_lshl_add_u64 v[92:93], v[110:111], 0, v[90:91]
	v_lshlrev_b32_e32 v96, 1, v0
	v_mov_b32_e32 v97, v1
	global_load_dwordx2 v[112:113], v[92:93], off nt
	v_lshl_add_u64 v[92:93], v[110:111], 0, v[96:97]
	v_or_b32_e32 v0, 0xd000, v186
	global_load_dwordx2 v[108:109], v[92:93], off nt
	v_lshlrev_b32_e32 v92, 1, v0
	v_mov_b32_e32 v93, v1
	v_lshl_add_u64 v[94:95], v[110:111], 0, v[92:93]
	v_or_b32_e32 v0, 0xe000, v186
	global_load_dwordx2 v[140:141], v[66:67], off nt
	global_load_dwordx2 v[106:107], v[94:95], off nt
	v_lshlrev_b32_e32 v94, 1, v0
	v_mov_b32_e32 v95, v1
	v_lshl_add_u64 v[98:99], v[110:111], 0, v[94:95]
	v_or_b32_e32 v0, 0xf000, v186
	global_load_dwordx2 v[102:103], v[98:99], off nt
	v_lshlrev_b32_e32 v98, 1, v0
	v_mov_b32_e32 v99, v1
	v_lshl_add_u64 v[100:101], v[110:111], 0, v[98:99]
	global_load_dwordx2 v[100:101], v[100:101], off nt
	v_mad_u32_u24 v0, v183, s4, v184
	ds_read_b128 v[136:139], v0
	v_lshl_add_u64 v[134:135], v[134:135], 0, v[104:105]
	s_mov_b64 s[4:5], -1
	s_and_b64 vcc, exec, s[70:71]
	v_lshlrev_b32_e32 v0, 1, v186
	s_waitcnt vmcnt(3)
	v_lshlrev_b32_e32 v104, 16, v140
	v_and_b32_e32 v105, 0xffff0000, v140
	s_waitcnt lgkmcnt(0)
	v_add_f32_e32 v104, v136, v104
	v_add_f32_e32 v105, v137, v105
	v_lshlrev_b32_e32 v136, 16, v141
	v_and_b32_e32 v137, 0xffff0000, v141
	v_add_f32_e32 v136, v138, v136
	v_add_f32_e32 v137, v139, v137
	v_cvt_pk_bf16_f32 v138, v104, v105
	v_cvt_pk_bf16_f32 v139, v136, v137
	s_cbranch_vccz .LBB0_401
	v_lshl_add_u64 v[140:141], v[134:135], 0, v[0:1]
	global_store_dwordx2 v[140:141], v[138:139], off sc1
	s_mov_b64 s[4:5], 0
.LBB0_401:
	s_andn2_b64 vcc, exec, s[4:5]
	s_cbranch_vccnz .LBB0_403
	global_store_dwordx2 v[66:67], v[138:139], off sc1

; DI float bflo(unsigned v) { return __uint_as_float(v << 16); }
; DI float bfhi(unsigned v) { return __uint_as_float(v & 0xffff0000u); }
; template <int EPI>
; DI void gemm_tile(const Params& p, int layer, int mt, int nt, u16* sm, int wv) {
;     ...
;       for (int t = 0; t < 16; ++t) {
;         const int row = (lane >> 4) + 4 * t;
;         const f32x4 a4 = *(const f32x4*)(stg + row * 68 + kc * 4);
;         const float v0 = bflo(xb[t][0]) + a4[0], v1 = bfhi(xb[t][0]) + a4[1], v2 = bflo(xb[t][1]) + a4[2], v3 = bfhi(xb[t][1]) + a4[3];
;         float sq = v0 * v0 + v1 * v1 + v2 * v2 + v3 * v3;
;         u32x2 pv = {pk2(v0, v1), pk2(v2, v3)};
;         if (has_next) *(u32x2*)(xrow + (size_t)row * DM) = pv;
;         else *(u32x2*)(x2row + (size_t)row * DM) = pv;
;         sq += shx(sq, lane, 1); sq += shx(sq, lane, 2); sq += shx(sq, lane, 4); sq += shx(sq, lane, 8);
;         if (kc == 0) atomicAdd(ssn + mrow0 + row, sq);
.LBB0_405:
	v_mul_u32_u24_e32 v67, 0x110, v183
	v_add_u32_e32 v69, v67, v184
	ds_read_b128 v[140:143], v69 offset:1088
	v_lshlrev_b32_e32 v144, 16, v132
	v_and_b32_e32 v145, 0xffff0000, v132
	v_lshlrev_b32_e32 v132, 16, v133
	v_and_b32_e32 v133, 0xffff0000, v133
	s_waitcnt lgkmcnt(0)
	v_add_f32_e32 v140, v140, v144
	v_add_f32_e32 v141, v141, v145
	v_add_f32_e32 v142, v142, v132
	v_add_f32_e32 v143, v143, v133
	v_mul_f32_e32 v132, v140, v140
	v_mul_f32_e32 v133, v141, v141
	v_mul_f32_e32 v144, v142, v142
	v_mul_f32_e32 v145, v143, v143
	v_add_f32_e32 v67, v132, v133
	v_add_f32_e32 v67, v144, v67
	v_add_f32_e32 v67, v145, v67
	s_nop 1
	v_mov_b32_dpp v71, v67 quad_perm:[1,0,3,2] row_mask:0xf bank_mask:0xf
	v_or_b32_e32 v132, 4, v183
	v_cndmask_b32_e64 v111, v135, v111, s[34:35]
	v_cndmask_b32_e64 v110, v134, v110, s[34:35]
	v_lshlrev_b32_e32 v134, 11, v132
	s_waitcnt lgkmcnt(0)
	v_add_f32_e32 v67, v67, v71
	s_nop 1
	v_mov_b32_dpp v71, v67 quad_perm:[2,3,0,1] row_mask:0xf bank_mask:0xf
	v_mov_b32_e32 v135, v1
	v_cvt_pk_bf16_f32 v140, v140, v141
	v_cvt_pk_bf16_f32 v141, v142, v143
	v_lshl_add_u64 v[134:135], v[110:111], 0, v[134:135]
	s_waitcnt lgkmcnt(0)
	v_add_f32_e32 v67, v67, v71
	s_nop 1
	v_mov_b32_dpp v71, v67 row_half_mirror row_mask:0xf bank_mask:0xf
	global_store_dwordx2 v[134:135], v[140:141], off sc1
	s_waitcnt lgkmcnt(0)
	v_add_f32_e32 v67, v67, v71
	s_nop 1
	v_mov_b32_dpp v71, v67 row_mirror row_mask:0xf bank_mask:0xf
	v_add_f32_e32 v146, v67, v71
	v_cmp_eq_u32_e64 s[4:5], 1, v180
	s_nop 1
	v_cndmask_b32_e64 v147, v147, v146, s[4:5]
.LBB0_407:
	ds_read_b128 v[140:143], v69 offset:2176
	v_lshlrev_b32_e32 v134, 16, v130
	v_and_b32_e32 v135, 0xffff0000, v130
	v_lshlrev_b32_e32 v130, 16, v131
	v_and_b32_e32 v131, 0xffff0000, v131
	s_waitcnt lgkmcnt(0)
	v_add_f32_e32 v134, v140, v134
	v_add_f32_e32 v135, v141, v135
	v_add_f32_e32 v140, v142, v130
	v_add_f32_e32 v141, v143, v131
	v_mul_f32_e32 v130, v134, v134
	v_mul_f32_e32 v131, v135, v135
	v_mul_f32_e32 v142, v140, v140
	v_mul_f32_e32 v143, v141, v141
	v_add_f32_e32 v67, v130, v131
	v_add_f32_e32 v67, v142, v67
	v_add_f32_e32 v67, v143, v67
	s_nop 1
	v_mov_b32_dpp v71, v67 quad_perm:[1,0,3,2] row_mask:0xf bank_mask:0xf
	v_or_b32_e32 v130, 8, v183
	v_cvt_pk_bf16_f32 v134, v134, v135
	v_cvt_pk_bf16_f32 v135, v140, v141
	v_lshlrev_b32_e32 v140, 11, v130
	s_waitcnt lgkmcnt(0)
	v_add_f32_e32 v67, v67, v71
	s_nop 1
	v_mov_b32_dpp v71, v67 quad_perm:[2,3,0,1] row_mask:0xf bank_mask:0xf
	v_mov_b32_e32 v141, v1
	v_lshl_add_u64 v[140:141], v[110:111], 0, v[140:141]
	global_store_dwordx2 v[140:141], v[134:135], off sc1
	s_waitcnt lgkmcnt(0)
	v_add_f32_e32 v67, v67, v71
	s_nop 1
	v_mov_b32_dpp v71, v67 row_half_mirror row_mask:0xf bank_mask:0xf
	s_waitcnt lgkmcnt(0)
	v_add_f32_e32 v67, v67, v71
	s_nop 1
	v_mov_b32_dpp v71, v67 row_mirror row_mask:0xf bank_mask:0xf
	v_add_f32_e32 v146, v67, v71
	v_cmp_eq_u32_e64 s[4:5], 2, v180
	s_nop 1
	v_cndmask_b32_e64 v147, v147, v146, s[4:5]
.LBB0_409:
	ds_read_b128 v[140:143], v69 offset:3264
	v_lshlrev_b32_e32 v134, 16, v128
	v_and_b32_e32 v135, 0xffff0000, v128
	v_lshlrev_b32_e32 v128, 16, v129
	v_and_b32_e32 v129, 0xffff0000, v129
	s_waitcnt lgkmcnt(0)
	v_add_f32_e32 v134, v140, v134
	v_add_f32_e32 v135, v141, v135
	v_add_f32_e32 v140, v142, v128
	v_add_f32_e32 v141, v143, v129
	v_mul_f32_e32 v128, v134, v134
	v_mul_f32_e32 v129, v135, v135
	v_mul_f32_e32 v142, v140, v140
	v_mul_f32_e32 v143, v141, v141
	v_add_f32_e32 v67, v128, v129
	v_add_f32_e32 v67, v142, v67
	v_add_f32_e32 v67, v143, v67
	s_nop 1
	v_mov_b32_dpp v71, v67 quad_perm:[1,0,3,2] row_mask:0xf bank_mask:0xf
	v_or_b32_e32 v128, 12, v183
	v_cvt_pk_bf16_f32 v134, v134, v135
	v_cvt_pk_bf16_f32 v135, v140, v141
	v_lshlrev_b32_e32 v140, 11, v128
	s_waitcnt lgkmcnt(0)
	v_add_f32_e32 v67, v67, v71
	s_nop 1
	v_mov_b32_dpp v71, v67 quad_perm:[2,3,0,1] row_mask:0xf bank_mask:0xf
	v_mov_b32_e32 v141, v1
	v_lshl_add_u64 v[140:141], v[110:111], 0, v[140:141]
	global_store_dwordx2 v[140:141], v[134:135], off sc1
	s_waitcnt lgkmcnt(0)
	v_add_f32_e32 v67, v67, v71
	s_nop 1
	v_mov_b32_dpp v71, v67 row_half_mirror row_mask:0xf bank_mask:0xf
	s_waitcnt lgkmcnt(0)
	v_add_f32_e32 v67, v67, v71
	s_nop 1
	v_mov_b32_dpp v71, v67 row_mirror row_mask:0xf bank_mask:0xf
	v_add_f32_e32 v146, v67, v71
	v_cmp_eq_u32_e64 s[4:5], 3, v180
	s_nop 1
	v_cndmask_b32_e64 v147, v147, v146, s[4:5]
.LBB0_411:
	ds_read_b128 v[140:143], v69 offset:4352
	v_lshlrev_b32_e32 v134, 16, v126
	v_and_b32_e32 v135, 0xffff0000, v126
	v_lshlrev_b32_e32 v126, 16, v127
	v_and_b32_e32 v127, 0xffff0000, v127
	s_waitcnt lgkmcnt(0)
	v_add_f32_e32 v134, v140, v134
	v_add_f32_e32 v135, v141, v135
	v_add_f32_e32 v140, v142, v126
	v_add_f32_e32 v141, v143, v127
	v_mul_f32_e32 v126, v134, v134
	v_mul_f32_e32 v127, v135, v135
	v_mul_f32_e32 v142, v140, v140
	v_mul_f32_e32 v143, v141, v141
	v_add_f32_e32 v67, v126, v127
	v_add_f32_e32 v67, v142, v67
	v_add_f32_e32 v67, v143, v67
	s_nop 1
	v_mov_b32_dpp v71, v67 quad_perm:[1,0,3,2] row_mask:0xf bank_mask:0xf
	v_or_b32_e32 v126, 16, v183
	v_cvt_pk_bf16_f32 v134, v134, v135
	v_cvt_pk_bf16_f32 v135, v140, v141
	v_lshlrev_b32_e32 v140, 11, v126
	s_waitcnt lgkmcnt(0)
	v_add_f32_e32 v67, v67, v71
	s_nop 1
	v_mov_b32_dpp v71, v67 quad_perm:[2,3,0,1] row_mask:0xf bank_mask:0xf
	v_mov_b32_e32 v141, v1
	v_lshl_add_u64 v[140:141], v[110:111], 0, v[140:141]
	global_store_dwordx2 v[140:141], v[134:135], off sc1
	s_waitcnt lgkmcnt(0)
	v_add_f32_e32 v67, v67, v71
	s_nop 1
	v_mov_b32_dpp v71, v67 row_half_mirror row_mask:0xf bank_mask:0xf
	s_waitcnt lgkmcnt(0)
	v_add_f32_e32 v67, v67, v71
	s_nop 1
	v_mov_b32_dpp v71, v67 row_mirror row_mask:0xf bank_mask:0xf
	v_add_f32_e32 v146, v67, v71
	v_cmp_eq_u32_e64 s[4:5], 4, v180
	s_nop 1
	v_cndmask_b32_e64 v147, v147, v146, s[4:5]
; DI float bflo(unsigned v) { return __uint_as_float(v << 16); }
; DI float bfhi(unsigned v) { return __uint_as_float(v & 0xffff0000u); }
; template <int EPI>
; DI void gemm_tile(const Params& p, int layer, int mt, int nt, u16* sm, int wv) {
;     ...
;       for (int t = 0; t < 16; ++t) {
;         const int row = (lane >> 4) + 4 * t;
;         const f32x4 a4 = *(const f32x4*)(stg + row * 68 + kc * 4);
;         const float v0 = bflo(xb[t][0]) + a4[0], v1 = bfhi(xb[t][0]) + a4[1], v2 = bflo(xb[t][1]) + a4[2], v3 = bfhi(xb[t][1]) + a4[3];
;         float sq = v0 * v0 + v1 * v1 + v2 * v2 + v3 * v3;
;         u32x2 pv = {pk2(v0, v1), pk2(v2, v3)};
;         if (has_next) *(u32x2*)(xrow + (size_t)row * DM) = pv;
;         else *(u32x2*)(x2row + (size_t)row * DM) = pv;
;         sq += shx(sq, lane, 1); sq += shx(sq, lane, 2); sq += shx(sq, lane, 4); sq += shx(sq, lane, 8);
;         if (kc == 0) atomicAdd(ssn + mrow0 + row, sq);
.LBB0_413:
	ds_read_b128 v[140:143], v69 offset:5440
	v_lshlrev_b32_e32 v134, 16, v124
	v_and_b32_e32 v135, 0xffff0000, v124
	v_lshlrev_b32_e32 v124, 16, v125
	v_and_b32_e32 v125, 0xffff0000, v125
	s_waitcnt lgkmcnt(0)
	v_add_f32_e32 v134, v140, v134
	v_add_f32_e32 v135, v141, v135
	v_add_f32_e32 v140, v142, v124
	v_add_f32_e32 v141, v143, v125
	v_mul_f32_e32 v124, v134, v134
	v_mul_f32_e32 v125, v135, v135
	v_mul_f32_e32 v142, v140, v140
	v_mul_f32_e32 v143, v141, v141
	v_add_f32_e32 v67, v124, v125
	v_add_f32_e32 v67, v142, v67
	v_add_f32_e32 v67, v143, v67
	s_nop 1
	v_mov_b32_dpp v71, v67 quad_perm:[1,0,3,2] row_mask:0xf bank_mask:0xf
	v_or_b32_e32 v124, 20, v183
	v_cvt_pk_bf16_f32 v134, v134, v135
	v_cvt_pk_bf16_f32 v135, v140, v141
	v_lshlrev_b32_e32 v140, 11, v124
	s_waitcnt lgkmcnt(0)
	v_add_f32_e32 v67, v67, v71
	s_nop 1
	v_mov_b32_dpp v71, v67 quad_perm:[2,3,0,1] row_mask:0xf bank_mask:0xf
	v_mov_b32_e32 v141, v1
	v_lshl_add_u64 v[140:141], v[110:111], 0, v[140:141]
	global_store_dwordx2 v[140:141], v[134:135], off sc1
	s_waitcnt lgkmcnt(0)
	v_add_f32_e32 v67, v67, v71
	s_nop 1
	v_mov_b32_dpp v71, v67 row_half_mirror row_mask:0xf bank_mask:0xf
	s_waitcnt lgkmcnt(0)
	v_add_f32_e32 v67, v67, v71
	s_nop 1
	v_mov_b32_dpp v71, v67 row_mirror row_mask:0xf bank_mask:0xf
	v_add_f32_e32 v146, v67, v71
	v_cmp_eq_u32_e64 s[4:5], 5, v180
	s_nop 1
	v_cndmask_b32_e64 v147, v147, v146, s[4:5]
.LBB0_415:
	ds_read_b128 v[140:143], v69 offset:6528
	v_lshlrev_b32_e32 v134, 16, v122
	v_and_b32_e32 v135, 0xffff0000, v122
	v_lshlrev_b32_e32 v122, 16, v123
	v_and_b32_e32 v123, 0xffff0000, v123
	s_waitcnt lgkmcnt(0)
	v_add_f32_e32 v134, v140, v134
	v_add_f32_e32 v135, v141, v135
	v_add_f32_e32 v140, v142, v122
	v_add_f32_e32 v141, v143, v123
	v_mul_f32_e32 v122, v134, v134
	v_mul_f32_e32 v123, v135, v135
	v_mul_f32_e32 v142, v140, v140
	v_mul_f32_e32 v143, v141, v141
	v_add_f32_e32 v67, v122, v123
	v_add_f32_e32 v67, v142, v67
	v_add_f32_e32 v67, v143, v67
	s_nop 1
	v_mov_b32_dpp v71, v67 quad_perm:[1,0,3,2] row_mask:0xf bank_mask:0xf
	v_or_b32_e32 v122, 24, v183
	v_cvt_pk_bf16_f32 v134, v134, v135
	v_cvt_pk_bf16_f32 v135, v140, v141
	v_lshlrev_b32_e32 v140, 11, v122
	s_waitcnt lgkmcnt(0)
	v_add_f32_e32 v67, v67, v71
	s_nop 1
	v_mov_b32_dpp v71, v67 quad_perm:[2,3,0,1] row_mask:0xf bank_mask:0xf
	v_mov_b32_e32 v141, v1
	v_lshl_add_u64 v[140:141], v[110:111], 0, v[140:141]
	global_store_dwordx2 v[140:141], v[134:135], off sc1
	s_waitcnt lgkmcnt(0)
	v_add_f32_e32 v67, v67, v71
	s_nop 1
	v_mov_b32_dpp v71, v67 row_half_mirror row_mask:0xf bank_mask:0xf
	s_waitcnt lgkmcnt(0)
	v_add_f32_e32 v67, v67, v71
	s_nop 1
	v_mov_b32_dpp v71, v67 row_mirror row_mask:0xf bank_mask:0xf
	v_add_f32_e32 v146, v67, v71
	v_cmp_eq_u32_e64 s[4:5], 6, v180
	s_nop 1
	v_cndmask_b32_e64 v147, v147, v146, s[4:5]
.LBB0_417:
	ds_read_b128 v[140:143], v69 offset:7616
	v_lshlrev_b32_e32 v134, 16, v120
	v_and_b32_e32 v135, 0xffff0000, v120
	v_lshlrev_b32_e32 v120, 16, v121
	v_and_b32_e32 v121, 0xffff0000, v121
	s_waitcnt lgkmcnt(0)
	v_add_f32_e32 v134, v140, v134
	v_add_f32_e32 v135, v141, v135
	v_add_f32_e32 v140, v142, v120
	v_add_f32_e32 v141, v143, v121
	v_mul_f32_e32 v120, v134, v134
	v_mul_f32_e32 v121, v135, v135
	v_mul_f32_e32 v142, v140, v140
	v_mul_f32_e32 v143, v141, v141
	v_add_f32_e32 v67, v120, v121
	v_add_f32_e32 v67, v142, v67
	v_add_f32_e32 v67, v143, v67
	s_nop 1
	v_mov_b32_dpp v71, v67 quad_perm:[1,0,3,2] row_mask:0xf bank_mask:0xf
	v_or_b32_e32 v120, 28, v183
	v_cvt_pk_bf16_f32 v134, v134, v135
	v_cvt_pk_bf16_f32 v135, v140, v141
	v_lshlrev_b32_e32 v140, 11, v120
	s_waitcnt lgkmcnt(0)
	v_add_f32_e32 v67, v67, v71
	s_nop 1
	v_mov_b32_dpp v71, v67 quad_perm:[2,3,0,1] row_mask:0xf bank_mask:0xf
	v_mov_b32_e32 v141, v1
	v_lshl_add_u64 v[140:141], v[110:111], 0, v[140:141]
	global_store_dwordx2 v[140:141], v[134:135], off sc1
	s_waitcnt lgkmcnt(0)
	v_add_f32_e32 v67, v67, v71
	s_nop 1
	v_mov_b32_dpp v71, v67 row_half_mirror row_mask:0xf bank_mask:0xf
	s_waitcnt lgkmcnt(0)
	v_add_f32_e32 v67, v67, v71
	s_nop 1
	v_mov_b32_dpp v71, v67 row_mirror row_mask:0xf bank_mask:0xf
	v_add_f32_e32 v146, v67, v71
	v_cmp_eq_u32_e64 s[4:5], 7, v180
	s_nop 1
	v_cndmask_b32_e64 v147, v147, v146, s[4:5]
.LBB0_419:
	ds_read_b128 v[140:143], v69 offset:8704
	v_lshlrev_b32_e32 v134, 16, v118
	v_and_b32_e32 v135, 0xffff0000, v118
	v_lshlrev_b32_e32 v118, 16, v119
	v_and_b32_e32 v119, 0xffff0000, v119
	s_waitcnt lgkmcnt(0)
	v_add_f32_e32 v134, v140, v134
	v_add_f32_e32 v135, v141, v135
	v_add_f32_e32 v140, v142, v118
	v_add_f32_e32 v141, v143, v119
	v_mul_f32_e32 v118, v134, v134
	v_mul_f32_e32 v119, v135, v135
	v_mul_f32_e32 v142, v140, v140
	v_mul_f32_e32 v143, v141, v141
	v_add_f32_e32 v67, v118, v119
	v_add_f32_e32 v67, v142, v67
	v_add_f32_e32 v67, v143, v67
	s_nop 1
	v_mov_b32_dpp v71, v67 quad_perm:[1,0,3,2] row_mask:0xf bank_mask:0xf
	v_or_b32_e32 v118, 32, v183
	v_cvt_pk_bf16_f32 v134, v134, v135
	v_cvt_pk_bf16_f32 v135, v140, v141
	v_lshlrev_b32_e32 v140, 11, v118
	s_waitcnt lgkmcnt(0)
	v_add_f32_e32 v67, v67, v71
	s_nop 1
	v_mov_b32_dpp v71, v67 quad_perm:[2,3,0,1] row_mask:0xf bank_mask:0xf
	v_mov_b32_e32 v141, v1
	v_lshl_add_u64 v[140:141], v[110:111], 0, v[140:141]
	global_store_dwordx2 v[140:141], v[134:135], off sc1
	s_waitcnt lgkmcnt(0)
	v_add_f32_e32 v67, v67, v71
	s_nop 1
	v_mov_b32_dpp v71, v67 row_half_mirror row_mask:0xf bank_mask:0xf
	s_waitcnt lgkmcnt(0)
	v_add_f32_e32 v67, v67, v71
	s_nop 1
	v_mov_b32_dpp v71, v67 row_mirror row_mask:0xf bank_mask:0xf
	v_add_f32_e32 v146, v67, v71
	v_cmp_eq_u32_e64 s[4:5], 8, v180
	s_nop 1
	v_cndmask_b32_e64 v147, v147, v146, s[4:5]
; DI float bflo(unsigned v) { return __uint_as_float(v << 16); }
; DI float bfhi(unsigned v) { return __uint_as_float(v & 0xffff0000u); }
; template <int EPI>
; DI void gemm_tile(const Params& p, int layer, int mt, int nt, u16* sm, int wv) {
;     ...
;       for (int t = 0; t < 16; ++t) {
;         const int row = (lane >> 4) + 4 * t;
;         const f32x4 a4 = *(const f32x4*)(stg + row * 68 + kc * 4);
;         const float v0 = bflo(xb[t][0]) + a4[0], v1 = bfhi(xb[t][0]) + a4[1], v2 = bflo(xb[t][1]) + a4[2], v3 = bfhi(xb[t][1]) + a4[3];
;         float sq = v0 * v0 + v1 * v1 + v2 * v2 + v3 * v3;
;         u32x2 pv = {pk2(v0, v1), pk2(v2, v3)};
;         if (has_next) *(u32x2*)(xrow + (size_t)row * DM) = pv;
;         else *(u32x2*)(x2row + (size_t)row * DM) = pv;
;         sq += shx(sq, lane, 1); sq += shx(sq, lane, 2); sq += shx(sq, lane, 4); sq += shx(sq, lane, 8);
;         if (kc == 0) atomicAdd(ssn + mrow0 + row, sq);
.LBB0_421:
	ds_read_b128 v[140:143], v69 offset:9792
	v_lshlrev_b32_e32 v134, 16, v116
	v_and_b32_e32 v135, 0xffff0000, v116
	v_lshlrev_b32_e32 v116, 16, v117
	v_and_b32_e32 v117, 0xffff0000, v117
	s_waitcnt lgkmcnt(0)
	v_add_f32_e32 v134, v140, v134
	v_add_f32_e32 v135, v141, v135
	v_add_f32_e32 v140, v142, v116
	v_add_f32_e32 v141, v143, v117
	v_mul_f32_e32 v116, v134, v134
	v_mul_f32_e32 v117, v135, v135
	v_mul_f32_e32 v142, v140, v140
	v_mul_f32_e32 v143, v141, v141
	v_add_f32_e32 v67, v116, v117
	v_add_f32_e32 v67, v142, v67
	v_add_f32_e32 v67, v143, v67
	s_nop 1
	v_mov_b32_dpp v71, v67 quad_perm:[1,0,3,2] row_mask:0xf bank_mask:0xf
	v_or_b32_e32 v116, 36, v183
	v_cvt_pk_bf16_f32 v134, v134, v135
	v_cvt_pk_bf16_f32 v135, v140, v141
	v_lshlrev_b32_e32 v140, 11, v116
	s_waitcnt lgkmcnt(0)
	v_add_f32_e32 v67, v67, v71
	s_nop 1
	v_mov_b32_dpp v71, v67 quad_perm:[2,3,0,1] row_mask:0xf bank_mask:0xf
	v_mov_b32_e32 v141, v1
	v_lshl_add_u64 v[140:141], v[110:111], 0, v[140:141]
	global_store_dwordx2 v[140:141], v[134:135], off sc1
	s_waitcnt lgkmcnt(0)
	v_add_f32_e32 v67, v67, v71
	s_nop 1
	v_mov_b32_dpp v71, v67 row_half_mirror row_mask:0xf bank_mask:0xf
	s_waitcnt lgkmcnt(0)
	v_add_f32_e32 v67, v67, v71
	s_nop 1
	v_mov_b32_dpp v71, v67 row_mirror row_mask:0xf bank_mask:0xf
	v_add_f32_e32 v146, v67, v71
	v_cmp_eq_u32_e64 s[4:5], 9, v180
	s_nop 1
	v_cndmask_b32_e64 v147, v147, v146, s[4:5]
.LBB0_423:
	ds_read_b128 v[140:143], v69 offset:10880
	v_lshlrev_b32_e32 v134, 16, v114
	v_and_b32_e32 v135, 0xffff0000, v114
	v_lshlrev_b32_e32 v114, 16, v115
	v_and_b32_e32 v115, 0xffff0000, v115
	s_waitcnt lgkmcnt(0)
	v_add_f32_e32 v134, v140, v134
	v_add_f32_e32 v135, v141, v135
	v_add_f32_e32 v140, v142, v114
	v_add_f32_e32 v141, v143, v115
	v_mul_f32_e32 v114, v134, v134
	v_mul_f32_e32 v115, v135, v135
	v_mul_f32_e32 v142, v140, v140
	v_mul_f32_e32 v143, v141, v141
	v_add_f32_e32 v67, v114, v115
	v_add_f32_e32 v67, v142, v67
	v_add_f32_e32 v67, v143, v67
	s_nop 1
	v_mov_b32_dpp v71, v67 quad_perm:[1,0,3,2] row_mask:0xf bank_mask:0xf
	v_or_b32_e32 v114, 40, v183
	v_cvt_pk_bf16_f32 v134, v134, v135
	v_cvt_pk_bf16_f32 v135, v140, v141
	v_lshlrev_b32_e32 v140, 11, v114
	s_waitcnt lgkmcnt(0)
	v_add_f32_e32 v67, v67, v71
	s_nop 1
	v_mov_b32_dpp v71, v67 quad_perm:[2,3,0,1] row_mask:0xf bank_mask:0xf
	v_mov_b32_e32 v141, v1
	v_lshl_add_u64 v[140:141], v[110:111], 0, v[140:141]
	global_store_dwordx2 v[140:141], v[134:135], off sc1
	s_waitcnt lgkmcnt(0)
	v_add_f32_e32 v67, v67, v71
	s_nop 1
	v_mov_b32_dpp v71, v67 row_half_mirror row_mask:0xf bank_mask:0xf
	s_waitcnt lgkmcnt(0)
	v_add_f32_e32 v67, v67, v71
	s_nop 1
	v_mov_b32_dpp v71, v67 row_mirror row_mask:0xf bank_mask:0xf
	v_add_f32_e32 v146, v67, v71
	v_cmp_eq_u32_e64 s[4:5], 10, v180
	s_nop 1
	v_cndmask_b32_e64 v147, v147, v146, s[4:5]
.LBB0_425:
	ds_read_b128 v[140:143], v69 offset:11968
	v_lshlrev_b32_e32 v134, 16, v112
	v_and_b32_e32 v135, 0xffff0000, v112
	v_lshlrev_b32_e32 v112, 16, v113
	v_and_b32_e32 v113, 0xffff0000, v113
	s_waitcnt lgkmcnt(0)
	v_add_f32_e32 v134, v140, v134
	v_add_f32_e32 v135, v141, v135
	v_add_f32_e32 v140, v142, v112
	v_add_f32_e32 v141, v143, v113
	v_mul_f32_e32 v112, v134, v134
	v_mul_f32_e32 v113, v135, v135
	v_mul_f32_e32 v142, v140, v140
	v_mul_f32_e32 v143, v141, v141
	v_add_f32_e32 v67, v112, v113
	v_add_f32_e32 v67, v142, v67
	v_add_f32_e32 v67, v143, v67
	s_nop 1
	v_mov_b32_dpp v71, v67 quad_perm:[1,0,3,2] row_mask:0xf bank_mask:0xf
	v_or_b32_e32 v112, 44, v183
	v_cvt_pk_bf16_f32 v134, v134, v135
	v_cvt_pk_bf16_f32 v135, v140, v141
	v_lshlrev_b32_e32 v140, 11, v112
	s_waitcnt lgkmcnt(0)
	v_add_f32_e32 v67, v67, v71
	s_nop 1
	v_mov_b32_dpp v71, v67 quad_perm:[2,3,0,1] row_mask:0xf bank_mask:0xf
	v_mov_b32_e32 v141, v1
	v_lshl_add_u64 v[140:141], v[110:111], 0, v[140:141]
	global_store_dwordx2 v[140:141], v[134:135], off sc1
	s_waitcnt lgkmcnt(0)
	v_add_f32_e32 v67, v67, v71
	s_nop 1
	v_mov_b32_dpp v71, v67 row_half_mirror row_mask:0xf bank_mask:0xf
	s_waitcnt lgkmcnt(0)
	v_add_f32_e32 v67, v67, v71
	s_nop 1
	v_mov_b32_dpp v71, v67 row_mirror row_mask:0xf bank_mask:0xf
	v_add_f32_e32 v146, v67, v71
	v_cmp_eq_u32_e64 s[4:5], 11, v180
	s_nop 1
	v_cndmask_b32_e64 v147, v147, v146, s[4:5]
.LBB0_427:
	ds_read_b128 v[140:143], v69 offset:13056
	v_lshlrev_b32_e32 v134, 16, v108
	v_and_b32_e32 v135, 0xffff0000, v108
	v_lshlrev_b32_e32 v108, 16, v109
	v_and_b32_e32 v109, 0xffff0000, v109
	s_waitcnt lgkmcnt(0)
	v_add_f32_e32 v134, v140, v134
	v_add_f32_e32 v135, v141, v135
	v_add_f32_e32 v140, v142, v108
	v_add_f32_e32 v141, v143, v109
	v_mul_f32_e32 v108, v134, v134
	v_mul_f32_e32 v109, v135, v135
	v_mul_f32_e32 v142, v140, v140
	v_mul_f32_e32 v143, v141, v141
	v_add_f32_e32 v67, v108, v109
	v_add_f32_e32 v67, v142, v67
	v_add_f32_e32 v67, v143, v67
	s_nop 1
	v_mov_b32_dpp v71, v67 quad_perm:[1,0,3,2] row_mask:0xf bank_mask:0xf
	v_or_b32_e32 v108, 48, v183
	v_cvt_pk_bf16_f32 v134, v134, v135
	v_cvt_pk_bf16_f32 v135, v140, v141
	v_lshlrev_b32_e32 v140, 11, v108
	s_waitcnt lgkmcnt(0)
	v_add_f32_e32 v67, v67, v71
	s_nop 1
	v_mov_b32_dpp v71, v67 quad_perm:[2,3,0,1] row_mask:0xf bank_mask:0xf
	v_mov_b32_e32 v141, v1
	v_lshl_add_u64 v[140:141], v[110:111], 0, v[140:141]
	global_store_dwordx2 v[140:141], v[134:135], off sc1
	s_waitcnt lgkmcnt(0)
	v_add_f32_e32 v67, v67, v71
	s_nop 1
	v_mov_b32_dpp v71, v67 row_half_mirror row_mask:0xf bank_mask:0xf
	s_waitcnt lgkmcnt(0)
	v_add_f32_e32 v67, v67, v71
	s_nop 1
	v_mov_b32_dpp v71, v67 row_mirror row_mask:0xf bank_mask:0xf
	v_add_f32_e32 v146, v67, v71
	v_cmp_eq_u32_e64 s[4:5], 12, v180
	s_nop 1
	v_cndmask_b32_e64 v147, v147, v146, s[4:5]
; DI float bflo(unsigned v) { return __uint_as_float(v << 16); }
; DI float bfhi(unsigned v) { return __uint_as_float(v & 0xffff0000u); }
; template <int EPI>
; DI void gemm_tile(const Params& p, int layer, int mt, int nt, u16* sm, int wv) {
;     ...
;       for (int t = 0; t < 16; ++t) {
;         const int row = (lane >> 4) + 4 * t;
;         const f32x4 a4 = *(const f32x4*)(stg + row * 68 + kc * 4);
;         const float v0 = bflo(xb[t][0]) + a4[0], v1 = bfhi(xb[t][0]) + a4[1], v2 = bflo(xb[t][1]) + a4[2], v3 = bfhi(xb[t][1]) + a4[3];
;         float sq = v0 * v0 + v1 * v1 + v2 * v2 + v3 * v3;
;         u32x2 pv = {pk2(v0, v1), pk2(v2, v3)};
;         if (has_next) *(u32x2*)(xrow + (size_t)row * DM) = pv;
;         else *(u32x2*)(x2row + (size_t)row * DM) = pv;
;         sq += shx(sq, lane, 1); sq += shx(sq, lane, 2); sq += shx(sq, lane, 4); sq += shx(sq, lane, 8);
;         if (kc == 0) atomicAdd(ssn + mrow0 + row, sq);
.LBB0_429:
	ds_read_b128 v[140:143], v69 offset:14144
	s_waitcnt vmcnt(14)
	v_lshlrev_b32_e32 v134, 16, v106
	v_and_b32_e32 v135, 0xffff0000, v106
	v_lshlrev_b32_e32 v106, 16, v107
	v_and_b32_e32 v107, 0xffff0000, v107
	s_waitcnt lgkmcnt(0)
	v_add_f32_e32 v134, v140, v134
	v_add_f32_e32 v135, v141, v135
	v_add_f32_e32 v140, v142, v106
	v_add_f32_e32 v141, v143, v107
	v_mul_f32_e32 v106, v134, v134
	v_mul_f32_e32 v107, v135, v135
	v_mul_f32_e32 v142, v140, v140
	v_mul_f32_e32 v143, v141, v141
	v_add_f32_e32 v67, v106, v107
	v_add_f32_e32 v67, v142, v67
	v_add_f32_e32 v67, v143, v67
	s_nop 1
	v_mov_b32_dpp v71, v67 quad_perm:[1,0,3,2] row_mask:0xf bank_mask:0xf
	v_or_b32_e32 v106, 52, v183
	v_cvt_pk_bf16_f32 v134, v134, v135
	v_cvt_pk_bf16_f32 v135, v140, v141
	v_lshlrev_b32_e32 v140, 11, v106
	s_waitcnt lgkmcnt(0)
	v_add_f32_e32 v67, v67, v71
	s_nop 1
	v_mov_b32_dpp v71, v67 quad_perm:[2,3,0,1] row_mask:0xf bank_mask:0xf
	v_mov_b32_e32 v141, v1
	v_lshl_add_u64 v[140:141], v[110:111], 0, v[140:141]
	global_store_dwordx2 v[140:141], v[134:135], off sc1
	s_waitcnt lgkmcnt(0)
	v_add_f32_e32 v67, v67, v71
	s_nop 1
	v_mov_b32_dpp v71, v67 row_half_mirror row_mask:0xf bank_mask:0xf
	s_waitcnt lgkmcnt(0)
	v_add_f32_e32 v67, v67, v71
	s_nop 1
	v_mov_b32_dpp v71, v67 row_mirror row_mask:0xf bank_mask:0xf
	v_add_f32_e32 v146, v67, v71
	v_cmp_eq_u32_e64 s[4:5], 13, v180
	s_nop 1
	v_cndmask_b32_e64 v147, v147, v146, s[4:5]
.LBB0_431:
	ds_read_b128 v[140:143], v69 offset:15232
	s_waitcnt vmcnt(14)
	v_lshlrev_b32_e32 v134, 16, v102
	v_and_b32_e32 v135, 0xffff0000, v102
	v_lshlrev_b32_e32 v102, 16, v103
	v_and_b32_e32 v103, 0xffff0000, v103
	s_waitcnt lgkmcnt(0)
	v_add_f32_e32 v134, v140, v134
	v_add_f32_e32 v135, v141, v135
	v_add_f32_e32 v140, v142, v102
	v_add_f32_e32 v141, v143, v103
	v_mul_f32_e32 v102, v134, v134
	v_mul_f32_e32 v103, v135, v135
	v_mul_f32_e32 v142, v140, v140
	v_mul_f32_e32 v143, v141, v141
	v_add_f32_e32 v67, v102, v103
	v_add_f32_e32 v67, v142, v67
	v_add_f32_e32 v67, v143, v67
	s_nop 1
	v_mov_b32_dpp v71, v67 quad_perm:[1,0,3,2] row_mask:0xf bank_mask:0xf
	v_or_b32_e32 v103, 56, v183
	v_cvt_pk_bf16_f32 v134, v134, v135
	v_cvt_pk_bf16_f32 v135, v140, v141
	v_lshlrev_b32_e32 v140, 11, v103
	s_waitcnt lgkmcnt(0)
	v_add_f32_e32 v67, v67, v71
	s_nop 1
	v_mov_b32_dpp v71, v67 quad_perm:[2,3,0,1] row_mask:0xf bank_mask:0xf
	v_mov_b32_e32 v141, v1
	v_lshl_add_u64 v[140:141], v[110:111], 0, v[140:141]
	global_store_dwordx2 v[140:141], v[134:135], off sc1
	s_waitcnt lgkmcnt(0)
	v_add_f32_e32 v67, v67, v71
	s_nop 1
	v_mov_b32_dpp v71, v67 row_half_mirror row_mask:0xf bank_mask:0xf
	s_waitcnt lgkmcnt(0)
	v_add_f32_e32 v67, v67, v71
	s_nop 1
	v_mov_b32_dpp v71, v67 row_mirror row_mask:0xf bank_mask:0xf
	v_add_f32_e32 v146, v67, v71
	v_cmp_eq_u32_e64 s[4:5], 14, v180
	s_nop 1
	v_cndmask_b32_e64 v147, v147, v146, s[4:5]
.LBB0_433:
	ds_read_b128 v[140:143], v69 offset:16320
	s_waitcnt vmcnt(14)
	v_lshlrev_b32_e32 v134, 16, v100
	v_and_b32_e32 v135, 0xffff0000, v100
	v_lshlrev_b32_e32 v100, 16, v101
	v_and_b32_e32 v101, 0xffff0000, v101
	s_waitcnt lgkmcnt(0)
	v_add_f32_e32 v134, v140, v134
	v_add_f32_e32 v135, v141, v135
	v_add_f32_e32 v100, v142, v100
	v_add_f32_e32 v101, v143, v101
	v_mul_f32_e32 v140, v134, v134
	v_mul_f32_e32 v141, v135, v135
	v_mul_f32_e32 v142, v100, v100
	v_mul_f32_e32 v143, v101, v101
	v_add_f32_e32 v67, v140, v141
	v_add_f32_e32 v67, v142, v67
	v_add_f32_e32 v67, v143, v67
	s_nop 1
	v_mov_b32_dpp v71, v67 quad_perm:[1,0,3,2] row_mask:0xf bank_mask:0xf
	v_or_b32_e32 v102, 60, v183
	v_cvt_pk_bf16_f32 v134, v134, v135
	v_cvt_pk_bf16_f32 v135, v100, v101
	v_lshlrev_b32_e32 v100, 11, v102
	s_waitcnt lgkmcnt(0)
	v_add_f32_e32 v67, v67, v71
	s_nop 1
	v_mov_b32_dpp v71, v67 quad_perm:[2,3,0,1] row_mask:0xf bank_mask:0xf
	v_mov_b32_e32 v101, v1
	v_lshl_add_u64 v[100:101], v[110:111], 0, v[100:101]
	global_store_dwordx2 v[100:101], v[134:135], off sc1
	s_waitcnt lgkmcnt(0)
	v_add_f32_e32 v67, v67, v71
	s_nop 1
	v_mov_b32_dpp v71, v67 row_half_mirror row_mask:0xf bank_mask:0xf
	s_waitcnt lgkmcnt(0)
	v_add_f32_e32 v67, v67, v71
	s_nop 1
	v_mov_b32_dpp v71, v67 row_mirror row_mask:0xf bank_mask:0xf
	v_add_f32_e32 v146, v67, v71
	v_cmp_eq_u32_e64 s[4:5], 15, v180
	s_nop 1
	v_cndmask_b32_e64 v147, v147, v146, s[4:5]
; DI float bflo(unsigned v) { return __uint_as_float(v << 16); }
; DI float bfhi(unsigned v) { return __uint_as_float(v & 0xffff0000u); }
; template <int EPI>
; DI void gemm_tile(const Params& p, int layer, int mt, int nt, u16* sm, int wv) {
;     ...
; #pragma unroll
;     for (int hh = 0; hh < 2; ++hh) {
; #pragma unroll
;       for (int i2 = 0; i2 < 4; ++i2)
; #pragma unroll
;         for (int j = 0; j < 4; ++j)
;           *(f32x4*)(stg + (16 * i2 + fr) * 68 + 16 * j + 4 * fq) = acc[4 * hh + i2][j];
;       const size_t mrow0 = (size_t)(m0 + wm * 128 + 64 * hh);
;       u16* xrow = p.xg + mrow0 * DM + n0 + wn * 64 + kc * 4;
;       u16* x2row = (u16*)p.x2 + mrow0 * DM + n0 + wn * 64 + kc * 4;
;       u32x2 xb[16];
; #pragma unroll
;       for (int t = 0; t < 16; ++t) xb[t] = __builtin_nontemporal_load((const u32x2*)(xrow + (size_t)((lane >> 4) + 4 * t) * DM));
; #pragma unroll
;       for (int t = 0; t < 16; ++t) {
;         const int row = (lane >> 4) + 4 * t;
;         const f32x4 a4 = *(const f32x4*)(stg + row * 68 + kc * 4);
;         const float v0 = bflo(xb[t][0]) + a4[0], v1 = bfhi(xb[t][0]) + a4[1], v2 = bflo(xb[t][1]) + a4[2], v3 = bfhi(xb[t][1]) + a4[3];
;         float sq = v0 * v0 + v1 * v1 + v2 * v2 + v3 * v3;
;         u32x2 pv = {pk2(v0, v1), pk2(v2, v3)};
;         if (has_next) *(u32x2*)(xrow + (size_t)row * DM) = pv;
;         else *(u32x2*)(x2row + (size_t)row * DM) = pv;
;         sq += shx(sq, lane, 1); sq += shx(sq, lane, 2); sq += shx(sq, lane, 4); sq += shx(sq, lane, 8);
;         if (kc == 0) atomicAdd(ssn + mrow0 + row, sq);
.LBB0_435:
	v_lshl_add_u32 v148, v180, 4, v66
	v_mov_b32_e32 v149, v1
	v_lshl_add_u64 v[148:149], v[104:105], 0, v[148:149]
	global_atomic_add_f32 v[148:149], v147, off
	v_mul_u32_u24_e32 v73, 0x110, v180
	v_add_u32_e32 v73, v182, v73
	ds_write_b128 v73, v[62:65]
	ds_write_b128 v73, v[58:61] offset:64
	ds_write_b128 v73, v[54:57] offset:128
	ds_write_b128 v73, v[50:53] offset:192
	ds_write_b128 v73, v[46:49] offset:4352
	ds_write_b128 v73, v[42:45] offset:4416
	ds_write_b128 v73, v[38:41] offset:4480
	ds_write_b128 v73, v[34:37] offset:4544
	ds_write_b128 v73, v[30:33] offset:8704
	ds_write_b128 v73, v[26:29] offset:8768
	ds_write_b128 v73, v[22:25] offset:8832
	ds_write_b128 v73, v[18:21] offset:8896
	ds_write_b128 v73, v[10:13] offset:13056
	ds_write_b128 v73, v[6:9] offset:13120
	ds_write_b128 v73, v[2:5] offset:13184
	ds_write_b128 v73, v[14:17] offset:13248
	v_or_b32_e32 v4, 64, v68
	v_ashrrev_i32_e32 v5, 31, v4
	v_lshlrev_b64 v[2:3], 11, v[4:5]
	v_lshlrev_b32_e32 v67, 6, v181
	v_lshl_add_u64 v[6:7], s[60:61], 0, v[2:3]
	s_waitcnt lgkmcnt(14)
	v_lshlrev_b32_e32 v71, 2, v180
	v_lshl_add_u64 v[6:7], v[6:7], 0, s[2:3]
	v_lshlrev_b32_e32 v8, 1, v67
	v_mov_b32_e32 v9, v1
	v_lshl_add_u64 v[6:7], v[6:7], 0, v[8:9]
	v_lshlrev_b32_e32 v38, 1, v71
	v_mov_b32_e32 v39, v1
	v_lshl_add_u64 v[2:3], s[82:83], 0, v[2:3]
	v_lshl_add_u64 v[10:11], v[6:7], 0, v[38:39]
	v_lshl_add_u64 v[2:3], v[2:3], 0, s[2:3]
	v_mov_b32_e32 v71, v1
	v_lshl_add_u64 v[40:41], v[2:3], 0, v[8:9]
	v_lshl_add_u64 v[2:3], v[10:11], 0, v[70:71]
	v_mov_b32_e32 v73, v1
	global_load_dwordx2 v[34:35], v[2:3], off nt
	v_lshl_add_u64 v[2:3], v[10:11], 0, v[72:73]
	v_mov_b32_e32 v75, v1
	global_load_dwordx2 v[32:33], v[2:3], off nt
	v_lshl_add_u64 v[2:3], v[10:11], 0, v[74:75]
	v_mov_b32_e32 v81, v1
	global_load_dwordx2 v[30:31], v[2:3], off nt
	v_lshl_add_u64 v[2:3], v[10:11], 0, v[80:81]
	v_mov_b32_e32 v77, v1
	global_load_dwordx2 v[28:29], v[2:3], off nt
	v_lshl_add_u64 v[2:3], v[10:11], 0, v[76:77]
	v_mov_b32_e32 v79, v1
	global_load_dwordx2 v[26:27], v[2:3], off nt
	v_lshl_add_u64 v[2:3], v[10:11], 0, v[78:79]
	v_mov_b32_e32 v83, v1
	global_load_dwordx2 v[24:25], v[2:3], off nt
	v_lshl_add_u64 v[2:3], v[10:11], 0, v[82:83]
	v_mov_b32_e32 v89, v1
	global_load_dwordx2 v[22:23], v[2:3], off nt
	v_lshl_add_u64 v[2:3], v[10:11], 0, v[88:89]
	v_mov_b32_e32 v85, v1
	global_load_dwordx2 v[20:21], v[2:3], off nt
	v_lshl_add_u64 v[2:3], v[10:11], 0, v[84:85]
	v_mov_b32_e32 v87, v1
	global_load_dwordx2 v[18:19], v[2:3], off nt
	v_lshl_add_u64 v[2:3], v[10:11], 0, v[86:87]
	v_mov_b32_e32 v91, v1
	global_load_dwordx2 v[16:17], v[2:3], off nt
	v_lshl_add_u64 v[2:3], v[10:11], 0, v[90:91]
	v_mov_b32_e32 v97, v1
	v_lshl_add_u64 v[36:37], v[10:11], 0, v[0:1]
	global_load_dwordx2 v[14:15], v[2:3], off nt
	v_lshl_add_u64 v[2:3], v[10:11], 0, v[96:97]
	v_mov_b32_e32 v93, v1
	global_load_dwordx2 v[44:45], v[36:37], off nt
	global_load_dwordx2 v[12:13], v[2:3], off nt
	v_lshl_add_u64 v[2:3], v[10:11], 0, v[92:93]
	v_mov_b32_e32 v95, v1
	global_load_dwordx2 v[8:9], v[2:3], off nt
	v_lshl_add_u64 v[2:3], v[10:11], 0, v[94:95]
	v_mov_b32_e32 v99, v1
	global_load_dwordx2 v[6:7], v[2:3], off nt
	v_lshl_add_u64 v[2:3], v[10:11], 0, v[98:99]
	global_load_dwordx2 v[2:3], v[2:3], off nt
	v_lshl_add_u64 v[38:39], v[40:41], 0, v[38:39]
	ds_read_b128 v[40:43], v69
	s_mov_b64 s[2:3], -1
	s_andn2_b64 vcc, exec, s[70:71]
	s_waitcnt vmcnt(4)
	v_lshlrev_b32_e32 v46, 16, v44
	v_and_b32_e32 v47, 0xffff0000, v44
	v_lshlrev_b32_e32 v44, 16, v45
	v_and_b32_e32 v45, 0xffff0000, v45
	s_waitcnt lgkmcnt(0)
	v_add_f32_e32 v40, v40, v46
	v_add_f32_e32 v41, v41, v47
	v_add_f32_e32 v42, v42, v44
	v_add_f32_e32 v43, v43, v45
	v_cvt_pk_bf16_f32 v44, v40, v41
	v_cvt_pk_bf16_f32 v45, v42, v43
	s_cbranch_vccnz .LBB0_437
	v_lshl_add_u64 v[46:47], v[38:39], 0, v[0:1]
	s_mov_b64 s[2:3], 0
	global_store_dwordx2 v[46:47], v[44:45], off sc1
.LBB0_437:
	s_andn2_b64 vcc, exec, s[2:3]
	s_cbranch_vccnz .LBB0_439
	global_store_dwordx2 v[36:37], v[44:45], off sc1

; DI float bflo(unsigned v) { return __uint_as_float(v << 16); }
; DI float bfhi(unsigned v) { return __uint_as_float(v & 0xffff0000u); }
; template <int EPI>
; DI void gemm_tile(const Params& p, int layer, int mt, int nt, u16* sm, int wv) {
;     ...
;       for (int t = 0; t < 16; ++t) {
;         const int row = (lane >> 4) + 4 * t;
;         const f32x4 a4 = *(const f32x4*)(stg + row * 68 + kc * 4);
;         const float v0 = bflo(xb[t][0]) + a4[0], v1 = bfhi(xb[t][0]) + a4[1], v2 = bflo(xb[t][1]) + a4[2], v3 = bfhi(xb[t][1]) + a4[3];
;         float sq = v0 * v0 + v1 * v1 + v2 * v2 + v3 * v3;
;         u32x2 pv = {pk2(v0, v1), pk2(v2, v3)};
;         if (has_next) *(u32x2*)(xrow + (size_t)row * DM) = pv;
;         else *(u32x2*)(x2row + (size_t)row * DM) = pv;
;         sq += shx(sq, lane, 1); sq += shx(sq, lane, 2); sq += shx(sq, lane, 4); sq += shx(sq, lane, 8);
;         if (kc == 0) atomicAdd(ssn + mrow0 + row, sq);
.LBB0_441:
	ds_read_b128 v[40:43], v69 offset:1088
	s_waitcnt lgkmcnt(1)
	v_lshlrev_b32_e32 v36, 16, v34
	v_and_b32_e32 v37, 0xffff0000, v34
	v_lshlrev_b32_e32 v34, 16, v35
	v_and_b32_e32 v35, 0xffff0000, v35
	s_waitcnt lgkmcnt(0)
	v_add_f32_e32 v36, v40, v36
	v_add_f32_e32 v37, v41, v37
	v_add_f32_e32 v34, v42, v34
	v_add_f32_e32 v35, v43, v35
	v_mul_f32_e32 v40, v36, v36
	v_mul_f32_e32 v41, v37, v37
	v_mul_f32_e32 v42, v34, v34
	v_mul_f32_e32 v43, v35, v35
	v_add_f32_e32 v40, v40, v41
	v_lshlrev_b32_e32 v0, 10, v132
	v_add_f32_e32 v40, v42, v40
	v_add_f32_e32 v40, v43, v40
	v_cndmask_b32_e64 v11, v39, v11, s[34:35]
	v_cndmask_b32_e64 v10, v38, v10, s[34:35]
	v_lshlrev_b32_e32 v0, 1, v0
	v_cvt_pk_bf16_f32 v36, v36, v37
	v_cvt_pk_bf16_f32 v37, v34, v35
	v_lshl_add_u64 v[34:35], v[10:11], 0, v[0:1]
	s_nop 1
	v_mov_b32_dpp v0, v40 quad_perm:[1,0,3,2] row_mask:0xf bank_mask:0xf
	global_store_dwordx2 v[34:35], v[36:37], off sc1
	v_lshl_add_u64 v[4:5], v[4:5], 2, s[0:1]
	s_waitcnt lgkmcnt(0)
	v_add_f32_e32 v0, v40, v0
	s_nop 1
	v_mov_b32_dpp v34, v0 quad_perm:[2,3,0,1] row_mask:0xf bank_mask:0xf
	s_waitcnt lgkmcnt(0)
	v_add_f32_e32 v0, v0, v34
	s_nop 1
	v_mov_b32_dpp v34, v0 row_half_mirror row_mask:0xf bank_mask:0xf
	s_waitcnt lgkmcnt(0)
	v_add_f32_e32 v0, v0, v34
	s_nop 1
	v_mov_b32_dpp v34, v0 row_mirror row_mask:0xf bank_mask:0xf
	v_add_f32_e32 v146, v0, v34
	v_cmp_eq_u32_e64 s[2:3], 1, v180
	s_nop 1
	v_cndmask_b32_e64 v147, v147, v146, s[2:3]
.LBB0_443:
	s_waitcnt lgkmcnt(0)
	ds_read_b128 v[34:37], v69 offset:2176
	v_lshlrev_b32_e32 v38, 16, v32
	v_and_b32_e32 v39, 0xffff0000, v32
	v_lshlrev_b32_e32 v32, 16, v33
	v_and_b32_e32 v33, 0xffff0000, v33
	s_waitcnt lgkmcnt(0)
	v_add_f32_e32 v34, v34, v38
	v_add_f32_e32 v35, v35, v39
	v_add_f32_e32 v32, v36, v32
	v_add_f32_e32 v33, v37, v33
	v_mul_f32_e32 v36, v34, v34
	v_mul_f32_e32 v37, v35, v35
	v_mul_f32_e32 v38, v32, v32
	v_mul_f32_e32 v39, v33, v33
	v_add_f32_e32 v36, v36, v37
	v_lshlrev_b32_e32 v0, 10, v130
	v_add_f32_e32 v36, v38, v36
	v_add_f32_e32 v36, v39, v36
	v_lshlrev_b32_e32 v0, 1, v0
	v_cvt_pk_bf16_f32 v34, v34, v35
	v_cvt_pk_bf16_f32 v35, v32, v33
	v_lshl_add_u64 v[32:33], v[10:11], 0, v[0:1]
	s_nop 1
	v_mov_b32_dpp v0, v36 quad_perm:[1,0,3,2] row_mask:0xf bank_mask:0xf
	global_store_dwordx2 v[32:33], v[34:35], off sc1
	s_waitcnt lgkmcnt(0)
	v_add_f32_e32 v0, v36, v0
	s_nop 1
	v_mov_b32_dpp v32, v0 quad_perm:[2,3,0,1] row_mask:0xf bank_mask:0xf
	s_waitcnt lgkmcnt(0)
	v_add_f32_e32 v0, v0, v32
	s_nop 1
	v_mov_b32_dpp v32, v0 row_half_mirror row_mask:0xf bank_mask:0xf
	s_waitcnt lgkmcnt(0)
	v_add_f32_e32 v0, v0, v32
	s_nop 1
	v_mov_b32_dpp v32, v0 row_mirror row_mask:0xf bank_mask:0xf
	v_add_f32_e32 v146, v0, v32
	v_cmp_eq_u32_e64 s[2:3], 2, v180
	s_nop 1
	v_cndmask_b32_e64 v147, v147, v146, s[2:3]
.LBB0_445:
	s_waitcnt lgkmcnt(0)
	ds_read_b128 v[32:35], v69 offset:3264
	v_lshlrev_b32_e32 v36, 16, v30
	v_and_b32_e32 v37, 0xffff0000, v30
	v_lshlrev_b32_e32 v30, 16, v31
	v_and_b32_e32 v31, 0xffff0000, v31
	s_waitcnt lgkmcnt(0)
	v_add_f32_e32 v32, v32, v36
	v_add_f32_e32 v33, v33, v37
	v_add_f32_e32 v30, v34, v30
	v_add_f32_e32 v31, v35, v31
	v_mul_f32_e32 v34, v32, v32
	v_mul_f32_e32 v35, v33, v33
	v_mul_f32_e32 v36, v30, v30
	v_mul_f32_e32 v37, v31, v31
	v_add_f32_e32 v34, v34, v35
	v_lshlrev_b32_e32 v0, 10, v128
	v_add_f32_e32 v34, v36, v34
	v_add_f32_e32 v34, v37, v34
	v_lshlrev_b32_e32 v0, 1, v0
	v_cvt_pk_bf16_f32 v32, v32, v33
	v_cvt_pk_bf16_f32 v33, v30, v31
	v_lshl_add_u64 v[30:31], v[10:11], 0, v[0:1]
	s_nop 1
	v_mov_b32_dpp v0, v34 quad_perm:[1,0,3,2] row_mask:0xf bank_mask:0xf
	global_store_dwordx2 v[30:31], v[32:33], off sc1
	s_waitcnt lgkmcnt(0)
	v_add_f32_e32 v0, v34, v0
	s_nop 1
	v_mov_b32_dpp v30, v0 quad_perm:[2,3,0,1] row_mask:0xf bank_mask:0xf
	s_waitcnt lgkmcnt(0)
	v_add_f32_e32 v0, v0, v30
	s_nop 1
	v_mov_b32_dpp v30, v0 row_half_mirror row_mask:0xf bank_mask:0xf
	s_waitcnt lgkmcnt(0)
	v_add_f32_e32 v0, v0, v30
	s_nop 1
	v_mov_b32_dpp v30, v0 row_mirror row_mask:0xf bank_mask:0xf
	v_add_f32_e32 v146, v0, v30
	v_cmp_eq_u32_e64 s[2:3], 3, v180
	s_nop 1
	v_cndmask_b32_e64 v147, v147, v146, s[2:3]
.LBB0_447:
	s_waitcnt lgkmcnt(0)
	ds_read_b128 v[30:33], v69 offset:4352
	v_lshlrev_b32_e32 v34, 16, v28
	v_and_b32_e32 v35, 0xffff0000, v28
	v_lshlrev_b32_e32 v28, 16, v29
	v_and_b32_e32 v29, 0xffff0000, v29
	s_waitcnt lgkmcnt(0)
	v_add_f32_e32 v30, v30, v34
	v_add_f32_e32 v31, v31, v35
	v_add_f32_e32 v28, v32, v28
	v_add_f32_e32 v29, v33, v29
	v_mul_f32_e32 v32, v30, v30
	v_mul_f32_e32 v33, v31, v31
	v_mul_f32_e32 v34, v28, v28
	v_mul_f32_e32 v35, v29, v29
	v_add_f32_e32 v32, v32, v33
	v_lshlrev_b32_e32 v0, 10, v126
	v_add_f32_e32 v32, v34, v32
	v_add_f32_e32 v32, v35, v32
	v_lshlrev_b32_e32 v0, 1, v0
	v_cvt_pk_bf16_f32 v30, v30, v31
	v_cvt_pk_bf16_f32 v31, v28, v29
	v_lshl_add_u64 v[28:29], v[10:11], 0, v[0:1]
	s_nop 1
	v_mov_b32_dpp v0, v32 quad_perm:[1,0,3,2] row_mask:0xf bank_mask:0xf
	global_store_dwordx2 v[28:29], v[30:31], off sc1
	s_waitcnt lgkmcnt(0)
	v_add_f32_e32 v0, v32, v0
	s_nop 1
	v_mov_b32_dpp v28, v0 quad_perm:[2,3,0,1] row_mask:0xf bank_mask:0xf
	s_waitcnt lgkmcnt(0)
	v_add_f32_e32 v0, v0, v28
	s_nop 1
	v_mov_b32_dpp v28, v0 row_half_mirror row_mask:0xf bank_mask:0xf
	s_waitcnt lgkmcnt(0)
	v_add_f32_e32 v0, v0, v28
	s_nop 1
	v_mov_b32_dpp v28, v0 row_mirror row_mask:0xf bank_mask:0xf
	v_add_f32_e32 v146, v0, v28
	v_cmp_eq_u32_e64 s[2:3], 4, v180
	s_nop 1
	v_cndmask_b32_e64 v147, v147, v146, s[2:3]
; DI float bflo(unsigned v) { return __uint_as_float(v << 16); }
; DI float bfhi(unsigned v) { return __uint_as_float(v & 0xffff0000u); }
; template <int EPI>
; DI void gemm_tile(const Params& p, int layer, int mt, int nt, u16* sm, int wv) {
;     ...
;       for (int t = 0; t < 16; ++t) {
;         const int row = (lane >> 4) + 4 * t;
;         const f32x4 a4 = *(const f32x4*)(stg + row * 68 + kc * 4);
;         const float v0 = bflo(xb[t][0]) + a4[0], v1 = bfhi(xb[t][0]) + a4[1], v2 = bflo(xb[t][1]) + a4[2], v3 = bfhi(xb[t][1]) + a4[3];
;         float sq = v0 * v0 + v1 * v1 + v2 * v2 + v3 * v3;
;         u32x2 pv = {pk2(v0, v1), pk2(v2, v3)};
;         if (has_next) *(u32x2*)(xrow + (size_t)row * DM) = pv;
;         else *(u32x2*)(x2row + (size_t)row * DM) = pv;
;         sq += shx(sq, lane, 1); sq += shx(sq, lane, 2); sq += shx(sq, lane, 4); sq += shx(sq, lane, 8);
;         if (kc == 0) atomicAdd(ssn + mrow0 + row, sq);
.LBB0_449:
	s_waitcnt lgkmcnt(0)
	ds_read_b128 v[28:31], v69 offset:5440
	v_lshlrev_b32_e32 v32, 16, v26
	v_and_b32_e32 v33, 0xffff0000, v26
	v_lshlrev_b32_e32 v26, 16, v27
	v_and_b32_e32 v27, 0xffff0000, v27
	s_waitcnt lgkmcnt(0)
	v_add_f32_e32 v28, v28, v32
	v_add_f32_e32 v29, v29, v33
	v_add_f32_e32 v26, v30, v26
	v_add_f32_e32 v27, v31, v27
	v_mul_f32_e32 v30, v28, v28
	v_mul_f32_e32 v31, v29, v29
	v_mul_f32_e32 v32, v26, v26
	v_mul_f32_e32 v33, v27, v27
	v_add_f32_e32 v30, v30, v31
	v_lshlrev_b32_e32 v0, 10, v124
	v_add_f32_e32 v30, v32, v30
	v_add_f32_e32 v30, v33, v30
	v_lshlrev_b32_e32 v0, 1, v0
	v_cvt_pk_bf16_f32 v28, v28, v29
	v_cvt_pk_bf16_f32 v29, v26, v27
	v_lshl_add_u64 v[26:27], v[10:11], 0, v[0:1]
	s_nop 1
	v_mov_b32_dpp v0, v30 quad_perm:[1,0,3,2] row_mask:0xf bank_mask:0xf
	global_store_dwordx2 v[26:27], v[28:29], off sc1
	s_waitcnt lgkmcnt(0)
	v_add_f32_e32 v0, v30, v0
	s_nop 1
	v_mov_b32_dpp v26, v0 quad_perm:[2,3,0,1] row_mask:0xf bank_mask:0xf
	s_waitcnt lgkmcnt(0)
	v_add_f32_e32 v0, v0, v26
	s_nop 1
	v_mov_b32_dpp v26, v0 row_half_mirror row_mask:0xf bank_mask:0xf
	s_waitcnt lgkmcnt(0)
	v_add_f32_e32 v0, v0, v26
	s_nop 1
	v_mov_b32_dpp v26, v0 row_mirror row_mask:0xf bank_mask:0xf
	v_add_f32_e32 v146, v0, v26
	v_cmp_eq_u32_e64 s[2:3], 5, v180
	s_nop 1
	v_cndmask_b32_e64 v147, v147, v146, s[2:3]
.LBB0_451:
	s_waitcnt lgkmcnt(0)
	ds_read_b128 v[26:29], v69 offset:6528
	v_lshlrev_b32_e32 v30, 16, v24
	v_and_b32_e32 v31, 0xffff0000, v24
	v_lshlrev_b32_e32 v24, 16, v25
	v_and_b32_e32 v25, 0xffff0000, v25
	s_waitcnt lgkmcnt(0)
	v_add_f32_e32 v26, v26, v30
	v_add_f32_e32 v27, v27, v31
	v_add_f32_e32 v24, v28, v24
	v_add_f32_e32 v25, v29, v25
	v_mul_f32_e32 v28, v26, v26
	v_mul_f32_e32 v29, v27, v27
	v_mul_f32_e32 v30, v24, v24
	v_mul_f32_e32 v31, v25, v25
	v_add_f32_e32 v28, v28, v29
	v_lshlrev_b32_e32 v0, 10, v122
	v_add_f32_e32 v28, v30, v28
	v_add_f32_e32 v28, v31, v28
	v_lshlrev_b32_e32 v0, 1, v0
	v_cvt_pk_bf16_f32 v26, v26, v27
	v_cvt_pk_bf16_f32 v27, v24, v25
	v_lshl_add_u64 v[24:25], v[10:11], 0, v[0:1]
	s_nop 1
	v_mov_b32_dpp v0, v28 quad_perm:[1,0,3,2] row_mask:0xf bank_mask:0xf
	global_store_dwordx2 v[24:25], v[26:27], off sc1
	s_waitcnt lgkmcnt(0)
	v_add_f32_e32 v0, v28, v0
	s_nop 1
	v_mov_b32_dpp v24, v0 quad_perm:[2,3,0,1] row_mask:0xf bank_mask:0xf
	s_waitcnt lgkmcnt(0)
	v_add_f32_e32 v0, v0, v24
	s_nop 1
	v_mov_b32_dpp v24, v0 row_half_mirror row_mask:0xf bank_mask:0xf
	s_waitcnt lgkmcnt(0)
	v_add_f32_e32 v0, v0, v24
	s_nop 1
	v_mov_b32_dpp v24, v0 row_mirror row_mask:0xf bank_mask:0xf
	v_add_f32_e32 v146, v0, v24
	v_cmp_eq_u32_e64 s[2:3], 6, v180
	s_nop 1
	v_cndmask_b32_e64 v147, v147, v146, s[2:3]
.LBB0_453:
	s_waitcnt lgkmcnt(0)
	ds_read_b128 v[24:27], v69 offset:7616
	v_lshlrev_b32_e32 v28, 16, v22
	v_and_b32_e32 v29, 0xffff0000, v22
	v_lshlrev_b32_e32 v22, 16, v23
	v_and_b32_e32 v23, 0xffff0000, v23
	s_waitcnt lgkmcnt(0)
	v_add_f32_e32 v24, v24, v28
	v_add_f32_e32 v25, v25, v29
	v_add_f32_e32 v22, v26, v22
	v_add_f32_e32 v23, v27, v23
	v_mul_f32_e32 v26, v24, v24
	v_mul_f32_e32 v27, v25, v25
	v_mul_f32_e32 v28, v22, v22
	v_mul_f32_e32 v29, v23, v23
	v_add_f32_e32 v26, v26, v27
	v_lshlrev_b32_e32 v0, 10, v120
	v_add_f32_e32 v26, v28, v26
	v_add_f32_e32 v26, v29, v26
	v_lshlrev_b32_e32 v0, 1, v0
	v_cvt_pk_bf16_f32 v24, v24, v25
	v_cvt_pk_bf16_f32 v25, v22, v23
	v_lshl_add_u64 v[22:23], v[10:11], 0, v[0:1]
	s_nop 1
	v_mov_b32_dpp v0, v26 quad_perm:[1,0,3,2] row_mask:0xf bank_mask:0xf
	global_store_dwordx2 v[22:23], v[24:25], off sc1
	s_waitcnt lgkmcnt(0)
	v_add_f32_e32 v0, v26, v0
	s_nop 1
	v_mov_b32_dpp v22, v0 quad_perm:[2,3,0,1] row_mask:0xf bank_mask:0xf
	s_waitcnt lgkmcnt(0)
	v_add_f32_e32 v0, v0, v22
	s_nop 1
	v_mov_b32_dpp v22, v0 row_half_mirror row_mask:0xf bank_mask:0xf
	s_waitcnt lgkmcnt(0)
	v_add_f32_e32 v0, v0, v22
	s_nop 1
	v_mov_b32_dpp v22, v0 row_mirror row_mask:0xf bank_mask:0xf
	v_add_f32_e32 v146, v0, v22
	v_cmp_eq_u32_e64 s[2:3], 7, v180
	s_nop 1
	v_cndmask_b32_e64 v147, v147, v146, s[2:3]
.LBB0_455:
	s_waitcnt lgkmcnt(0)
	ds_read_b128 v[22:25], v69 offset:8704
	v_lshlrev_b32_e32 v26, 16, v20
	v_and_b32_e32 v27, 0xffff0000, v20
	v_lshlrev_b32_e32 v20, 16, v21
	v_and_b32_e32 v21, 0xffff0000, v21
	s_waitcnt lgkmcnt(0)
	v_add_f32_e32 v22, v22, v26
	v_add_f32_e32 v23, v23, v27
	v_add_f32_e32 v20, v24, v20
	v_add_f32_e32 v21, v25, v21
	v_mul_f32_e32 v24, v22, v22
	v_mul_f32_e32 v25, v23, v23
	v_mul_f32_e32 v26, v20, v20
	v_mul_f32_e32 v27, v21, v21
	v_add_f32_e32 v24, v24, v25
	v_lshlrev_b32_e32 v0, 10, v118
	v_add_f32_e32 v24, v26, v24
	v_add_f32_e32 v24, v27, v24
	v_lshlrev_b32_e32 v0, 1, v0
	v_cvt_pk_bf16_f32 v22, v22, v23
	v_cvt_pk_bf16_f32 v23, v20, v21
	v_lshl_add_u64 v[20:21], v[10:11], 0, v[0:1]
	s_nop 1
	v_mov_b32_dpp v0, v24 quad_perm:[1,0,3,2] row_mask:0xf bank_mask:0xf
	global_store_dwordx2 v[20:21], v[22:23], off sc1
	s_waitcnt lgkmcnt(0)
	v_add_f32_e32 v0, v24, v0
	s_nop 1
	v_mov_b32_dpp v20, v0 quad_perm:[2,3,0,1] row_mask:0xf bank_mask:0xf
	s_waitcnt lgkmcnt(0)
	v_add_f32_e32 v0, v0, v20
	s_nop 1
	v_mov_b32_dpp v20, v0 row_half_mirror row_mask:0xf bank_mask:0xf
	s_waitcnt lgkmcnt(0)
	v_add_f32_e32 v0, v0, v20
	s_nop 1
	v_mov_b32_dpp v20, v0 row_mirror row_mask:0xf bank_mask:0xf
	v_add_f32_e32 v146, v0, v20
	v_cmp_eq_u32_e64 s[2:3], 8, v180
	s_nop 1
	v_cndmask_b32_e64 v147, v147, v146, s[2:3]
; DI float bflo(unsigned v) { return __uint_as_float(v << 16); }
; DI float bfhi(unsigned v) { return __uint_as_float(v & 0xffff0000u); }
; template <int EPI>
; DI void gemm_tile(const Params& p, int layer, int mt, int nt, u16* sm, int wv) {
;     ...
;       for (int t = 0; t < 16; ++t) {
;         const int row = (lane >> 4) + 4 * t;
;         const f32x4 a4 = *(const f32x4*)(stg + row * 68 + kc * 4);
;         const float v0 = bflo(xb[t][0]) + a4[0], v1 = bfhi(xb[t][0]) + a4[1], v2 = bflo(xb[t][1]) + a4[2], v3 = bfhi(xb[t][1]) + a4[3];
;         float sq = v0 * v0 + v1 * v1 + v2 * v2 + v3 * v3;
;         u32x2 pv = {pk2(v0, v1), pk2(v2, v3)};
;         if (has_next) *(u32x2*)(xrow + (size_t)row * DM) = pv;
;         else *(u32x2*)(x2row + (size_t)row * DM) = pv;
;         sq += shx(sq, lane, 1); sq += shx(sq, lane, 2); sq += shx(sq, lane, 4); sq += shx(sq, lane, 8);
;         if (kc == 0) atomicAdd(ssn + mrow0 + row, sq);
.LBB0_457:
	s_waitcnt lgkmcnt(0)
	ds_read_b128 v[20:23], v69 offset:9792
	v_lshlrev_b32_e32 v24, 16, v18
	v_and_b32_e32 v25, 0xffff0000, v18
	v_lshlrev_b32_e32 v18, 16, v19
	v_and_b32_e32 v19, 0xffff0000, v19
	s_waitcnt lgkmcnt(0)
	v_add_f32_e32 v20, v20, v24
	v_add_f32_e32 v21, v21, v25
	v_add_f32_e32 v18, v22, v18
	v_add_f32_e32 v19, v23, v19
	v_mul_f32_e32 v22, v20, v20
	v_mul_f32_e32 v23, v21, v21
	v_mul_f32_e32 v24, v18, v18
	v_mul_f32_e32 v25, v19, v19
	v_add_f32_e32 v22, v22, v23
	v_lshlrev_b32_e32 v0, 10, v116
	v_add_f32_e32 v22, v24, v22
	v_add_f32_e32 v22, v25, v22
	v_lshlrev_b32_e32 v0, 1, v0
	v_cvt_pk_bf16_f32 v20, v20, v21
	v_cvt_pk_bf16_f32 v21, v18, v19
	v_lshl_add_u64 v[18:19], v[10:11], 0, v[0:1]
	s_nop 1
	v_mov_b32_dpp v0, v22 quad_perm:[1,0,3,2] row_mask:0xf bank_mask:0xf
	global_store_dwordx2 v[18:19], v[20:21], off sc1
	s_waitcnt lgkmcnt(0)
	v_add_f32_e32 v0, v22, v0
	s_nop 1
	v_mov_b32_dpp v18, v0 quad_perm:[2,3,0,1] row_mask:0xf bank_mask:0xf
	s_waitcnt lgkmcnt(0)
	v_add_f32_e32 v0, v0, v18
	s_nop 1
	v_mov_b32_dpp v18, v0 row_half_mirror row_mask:0xf bank_mask:0xf
	s_waitcnt lgkmcnt(0)
	v_add_f32_e32 v0, v0, v18
	s_nop 1
	v_mov_b32_dpp v18, v0 row_mirror row_mask:0xf bank_mask:0xf
	v_add_f32_e32 v146, v0, v18
	v_cmp_eq_u32_e64 s[2:3], 9, v180
	s_nop 1
	v_cndmask_b32_e64 v147, v147, v146, s[2:3]
.LBB0_459:
	s_waitcnt lgkmcnt(0)
	ds_read_b128 v[18:21], v69 offset:10880
	v_lshlrev_b32_e32 v22, 16, v16
	v_and_b32_e32 v23, 0xffff0000, v16
	v_lshlrev_b32_e32 v16, 16, v17
	v_and_b32_e32 v17, 0xffff0000, v17
	s_waitcnt lgkmcnt(0)
	v_add_f32_e32 v18, v18, v22
	v_add_f32_e32 v19, v19, v23
	v_add_f32_e32 v16, v20, v16
	v_add_f32_e32 v17, v21, v17
	v_mul_f32_e32 v20, v18, v18
	v_mul_f32_e32 v21, v19, v19
	v_mul_f32_e32 v22, v16, v16
	v_mul_f32_e32 v23, v17, v17
	v_add_f32_e32 v20, v20, v21
	v_lshlrev_b32_e32 v0, 10, v114
	v_add_f32_e32 v20, v22, v20
	v_add_f32_e32 v20, v23, v20
	v_lshlrev_b32_e32 v0, 1, v0
	v_cvt_pk_bf16_f32 v18, v18, v19
	v_cvt_pk_bf16_f32 v19, v16, v17
	v_lshl_add_u64 v[16:17], v[10:11], 0, v[0:1]
	s_nop 1
	v_mov_b32_dpp v0, v20 quad_perm:[1,0,3,2] row_mask:0xf bank_mask:0xf
	global_store_dwordx2 v[16:17], v[18:19], off sc1
	s_waitcnt lgkmcnt(0)
	v_add_f32_e32 v0, v20, v0
	s_nop 1
	v_mov_b32_dpp v16, v0 quad_perm:[2,3,0,1] row_mask:0xf bank_mask:0xf
	s_waitcnt lgkmcnt(0)
	v_add_f32_e32 v0, v0, v16
	s_nop 1
	v_mov_b32_dpp v16, v0 row_half_mirror row_mask:0xf bank_mask:0xf
	s_waitcnt lgkmcnt(0)
	v_add_f32_e32 v0, v0, v16
	s_nop 1
	v_mov_b32_dpp v16, v0 row_mirror row_mask:0xf bank_mask:0xf
	v_add_f32_e32 v146, v0, v16
	v_cmp_eq_u32_e64 s[2:3], 10, v180
	s_nop 1
	v_cndmask_b32_e64 v147, v147, v146, s[2:3]
.LBB0_461:
	s_waitcnt lgkmcnt(0)
	ds_read_b128 v[16:19], v69 offset:11968
	v_lshlrev_b32_e32 v20, 16, v14
	v_and_b32_e32 v21, 0xffff0000, v14
	v_lshlrev_b32_e32 v14, 16, v15
	v_and_b32_e32 v15, 0xffff0000, v15
	s_waitcnt lgkmcnt(0)
	v_add_f32_e32 v16, v16, v20
	v_add_f32_e32 v17, v17, v21
	v_add_f32_e32 v14, v18, v14
	v_add_f32_e32 v15, v19, v15
	v_mul_f32_e32 v18, v16, v16
	v_mul_f32_e32 v19, v17, v17
	v_mul_f32_e32 v20, v14, v14
	v_mul_f32_e32 v21, v15, v15
	v_add_f32_e32 v18, v18, v19
	v_lshlrev_b32_e32 v0, 10, v112
	v_add_f32_e32 v18, v20, v18
	v_add_f32_e32 v18, v21, v18
	v_lshlrev_b32_e32 v0, 1, v0
	v_cvt_pk_bf16_f32 v16, v16, v17
	v_cvt_pk_bf16_f32 v17, v14, v15
	v_lshl_add_u64 v[14:15], v[10:11], 0, v[0:1]
	s_nop 1
	v_mov_b32_dpp v0, v18 quad_perm:[1,0,3,2] row_mask:0xf bank_mask:0xf
	global_store_dwordx2 v[14:15], v[16:17], off sc1
	s_waitcnt lgkmcnt(0)
	v_add_f32_e32 v0, v18, v0
	s_nop 1
	v_mov_b32_dpp v14, v0 quad_perm:[2,3,0,1] row_mask:0xf bank_mask:0xf
	s_waitcnt lgkmcnt(0)
	v_add_f32_e32 v0, v0, v14
	s_nop 1
	v_mov_b32_dpp v14, v0 row_half_mirror row_mask:0xf bank_mask:0xf
	s_waitcnt lgkmcnt(0)
	v_add_f32_e32 v0, v0, v14
	s_nop 1
	v_mov_b32_dpp v14, v0 row_mirror row_mask:0xf bank_mask:0xf
	v_add_f32_e32 v146, v0, v14
	v_cmp_eq_u32_e64 s[2:3], 11, v180
	s_nop 1
	v_cndmask_b32_e64 v147, v147, v146, s[2:3]
.LBB0_463:
	s_waitcnt lgkmcnt(0)
	ds_read_b128 v[14:17], v69 offset:13056
	s_waitcnt vmcnt(14)
	v_lshlrev_b32_e32 v18, 16, v12
	v_and_b32_e32 v19, 0xffff0000, v12
	v_lshlrev_b32_e32 v12, 16, v13
	v_and_b32_e32 v13, 0xffff0000, v13
	s_waitcnt lgkmcnt(0)
	v_add_f32_e32 v14, v14, v18
	v_add_f32_e32 v15, v15, v19
	v_add_f32_e32 v12, v16, v12
	v_add_f32_e32 v13, v17, v13
	v_mul_f32_e32 v16, v14, v14
	v_mul_f32_e32 v17, v15, v15
	v_mul_f32_e32 v18, v12, v12
	v_mul_f32_e32 v19, v13, v13
	v_add_f32_e32 v16, v16, v17
	v_lshlrev_b32_e32 v0, 10, v108
	v_add_f32_e32 v16, v18, v16
	v_add_f32_e32 v16, v19, v16
	v_lshlrev_b32_e32 v0, 1, v0
	v_cvt_pk_bf16_f32 v14, v14, v15
	v_cvt_pk_bf16_f32 v15, v12, v13
	v_lshl_add_u64 v[12:13], v[10:11], 0, v[0:1]
	s_nop 1
	v_mov_b32_dpp v0, v16 quad_perm:[1,0,3,2] row_mask:0xf bank_mask:0xf
	global_store_dwordx2 v[12:13], v[14:15], off sc1
	s_waitcnt lgkmcnt(0)
	v_add_f32_e32 v0, v16, v0
	s_nop 1
	v_mov_b32_dpp v12, v0 quad_perm:[2,3,0,1] row_mask:0xf bank_mask:0xf
	s_waitcnt lgkmcnt(0)
	v_add_f32_e32 v0, v0, v12
	s_nop 1
	v_mov_b32_dpp v12, v0 row_half_mirror row_mask:0xf bank_mask:0xf
	s_waitcnt lgkmcnt(0)
	v_add_f32_e32 v0, v0, v12
	s_nop 1
	v_mov_b32_dpp v12, v0 row_mirror row_mask:0xf bank_mask:0xf
	v_add_f32_e32 v146, v0, v12
	v_cmp_eq_u32_e64 s[2:3], 12, v180
	s_nop 1
	v_cndmask_b32_e64 v147, v147, v146, s[2:3]
; DI float bflo(unsigned v) { return __uint_as_float(v << 16); }
; DI float bfhi(unsigned v) { return __uint_as_float(v & 0xffff0000u); }
; template <int EPI>
; DI void gemm_tile(const Params& p, int layer, int mt, int nt, u16* sm, int wv) {
;     ...
;       for (int t = 0; t < 16; ++t) {
;         const int row = (lane >> 4) + 4 * t;
;         const f32x4 a4 = *(const f32x4*)(stg + row * 68 + kc * 4);
;         const float v0 = bflo(xb[t][0]) + a4[0], v1 = bfhi(xb[t][0]) + a4[1], v2 = bflo(xb[t][1]) + a4[2], v3 = bfhi(xb[t][1]) + a4[3];
;         float sq = v0 * v0 + v1 * v1 + v2 * v2 + v3 * v3;
;         u32x2 pv = {pk2(v0, v1), pk2(v2, v3)};
;         if (has_next) *(u32x2*)(xrow + (size_t)row * DM) = pv;
;         else *(u32x2*)(x2row + (size_t)row * DM) = pv;
;         sq += shx(sq, lane, 1); sq += shx(sq, lane, 2); sq += shx(sq, lane, 4); sq += shx(sq, lane, 8);
;         if (kc == 0) atomicAdd(ssn + mrow0 + row, sq);
.LBB0_465:
	s_waitcnt lgkmcnt(0)
	ds_read_b128 v[12:15], v69 offset:14144
	s_waitcnt vmcnt(14)
	v_lshlrev_b32_e32 v16, 16, v8
	v_and_b32_e32 v17, 0xffff0000, v8
	v_lshlrev_b32_e32 v8, 16, v9
	v_and_b32_e32 v9, 0xffff0000, v9
	s_waitcnt lgkmcnt(0)
	v_add_f32_e32 v12, v12, v16
	v_add_f32_e32 v13, v13, v17
	v_add_f32_e32 v8, v14, v8
	v_add_f32_e32 v9, v15, v9
	v_mul_f32_e32 v14, v12, v12
	v_mul_f32_e32 v15, v13, v13
	v_mul_f32_e32 v16, v8, v8
	v_mul_f32_e32 v17, v9, v9
	v_add_f32_e32 v14, v14, v15
	v_lshlrev_b32_e32 v0, 10, v106
	v_add_f32_e32 v14, v16, v14
	v_add_f32_e32 v14, v17, v14
	v_lshlrev_b32_e32 v0, 1, v0
	v_cvt_pk_bf16_f32 v12, v12, v13
	v_cvt_pk_bf16_f32 v13, v8, v9
	v_lshl_add_u64 v[8:9], v[10:11], 0, v[0:1]
	s_nop 1
	v_mov_b32_dpp v0, v14 quad_perm:[1,0,3,2] row_mask:0xf bank_mask:0xf
	global_store_dwordx2 v[8:9], v[12:13], off sc1
	s_waitcnt lgkmcnt(0)
	v_add_f32_e32 v0, v14, v0
	s_nop 1
	v_mov_b32_dpp v8, v0 quad_perm:[2,3,0,1] row_mask:0xf bank_mask:0xf
	s_waitcnt lgkmcnt(0)
	v_add_f32_e32 v0, v0, v8
	s_nop 1
	v_mov_b32_dpp v8, v0 row_half_mirror row_mask:0xf bank_mask:0xf
	s_waitcnt lgkmcnt(0)
	v_add_f32_e32 v0, v0, v8
	s_nop 1
	v_mov_b32_dpp v8, v0 row_mirror row_mask:0xf bank_mask:0xf
	v_add_f32_e32 v146, v0, v8
	v_cmp_eq_u32_e64 s[2:3], 13, v180
	s_nop 1
	v_cndmask_b32_e64 v147, v147, v146, s[2:3]
.LBB0_467:
	ds_read_b128 v[12:15], v69 offset:15232
	s_waitcnt vmcnt(14) lgkmcnt(1)
	v_lshlrev_b32_e32 v8, 16, v6
	v_and_b32_e32 v9, 0xffff0000, v6
	v_lshlrev_b32_e32 v6, 16, v7
	v_and_b32_e32 v7, 0xffff0000, v7
	s_waitcnt lgkmcnt(0)
	v_add_f32_e32 v8, v12, v8
	v_add_f32_e32 v9, v13, v9
	v_add_f32_e32 v6, v14, v6
	v_add_f32_e32 v7, v15, v7
	v_mul_f32_e32 v12, v8, v8
	v_mul_f32_e32 v13, v9, v9
	v_mul_f32_e32 v14, v6, v6
	v_mul_f32_e32 v15, v7, v7
	v_add_f32_e32 v12, v12, v13
	v_lshlrev_b32_e32 v0, 10, v103
	v_add_f32_e32 v12, v14, v12
	v_add_f32_e32 v12, v15, v12
	v_lshlrev_b32_e32 v0, 1, v0
	v_cvt_pk_bf16_f32 v8, v8, v9
	v_cvt_pk_bf16_f32 v9, v6, v7
	v_lshl_add_u64 v[6:7], v[10:11], 0, v[0:1]
	s_nop 1
	v_mov_b32_dpp v0, v12 quad_perm:[1,0,3,2] row_mask:0xf bank_mask:0xf
	global_store_dwordx2 v[6:7], v[8:9], off sc1
	s_waitcnt lgkmcnt(0)
	v_add_f32_e32 v0, v12, v0
	s_nop 1
	v_mov_b32_dpp v6, v0 quad_perm:[2,3,0,1] row_mask:0xf bank_mask:0xf
	s_waitcnt lgkmcnt(0)
	v_add_f32_e32 v0, v0, v6
	s_nop 1
	v_mov_b32_dpp v6, v0 row_half_mirror row_mask:0xf bank_mask:0xf
	s_waitcnt lgkmcnt(0)
	v_add_f32_e32 v0, v0, v6
	s_nop 1
	v_mov_b32_dpp v6, v0 row_mirror row_mask:0xf bank_mask:0xf
	v_add_f32_e32 v146, v0, v6
	v_cmp_eq_u32_e64 s[2:3], 14, v180
	s_nop 1
	v_cndmask_b32_e64 v147, v147, v146, s[2:3]
.LBB0_469:
	s_waitcnt lgkmcnt(0)
	ds_read_b128 v[6:9], v69 offset:16320
	s_waitcnt vmcnt(14)
	v_lshlrev_b32_e32 v12, 16, v2
	v_and_b32_e32 v13, 0xffff0000, v2
	v_lshlrev_b32_e32 v2, 16, v3
	v_and_b32_e32 v3, 0xffff0000, v3
	s_waitcnt lgkmcnt(0)
	v_add_f32_e32 v6, v6, v12
	v_add_f32_e32 v7, v7, v13
	v_add_f32_e32 v2, v8, v2
	v_add_f32_e32 v3, v9, v3
	v_mul_f32_e32 v8, v6, v6
	v_mul_f32_e32 v9, v7, v7
	v_mul_f32_e32 v12, v2, v2
	v_mul_f32_e32 v13, v3, v3
	v_add_f32_e32 v8, v8, v9
	v_lshlrev_b32_e32 v0, 10, v102
	v_add_f32_e32 v8, v12, v8
	v_add_f32_e32 v8, v13, v8
	v_lshlrev_b32_e32 v0, 1, v0
	v_cvt_pk_bf16_f32 v6, v6, v7
	v_cvt_pk_bf16_f32 v7, v2, v3
	v_lshl_add_u64 v[2:3], v[10:11], 0, v[0:1]
	s_nop 1
	v_mov_b32_dpp v0, v8 quad_perm:[1,0,3,2] row_mask:0xf bank_mask:0xf
	global_store_dwordx2 v[2:3], v[6:7], off sc1
	s_waitcnt lgkmcnt(0)
	v_add_f32_e32 v0, v8, v0
	s_nop 1
	v_mov_b32_dpp v2, v0 quad_perm:[2,3,0,1] row_mask:0xf bank_mask:0xf
	s_waitcnt lgkmcnt(0)
	v_add_f32_e32 v0, v0, v2
	s_nop 1
	v_mov_b32_dpp v2, v0 row_half_mirror row_mask:0xf bank_mask:0xf
	s_waitcnt lgkmcnt(0)
	v_add_f32_e32 v0, v0, v2
	s_nop 1
	v_mov_b32_dpp v2, v0 row_mirror row_mask:0xf bank_mask:0xf
	v_add_f32_e32 v146, v0, v2
	v_cmp_eq_u32_e64 s[2:3], 15, v180
	s_nop 1
	v_cndmask_b32_e64 v147, v147, v146, s[2:3]
	v_lshl_add_u32 v148, v180, 4, v66
	v_mov_b32_e32 v149, v1
	v_lshl_add_u64 v[148:149], v[4:5], 0, v[148:149]
	global_atomic_add_f32 v[148:149], v147, off
	s_branch .LBB0_394

; DI float bflo(unsigned v) { return __uint_as_float(v << 16); }
; DI float bfhi(unsigned v) { return __uint_as_float(v & 0xffff0000u); }
; __global__ void __launch_bounds__(256, 2) hymba_mega(Params p) {
;     ...
;     for (int row0 = (bid * 4 + (tid >> 6)) * 4; row0 < MTOK; row0 += nb * 16) {
;       f32x4 xv[4][4];
;       float rs[4];
; #pragma unroll
;       for (int q = 0; q < 4; ++q) {
;         rs[q] = ssf[row0 + q];
; #pragma unroll
;         for (int j = 0; j < 4; ++j) {
;           const u32x2 xb = __builtin_nontemporal_load((const u32x2*)((const u16*)p.x2 + (size_t)(row0 + q) * DM + j * 256 + lane * 4));
;           xv[q][j][0] = bflo(xb[0]); xv[q][j][1] = bfhi(xb[0]); xv[q][j][2] = bflo(xb[1]); xv[q][j][3] = bfhi(xb[1]);
;         }
;       }
.LBB0_524:
	global_load_dwordx4 v[16:19], v[22:23], off
	global_load_dwordx2 v[62:63], v[26:27], off offset:-4096 nt
	global_load_dwordx2 v[60:61], v[26:27], off offset:-3584 nt
	global_load_dwordx2 v[58:59], v[26:27], off offset:-3072 nt
	global_load_dwordx2 v[56:57], v[26:27], off offset:-2560 nt
	global_load_dwordx2 v[54:55], v[26:27], off offset:-2048 nt
	global_load_dwordx2 v[52:53], v[26:27], off offset:-1536 nt
	global_load_dwordx2 v[50:51], v[26:27], off offset:-1024 nt
	global_load_dwordx2 v[48:49], v[26:27], off offset:-512 nt
	global_load_dwordx2 v[46:47], v[26:27], off nt
	global_load_dwordx2 v[44:45], v[26:27], off offset:512 nt
	global_load_dwordx2 v[42:43], v[26:27], off offset:1024 nt
	global_load_dwordx2 v[36:37], v[26:27], off offset:1536 nt
	global_load_dwordx2 v[34:35], v[26:27], off offset:2048 nt
	global_load_dwordx2 v[32:33], v[26:27], off offset:2560 nt
	global_load_dwordx2 v[30:31], v[26:27], off offset:3072 nt
	global_load_dwordx2 v[28:29], v[26:27], off offset:3584 nt
	v_add_co_u32_e32 v38, vcc, s8, v24
	v_add_u32_e32 v20, s12, v20
	s_nop 0
	v_addc_co_u32_e32 v39, vcc, 0, v25, vcc
	v_add_co_u32_e32 v40, vcc, s9, v24
	v_lshl_add_u64 v[22:23], v[22:23], 0, s[0:1]
	s_nop 0
	v_addc_co_u32_e32 v41, vcc, 0, v25, vcc
	v_add_co_u32_e32 v94, vcc, s10, v24
	v_lshl_add_u64 v[26:27], v[26:27], 0, s[4:5]
	s_nop 0
	v_addc_co_u32_e32 v95, vcc, 0, v25, vcc
	v_cmp_lt_i32_e32 vcc, s11, v20
	s_or_b64 s[6:7], vcc, s[6:7]
	s_waitcnt vmcnt(16)
	v_fmamk_f32 v16, v16, 0x3a800000, v21
	v_fmamk_f32 v17, v17, 0x3a800000, v21
	v_fmamk_f32 v19, v19, 0x3a800000, v21
	v_rsq_f32_e32 v16, v16
	s_waitcnt vmcnt(15)
	v_lshlrev_b32_e32 v64, 16, v62
	v_and_b32_e32 v65, 0xffff0000, v62
	v_lshlrev_b32_e32 v62, 16, v63
	v_and_b32_e32 v63, 0xffff0000, v63
	s_waitcnt vmcnt(8)
	v_lshlrev_b32_e32 v80, 16, v48
	v_and_b32_e32 v81, 0xffff0000, v48
	v_fmamk_f32 v48, v18, 0x3a800000, v21
	v_rsq_f32_e32 v18, v17
	v_lshlrev_b32_e32 v66, 16, v60
	s_waitcnt vmcnt(3)
	v_lshlrev_b32_e32 v100, 16, v34
	v_and_b32_e32 v101, 0xffff0000, v34
	s_waitcnt vmcnt(1)
	v_lshlrev_b32_e32 v108, 16, v30
	v_and_b32_e32 v109, 0xffff0000, v30
	s_waitcnt vmcnt(0)
; __global__ void __launch_bounds__(256, 2) hymba_mega(Params p) {
;     ...
; #pragma unroll
;       for (int q = 0; q < 4; ++q) {
;         const float rq = __builtin_amdgcn_rsqf(rs[q] * (1.f / DM) + EPS);
; #pragma unroll
;         for (int j = 0; j < 4; ++j) {
;           f32x4 v = xv[q][j];
;           v[0] *= rq * gv[j][0]; v[1] *= rq * gv[j][1]; v[2] *= rq * gv[j][2]; v[3] *= rq * gv[j][3];
;           __builtin_nontemporal_store(v, (f32x4*)(p.out + (size_t)(row0 + q) * DM + j * 256 + lane * 4));
;         }
;       }
	v_lshlrev_b32_e32 v112, 16, v28
	v_and_b32_e32 v113, 0xffff0000, v28
	v_rsq_f32_e32 v28, v48
	v_rsq_f32_e32 v30, v19
	v_lshlrev_b32_e32 v102, 16, v35
	v_and_b32_e32 v103, 0xffff0000, v35
	v_lshlrev_b32_e32 v104, 16, v32
	v_and_b32_e32 v105, 0xffff0000, v32
	v_lshlrev_b32_e32 v106, 16, v33
	v_and_b32_e32 v107, 0xffff0000, v33
	v_mul_f32_e32 v32, v16, v12
	v_mul_f32_e32 v33, v16, v13
	v_mul_f32_e32 v34, v16, v14
	v_mul_f32_e32 v35, v16, v15
	v_and_b32_e32 v67, 0xffff0000, v60
	v_lshlrev_b32_e32 v60, 16, v61
	v_and_b32_e32 v61, 0xffff0000, v61
	v_lshlrev_b32_e32 v68, 16, v58
	v_and_b32_e32 v69, 0xffff0000, v58
	v_lshlrev_b32_e32 v58, 16, v59
	v_and_b32_e32 v59, 0xffff0000, v59
	v_lshlrev_b32_e32 v70, 16, v56
	v_and_b32_e32 v71, 0xffff0000, v56
	v_lshlrev_b32_e32 v56, 16, v57
	v_and_b32_e32 v57, 0xffff0000, v57
	v_lshlrev_b32_e32 v72, 16, v54
	v_and_b32_e32 v73, 0xffff0000, v54
	v_lshlrev_b32_e32 v54, 16, v55
	v_and_b32_e32 v55, 0xffff0000, v55
	v_lshlrev_b32_e32 v74, 16, v52
	v_and_b32_e32 v75, 0xffff0000, v52
	v_lshlrev_b32_e32 v52, 16, v53
	v_and_b32_e32 v53, 0xffff0000, v53
	v_lshlrev_b32_e32 v76, 16, v50
	v_and_b32_e32 v77, 0xffff0000, v50
	v_lshlrev_b32_e32 v78, 16, v51
	v_and_b32_e32 v79, 0xffff0000, v51
	v_lshlrev_b32_e32 v82, 16, v49
	v_and_b32_e32 v83, 0xffff0000, v49
	v_lshlrev_b32_e32 v84, 16, v46
	v_and_b32_e32 v85, 0xffff0000, v46
	v_lshlrev_b32_e32 v86, 16, v47
	v_and_b32_e32 v87, 0xffff0000, v47
	v_lshlrev_b32_e32 v88, 16, v44
	v_and_b32_e32 v89, 0xffff0000, v44
	v_lshlrev_b32_e32 v90, 16, v45
	v_and_b32_e32 v91, 0xffff0000, v45
	v_lshlrev_b32_e32 v92, 16, v42
	v_and_b32_e32 v93, 0xffff0000, v42
	v_lshlrev_b32_e32 v96, 16, v43
	v_and_b32_e32 v97, 0xffff0000, v43
	v_lshlrev_b32_e32 v98, 16, v36
	v_and_b32_e32 v99, 0xffff0000, v36
	v_lshlrev_b32_e32 v36, 16, v37
	v_and_b32_e32 v37, 0xffff0000, v37
	v_lshlrev_b32_e32 v110, 16, v31
	v_and_b32_e32 v111, 0xffff0000, v31
	v_lshlrev_b32_e32 v114, 16, v29
	v_and_b32_e32 v115, 0xffff0000, v29
	v_mul_f32_e32 v42, v16, v8
	v_mul_f32_e32 v43, v16, v9
	v_mul_f32_e32 v44, v16, v10
	v_mul_f32_e32 v45, v16, v11
	v_mul_f32_e32 v46, v16, v4
	v_mul_f32_e32 v47, v16, v5
	v_mul_f32_e32 v48, v16, v6
	v_mul_f32_e32 v49, v16, v7
	v_mul_f32_e32 v50, v16, v0
	v_mul_f32_e32 v51, v16, v1
	v_mul_f32_e32 v116, v16, v2
	v_mul_f32_e32 v117, v16, v3
	v_mul_f32_e32 v118, v18, v12
	v_mul_f32_e32 v119, v18, v13
	v_mul_f32_e32 v120, v18, v14
	v_mul_f32_e32 v121, v18, v15
	v_mul_f32_e32 v122, v18, v8
	v_mul_f32_e32 v123, v18, v9
	v_mul_f32_e32 v124, v18, v10
	v_mul_f32_e32 v125, v18, v11
	v_mul_f32_e32 v126, v18, v4
	v_mul_f32_e32 v127, v18, v5
	v_mul_f32_e32 v128, v18, v6
	v_mul_f32_e32 v129, v18, v7
	v_mul_f32_e32 v130, v18, v0
	v_mul_f32_e32 v131, v18, v1
	v_mul_f32_e32 v132, v18, v2
	v_mul_f32_e32 v133, v18, v3
	v_mul_f32_e32 v134, v28, v12
	v_mul_f32_e32 v135, v28, v13
	v_mul_f32_e32 v136, v28, v14
	v_mul_f32_e32 v137, v28, v15
	v_mul_f32_e32 v138, v28, v8
	v_mul_f32_e32 v139, v28, v9
	v_mul_f32_e32 v140, v28, v10
	v_mul_f32_e32 v141, v28, v11
	v_mul_f32_e32 v142, v28, v4
	v_mul_f32_e32 v143, v28, v5
	v_mul_f32_e32 v144, v28, v6
	v_mul_f32_e32 v145, v28, v7
	v_mul_f32_e32 v146, v28, v0
	v_mul_f32_e32 v147, v28, v1
	v_mul_f32_e32 v148, v28, v2
	v_mul_f32_e32 v149, v28, v3
	v_mul_f32_e32 v150, v30, v12
	v_mul_f32_e32 v151, v30, v13
	v_mul_f32_e32 v152, v30, v14
	v_mul_f32_e32 v153, v30, v15
	v_mul_f32_e32 v154, v30, v8
	v_mul_f32_e32 v155, v30, v9
	v_mul_f32_e32 v156, v30, v10
	v_mul_f32_e32 v157, v30, v11
	v_mul_f32_e32 v158, v30, v4
	v_mul_f32_e32 v159, v30, v5
	v_mul_f32_e32 v160, v30, v6
	v_mul_f32_e32 v161, v30, v7
	v_mul_f32_e32 v162, v30, v0
	v_mul_f32_e32 v163, v30, v1
	v_mul_f32_e32 v164, v30, v2
	v_mul_f32_e32 v165, v30, v3
	v_mul_f32_e32 v16, v32, v64
	v_mul_f32_e32 v17, v33, v65
	v_mul_f32_e32 v18, v34, v62
	v_mul_f32_e32 v19, v35, v63
	v_mul_f32_e32 v28, v42, v66
	v_mul_f32_e32 v29, v43, v67
	v_mul_f32_e32 v30, v44, v60
	v_mul_f32_e32 v31, v45, v61
	v_mul_f32_e32 v32, v46, v68
	v_mul_f32_e32 v33, v47, v69
	v_mul_f32_e32 v34, v48, v58
	v_mul_f32_e32 v35, v49, v59
	v_mul_f32_e32 v42, v50, v70
	v_mul_f32_e32 v43, v51, v71
	v_mul_f32_e32 v44, v116, v56
	v_mul_f32_e32 v45, v117, v57
	v_mul_f32_e32 v46, v118, v72
	v_mul_f32_e32 v47, v119, v73
	v_mul_f32_e32 v48, v120, v54
	v_mul_f32_e32 v49, v121, v55
	v_mul_f32_e32 v50, v122, v74
	v_mul_f32_e32 v51, v123, v75
	v_mul_f32_e32 v52, v124, v52
	v_mul_f32_e32 v53, v125, v53
	v_mul_f32_e32 v54, v126, v76
	v_mul_f32_e32 v55, v127, v77
	v_mul_f32_e32 v56, v128, v78
	v_mul_f32_e32 v57, v129, v79
	v_mul_f32_e32 v58, v130, v80
	v_mul_f32_e32 v59, v131, v81
	v_mul_f32_e32 v60, v132, v82
	v_mul_f32_e32 v61, v133, v83
	v_mul_f32_e32 v62, v134, v84
	v_mul_f32_e32 v63, v135, v85
	v_mul_f32_e32 v64, v136, v86
	v_mul_f32_e32 v65, v137, v87
	v_mul_f32_e32 v66, v138, v88
	v_mul_f32_e32 v67, v139, v89
	v_mul_f32_e32 v68, v140, v90
	v_mul_f32_e32 v69, v141, v91
	v_mul_f32_e32 v70, v142, v92
	v_mul_f32_e32 v71, v143, v93
	v_mul_f32_e32 v72, v144, v96
	v_mul_f32_e32 v73, v145, v97
	v_mul_f32_e32 v74, v146, v98
	v_mul_f32_e32 v75, v147, v99
	v_mul_f32_e32 v76, v148, v36
	v_mul_f32_e32 v77, v149, v37
	v_mul_f32_e32 v78, v150, v100
	v_mul_f32_e32 v79, v151, v101
	v_mul_f32_e32 v80, v152, v102
	v_mul_f32_e32 v81, v153, v103
	v_mul_f32_e32 v82, v154, v104
	v_mul_f32_e32 v83, v155, v105
	v_mul_f32_e32 v84, v156, v106
	v_mul_f32_e32 v85, v157, v107
	v_mul_f32_e32 v86, v158, v108
	v_mul_f32_e32 v87, v159, v109
	v_mul_f32_e32 v88, v160, v110
	v_mul_f32_e32 v89, v161, v111
	v_mul_f32_e32 v90, v162, v112
	v_mul_f32_e32 v91, v163, v113
	v_mul_f32_e32 v92, v164, v114
	v_mul_f32_e32 v93, v165, v115
	global_store_dwordx4 v[24:25], v[16:19], off nt sc1
	global_store_dwordx4 v[24:25], v[28:31], off offset:1024 nt sc1
	global_store_dwordx4 v[24:25], v[32:35], off offset:2048 nt sc1
	global_store_dwordx4 v[24:25], v[42:45], off offset:3072 nt sc1
	global_store_dwordx4 v[40:41], v[46:49], off offset:-4096 nt sc1
	global_store_dwordx4 v[38:39], v[50:53], off offset:1024 nt sc1
	global_store_dwordx4 v[38:39], v[54:57], off offset:2048 nt sc1
	global_store_dwordx4 v[38:39], v[58:61], off offset:3072 nt sc1
	global_store_dwordx4 v[40:41], v[62:65], off nt sc1
	global_store_dwordx4 v[40:41], v[66:69], off offset:1024 nt sc1
	global_store_dwordx4 v[40:41], v[70:73], off offset:2048 nt sc1
	global_store_dwordx4 v[40:41], v[74:77], off offset:3072 nt sc1
	global_store_dwordx4 v[94:95], v[78:81], off nt sc1
	global_store_dwordx4 v[94:95], v[82:85], off offset:1024 nt sc1
	global_store_dwordx4 v[94:95], v[86:89], off offset:2048 nt sc1
	global_store_dwordx4 v[94:95], v[90:93], off offset:3072 nt sc1
	v_lshl_add_u64 v[24:25], v[24:25], 0, s[2:3]
	s_andn2_b64 exec, exec, s[6:7]
	s_cbranch_execnz .LBB0_524
